# counted lgkmcnt split (8 then 0) in the remaining GEMM k-step blocks (phases D, E, mix, A second walk)
# baseline (speedup 1.0000x reference)
; #define MFMA16(a, b, c) __builtin_amdgcn_mfma_f32_16x16x32_bf16((a), (b), (c), 0, 0, 0)
; DI void gemm_tile(const bf16_t* __restrict__ A, int lda, const bf16_t* __restrict__ Bt, int ldb, int bvalid, int K, f32x4 (&acc)[4][4], char* lds, bool preloaded = false) {
;     ...
;   auto compute = [&](int st) {
;     const char* base = lds + st * 32768;
;     bf16x8 af[2][4], bfr[2][4];
; #pragma unroll
;     for (int s = 0; s < 2; ++s) {
;       const int ch = ((4 * s + fq) ^ fx) << 4;
; #pragma unroll
;       for (int mi = 0; mi < 4; ++mi) af[s][mi] = *(const bf16x8*)(base + (wm * 64 + mi * 16 + fr) * 128 + ch);
; #pragma unroll
;       for (int ni = 0; ni < 4; ++ni) bfr[s][ni] = *(const bf16x8*)(base + 16384 + (wn * 64 + ni * 16 + fr) * 128 + ch);
;     }
;     __builtin_amdgcn_s_setprio(1);
; #pragma unroll
;     for (int s = 0; s < 2; ++s)
; #pragma unroll
;       for (int mi = 0; mi < 4; ++mi)
; #pragma unroll
;         for (int ni = 0; ni < 4; ++ni) acc[mi][ni] = MFMA16(af[s][mi], bfr[s][ni], acc[mi][ni]);
;     __builtin_amdgcn_s_setprio(0);
;   };
;   const int nk = K >> 6;
;   if (!preloaded) { GLDS(0, 0) }
;   __syncthreads();
;   for (int kt = 0; kt < nk; ++kt) {
;     if (kt + 1 < nk) { GLDS((kt + 1) & 1, (kt + 1) << 6) }
;     compute(kt & 1);
;     __syncthreads();
.LBB0_170:
	v_lshl_add_u64 v[150:151], v[132:133], 0, s[8:9]
	s_mov_b64 s[24:25], 0x624e080
	s_add_i32 s23, s22, 0x8000
	v_lshl_add_u64 v[152:153], v[150:151], 0, s[24:25]
	s_and_b32 s24, s23, 0x8000
	v_add_u32_e32 v0, s24, v145
	v_add_u32_e32 v154, 0x4000, v0
	v_readfirstlane_b32 s24, v0
	s_mov_b32 m0, s24
	v_readfirstlane_b32 s24, v154
	global_load_lds_dwordx4 v[152:153], off
	v_lshl_add_u64 v[152:153], v[134:135], 0, s[8:9]
	s_mov_b32 m0, s24
	s_mov_b64 s[24:25], 0x625f080
	v_add_u32_e32 v154, 0x1000, v0
	global_load_lds_dwordx4 v[152:153], off
	v_lshl_add_u64 v[152:153], v[150:151], 0, s[24:25]
	v_readfirstlane_b32 s24, v154
	v_add_u32_e32 v154, 0x5000, v0
	s_mov_b32 m0, s24
	v_readfirstlane_b32 s24, v154
	global_load_lds_dwordx4 v[152:153], off
	v_lshl_add_u64 v[152:153], v[136:137], 0, s[8:9]
	s_mov_b32 m0, s24
	s_mov_b64 s[24:25], 0x6270080
	v_add_u32_e32 v154, 0x2000, v0
	global_load_lds_dwordx4 v[152:153], off
	v_lshl_add_u64 v[152:153], v[150:151], 0, s[24:25]
	v_readfirstlane_b32 s24, v154
	v_add_u32_e32 v154, 0x6000, v0
	s_mov_b32 m0, s24
	v_readfirstlane_b32 s24, v154
	global_load_lds_dwordx4 v[152:153], off
	v_lshl_add_u64 v[152:153], v[138:139], 0, s[8:9]
	s_mov_b32 m0, s24
	s_mov_b64 s[24:25], 0x6281080
	global_load_lds_dwordx4 v[152:153], off
	v_add_u32_e32 v152, 0x3000, v0
	v_lshl_add_u64 v[150:151], v[150:151], 0, s[24:25]
	v_readfirstlane_b32 s24, v152
	v_add_u32_e32 v0, 0x7000, v0
	s_mov_b32 m0, s24
	v_readfirstlane_b32 s24, v0
	global_load_lds_dwordx4 v[150:151], off
	v_lshl_add_u64 v[150:151], v[140:141], 0, s[8:9]
	s_mov_b32 m0, s24
	s_and_b32 s22, s22, 0x8000
	global_load_lds_dwordx4 v[150:151], off
	v_or_b32_e32 v0, s22, v149
	v_add_u32_e32 v179, v0, v148
	v_add_u32_e32 v0, v0, v146
	ds_read_b128 v[150:153], v179
	ds_read_b128 v[154:157], v179 offset:2048
	ds_read_b128 v[180:183], v179 offset:4096
	ds_read_b128 v[184:187], v179 offset:6144
	ds_read_b128 v[188:191], v0 offset:16384
	ds_read_b128 v[192:195], v0 offset:18432
	ds_read_b128 v[196:199], v0 offset:20480
	ds_read_b128 v[200:203], v0 offset:22528
	v_or_b32_e32 v0, s22, v147
	v_add_u32_e32 v179, v0, v148
	v_add_u32_e32 v0, v0, v146
	ds_read_b128 v[204:207], v179
	ds_read_b128 v[208:211], v179 offset:2048
	ds_read_b128 v[212:215], v179 offset:4096
	ds_read_b128 v[216:219], v179 offset:6144
	ds_read_b128 v[220:223], v0 offset:16384
	ds_read_b128 v[224:227], v0 offset:18432
	ds_read_b128 v[228:231], v0 offset:20480
	ds_read_b128 v[232:235], v0 offset:22528
	s_setprio 1
	s_waitcnt lgkmcnt(8)
	v_mfma_f32_16x16x32_bf16 v[126:129], v[150:153], v[188:191], v[126:129]
	v_mfma_f32_16x16x32_bf16 v[122:125], v[150:153], v[192:195], v[122:125]
	v_mfma_f32_16x16x32_bf16 v[118:121], v[150:153], v[196:199], v[118:121]
	v_mfma_f32_16x16x32_bf16 v[114:117], v[150:153], v[200:203], v[114:117]
	v_mfma_f32_16x16x32_bf16 v[110:113], v[154:157], v[188:191], v[110:113]
	v_mfma_f32_16x16x32_bf16 v[106:109], v[154:157], v[192:195], v[106:109]
	v_mfma_f32_16x16x32_bf16 v[102:105], v[154:157], v[196:199], v[102:105]
	v_mfma_f32_16x16x32_bf16 v[98:101], v[154:157], v[200:203], v[98:101]
	v_mfma_f32_16x16x32_bf16 v[94:97], v[180:183], v[188:191], v[94:97]
	v_mfma_f32_16x16x32_bf16 v[90:93], v[180:183], v[192:195], v[90:93]
	v_mfma_f32_16x16x32_bf16 v[86:89], v[180:183], v[196:199], v[86:89]
	v_mfma_f32_16x16x32_bf16 v[82:85], v[180:183], v[200:203], v[82:85]
	v_mfma_f32_16x16x32_bf16 v[78:81], v[184:187], v[188:191], v[78:81]
	v_mfma_f32_16x16x32_bf16 v[74:77], v[184:187], v[192:195], v[74:77]
	v_mfma_f32_16x16x32_bf16 v[70:73], v[184:187], v[196:199], v[70:73]
	v_mfma_f32_16x16x32_bf16 v[66:69], v[184:187], v[200:203], v[66:69]
	s_waitcnt lgkmcnt(0)
	v_mfma_f32_16x16x32_bf16 v[126:129], v[204:207], v[220:223], v[126:129]
	v_mfma_f32_16x16x32_bf16 v[122:125], v[204:207], v[224:227], v[122:125]
	v_mfma_f32_16x16x32_bf16 v[118:121], v[204:207], v[228:231], v[118:121]
	v_mfma_f32_16x16x32_bf16 v[114:117], v[204:207], v[232:235], v[114:117]
	v_mfma_f32_16x16x32_bf16 v[110:113], v[208:211], v[220:223], v[110:113]
	v_mfma_f32_16x16x32_bf16 v[106:109], v[208:211], v[224:227], v[106:109]
	v_mfma_f32_16x16x32_bf16 v[102:105], v[208:211], v[228:231], v[102:105]
	v_mfma_f32_16x16x32_bf16 v[98:101], v[208:211], v[232:235], v[98:101]
	v_mfma_f32_16x16x32_bf16 v[94:97], v[212:215], v[220:223], v[94:97]
	v_mfma_f32_16x16x32_bf16 v[90:93], v[212:215], v[224:227], v[90:93]
	v_mfma_f32_16x16x32_bf16 v[86:89], v[212:215], v[228:231], v[86:89]
	v_mfma_f32_16x16x32_bf16 v[82:85], v[212:215], v[232:235], v[82:85]
	v_mfma_f32_16x16x32_bf16 v[78:81], v[216:219], v[220:223], v[78:81]
	v_mfma_f32_16x16x32_bf16 v[74:77], v[216:219], v[224:227], v[74:77]
	v_mfma_f32_16x16x32_bf16 v[70:73], v[216:219], v[228:231], v[70:73]
	v_mfma_f32_16x16x32_bf16 v[66:69], v[216:219], v[232:235], v[66:69]
	s_setprio 0
	s_add_u32 s8, s8, 0x80
	s_addc_u32 s9, s9, 0
	s_cmpk_eq_i32 s8, 0x780
	s_mov_b32 s22, s23
	s_waitcnt vmcnt(0)
	s_barrier
	s_cbranch_scc0 .LBB0_170
; #define MFMA16(a, b, c) __builtin_amdgcn_mfma_f32_16x16x32_bf16((a), (b), (c), 0, 0, 0)
; DI void gemm_tile(const bf16_t* __restrict__ A, int lda, const bf16_t* __restrict__ Bt, int ldb, int bvalid, int K, f32x4 (&acc)[4][4], char* lds, bool preloaded = false) {
;     ...
;   auto compute = [&](int st) {
;     const char* base = lds + st * 32768;
;     bf16x8 af[2][4], bfr[2][4];
; #pragma unroll
;     for (int s = 0; s < 2; ++s) {
;       const int ch = ((4 * s + fq) ^ fx) << 4;
; #pragma unroll
;       for (int mi = 0; mi < 4; ++mi) af[s][mi] = *(const bf16x8*)(base + (wm * 64 + mi * 16 + fr) * 128 + ch);
; #pragma unroll
;       for (int ni = 0; ni < 4; ++ni) bfr[s][ni] = *(const bf16x8*)(base + 16384 + (wn * 64 + ni * 16 + fr) * 128 + ch);
;     }
;     __builtin_amdgcn_s_setprio(1);
; #pragma unroll
;     for (int s = 0; s < 2; ++s)
; #pragma unroll
;       for (int mi = 0; mi < 4; ++mi)
; #pragma unroll
;         for (int ni = 0; ni < 4; ++ni) acc[mi][ni] = MFMA16(af[s][mi], bfr[s][ni], acc[mi][ni]);
;     __builtin_amdgcn_s_setprio(0);
;   };
;   const int nk = K >> 6;
;   if (!preloaded) { GLDS(0, 0) }
;   __syncthreads();
;   for (int kt = 0; kt < nk; ++kt) {
;     if (kt + 1 < nk) { GLDS((kt + 1) & 1, (kt + 1) << 6) }
;     compute(kt & 1);
;     __syncthreads();
; DI void phaseE_tile(const P& p, int layer, int mt, int nt, char* lds) {
;     ...
;   float* tile = (float*)lds;
;   stage_acc(acc, tile, wm, wn, fr, fq);
;   __syncthreads();
;   bf16_t* XB = (bf16_t*)(p.ws + W_XB);
;   float* SS = (float*)(p.ws + W_SS);
; #pragma unroll
;   for (int ps = 0; ps < 16; ++ps) {
;     const int lr = ps * 8 + wm * 4 + fq, row = row0 + lr;
;     const f32x4 v = xr[ps] + *(const f32x4*)(tile + lr * EPS + wn * 64 + fr * 4);
;     *(f32x4*)(XF + (size_t)row * DM + col) = v;
	v_add_u32_e32 v0, v149, v148
	ds_read_b128 v[132:135], v0 offset:32768
	ds_read_b128 v[136:139], v0 offset:34816
	ds_read_b128 v[150:153], v0 offset:36864
	ds_read_b128 v[154:157], v0 offset:38912
	v_add_u32_e32 v0, v149, v146
	ds_read_b128 v[180:183], v0 offset:49152
	ds_read_b128 v[184:187], v0 offset:51200
	ds_read_b128 v[188:191], v0 offset:53248
	ds_read_b128 v[192:195], v0 offset:55296
	v_add_u32_e32 v0, v147, v148
	ds_read_b128 v[196:199], v0 offset:32768
	ds_read_b128 v[200:203], v0 offset:34816
	ds_read_b128 v[204:207], v0 offset:36864
	ds_read_b128 v[208:211], v0 offset:38912
	v_add_u32_e32 v0, v147, v146
	ds_read_b128 v[146:149], v0 offset:49152
	ds_read_b128 v[212:215], v0 offset:51200
	ds_read_b128 v[216:219], v0 offset:53248
	ds_read_b128 v[220:223], v0 offset:55296
	s_setprio 1
	s_waitcnt lgkmcnt(9)
	v_mfma_f32_16x16x32_bf16 v[70:73], v[154:157], v[188:191], v[70:73]
	s_waitcnt lgkmcnt(8)
	v_mfma_f32_16x16x32_bf16 v[66:69], v[154:157], v[192:195], v[66:69]
	v_mfma_f32_16x16x32_bf16 v[126:129], v[132:135], v[180:183], v[126:129]
	v_mfma_f32_16x16x32_bf16 v[122:125], v[132:135], v[184:187], v[122:125]
	v_mfma_f32_16x16x32_bf16 v[118:121], v[132:135], v[188:191], v[118:121]
	v_mfma_f32_16x16x32_bf16 v[114:117], v[132:135], v[192:195], v[114:117]
	v_mfma_f32_16x16x32_bf16 v[110:113], v[136:139], v[180:183], v[110:113]
	v_mfma_f32_16x16x32_bf16 v[106:109], v[136:139], v[184:187], v[106:109]
	v_mfma_f32_16x16x32_bf16 v[102:105], v[136:139], v[188:191], v[102:105]
	v_mfma_f32_16x16x32_bf16 v[98:101], v[136:139], v[192:195], v[98:101]
	v_mfma_f32_16x16x32_bf16 v[94:97], v[150:153], v[180:183], v[94:97]
	v_mfma_f32_16x16x32_bf16 v[90:93], v[150:153], v[184:187], v[90:93]
	v_mfma_f32_16x16x32_bf16 v[86:89], v[150:153], v[188:191], v[86:89]
	v_mfma_f32_16x16x32_bf16 v[82:85], v[150:153], v[192:195], v[82:85]
	v_mfma_f32_16x16x32_bf16 v[78:81], v[154:157], v[180:183], v[78:81]
	v_mfma_f32_16x16x32_bf16 v[74:77], v[154:157], v[184:187], v[74:77]
	s_waitcnt lgkmcnt(1)
	v_mfma_f32_16x16x32_bf16 v[70:73], v[208:211], v[216:219], v[70:73]
	s_waitcnt lgkmcnt(0)
	v_mfma_f32_16x16x32_bf16 v[66:69], v[208:211], v[220:223], v[66:69]
	v_mfma_f32_16x16x32_bf16 v[126:129], v[196:199], v[146:149], v[126:129]
	v_mfma_f32_16x16x32_bf16 v[122:125], v[196:199], v[212:215], v[122:125]
	v_mfma_f32_16x16x32_bf16 v[118:121], v[196:199], v[216:219], v[118:121]
	v_mfma_f32_16x16x32_bf16 v[114:117], v[196:199], v[220:223], v[114:117]
	v_mfma_f32_16x16x32_bf16 v[110:113], v[200:203], v[146:149], v[110:113]
	v_mfma_f32_16x16x32_bf16 v[106:109], v[200:203], v[212:215], v[106:109]
	v_mfma_f32_16x16x32_bf16 v[102:105], v[200:203], v[216:219], v[102:105]
	v_mfma_f32_16x16x32_bf16 v[98:101], v[200:203], v[220:223], v[98:101]
	v_mfma_f32_16x16x32_bf16 v[94:97], v[204:207], v[146:149], v[94:97]
	v_mfma_f32_16x16x32_bf16 v[90:93], v[204:207], v[212:215], v[90:93]
	v_mfma_f32_16x16x32_bf16 v[86:89], v[204:207], v[216:219], v[86:89]
	v_mfma_f32_16x16x32_bf16 v[82:85], v[204:207], v[220:223], v[82:85]
	v_mfma_f32_16x16x32_bf16 v[78:81], v[208:211], v[146:149], v[78:81]
	v_mfma_f32_16x16x32_bf16 v[74:77], v[208:211], v[212:215], v[74:77]
	s_setprio 0
	v_lshlrev_b32_e32 v0, 2, v142
	v_lshl_or_b32 v132, s20, 6, v0
	v_lshl_or_b32 v0, s19, 8, v144
	v_mad_u64_u32 v[132:133], s[8:9], v132, s56, v[0:1]
	v_add_u32_e32 v0, 0x400, v132
	s_barrier
	ds_write2_b32 v132, v126, v122 offset1:16
	ds_write2_b32 v132, v127, v123 offset0:132 offset1:148
	ds_write2_b32 v0, v128, v124 offset0:8 offset1:24
	ds_write2_b32 v0, v129, v125 offset0:140 offset1:156
	ds_write2_b32 v132, v118, v114 offset0:32 offset1:48
	ds_write2_b32 v132, v119, v115 offset0:164 offset1:180
	ds_write2_b32 v0, v120, v116 offset0:40 offset1:56
	ds_write2_b32 v0, v121, v117 offset0:172 offset1:188
	v_add_u32_e32 v0, 0x2000, v132
	ds_write2_b32 v0, v110, v106 offset0:64 offset1:80
	ds_write2_b32 v0, v111, v107 offset0:196 offset1:212
	v_add_u32_e32 v106, 0x2400, v132
	ds_write2_b32 v106, v112, v108 offset0:72 offset1:88
	ds_write2_b32 v106, v113, v109 offset0:204 offset1:220
	ds_write2_b32 v0, v102, v98 offset0:96 offset1:112
	ds_write2_b32 v0, v103, v99 offset0:228 offset1:244
	ds_write2_b32 v106, v104, v100 offset0:104 offset1:120
	ds_write2_b32 v106, v105, v101 offset0:236 offset1:252
	v_add_u32_e32 v0, 0x4000, v132
	ds_write2_b32 v0, v94, v90 offset0:128 offset1:144
	v_add_u32_e32 v90, 0x4400, v132
	ds_write2_b32 v90, v95, v91 offset0:4 offset1:20
	ds_write2_b32 v90, v96, v92 offset0:136 offset1:152
	v_add_u32_e32 v91, 0x4800, v132
	ds_write2_b32 v91, v97, v93 offset0:12 offset1:28
	ds_write2_b32 v0, v86, v82 offset0:160 offset1:176
	ds_write2_b32 v90, v87, v83 offset0:36 offset1:52
	ds_write2_b32 v90, v88, v84 offset0:168 offset1:184
	ds_write2_b32 v91, v89, v85 offset0:44 offset1:60
	v_add_u32_e32 v0, 0x6000, v132
	ds_write2_b32 v0, v78, v74 offset0:192 offset1:208
	v_add_u32_e32 v74, 0x6400, v132
	ds_write2_b32 v74, v79, v75 offset0:68 offset1:84
	ds_write2_b32 v74, v80, v76 offset0:200 offset1:216
	v_add_u32_e32 v75, 0x6800, v132
	ds_write2_b32 v75, v81, v77 offset0:76 offset1:92
	ds_write2_b32 v0, v70, v66 offset0:224 offset1:240
	ds_write2_b32 v74, v71, v67 offset0:100 offset1:116
	ds_write2_b32 v74, v72, v68 offset0:232 offset1:248
	ds_write2_b32 v75, v73, v69 offset0:108 offset1:124
	v_or_b32_e32 v68, s11, v142
	v_lshlrev_b32_e32 v0, 2, v144
	v_lshl_add_u32 v0, s21, 2, v0
	v_mul_lo_u32 v66, v68, s56
	v_add_u32_e32 v0, v0, v66
	s_waitcnt lgkmcnt(0)
	s_barrier
	ds_read_b128 v[72:75], v0
	v_add_u32_e32 v70, s10, v68
	v_ashrrev_i32_e32 v71, 31, v70
	v_lshl_add_u64 v[66:67], v[130:131], 2, s[88:89]
	v_lshlrev_b64 v[68:69], 12, v[70:71]
	s_waitcnt lgkmcnt(0)
	v_pk_add_f32 v[4:5], v[4:5], v[74:75]
	v_pk_add_f32 v[2:3], v[2:3], v[72:73]
	v_lshl_add_u64 v[68:69], v[66:67], 0, v[68:69]
	s_and_b64 vcc, exec, s[38:39]
	s_mov_b64 s[8:9], -1
	global_store_dwordx4 v[68:69], v[2:5], off
	s_cbranch_vccnz .LBB0_173
	s_mov_b64 s[8:9], 0

; DI int tidx() { int t = __builtin_amdgcn_workitem_id_x(); asm volatile("" : "+v"(t)); return t; }
; DI void gemm_tile(const bf16_t* __restrict__ A, int lda, const bf16_t* __restrict__ Bt, int ldb, int bvalid, int K, f32x4 (&acc)[4][4], char* lds, bool preloaded = false) {
;     ...
;   const bf16_t* ap = A + (size_t)lr * lda + ((lc ^ ((lr >> 1) & 7)) << 3);
;   const bf16_t* bp = Bt + ((lc ^ ((lr >> 1) & 7)) << 3);
;   typedef __attribute__((address_space(1))) const unsigned gptr_t;
;   typedef __attribute__((address_space(3))) unsigned lptr_t;
;   const unsigned lbase = (unsigned)(size_t)lds + (unsigned)tid * 16u;
; DI void phaseD_tile(const P& p, int layer, int mt, int nt, char* lds) {
;   const int lane = tidx() & 63, wave = __builtin_amdgcn_readfirstlane(tidx() >> 6);
;   const int row0 = mt * 128, col0 = nt * 128;
;   const int wm = wave >> 1, wn = wave & 1, fr = lane & 15, fq = lane >> 4;
;   f32x4 acc[4][4];
;   zero_acc(acc);
;   const size_t goff = ((size_t)((mt * 2 + wm) * 16 + nt * 2 + wn) * 64 + lane) * 16;
;   const unsigned* GP = (const unsigned*)(p.ws + W_GP) + goff;
;   const unsigned* GA = (const unsigned*)(p.ws + W_GA) + goff;
;   u32x4 gpv[4], gav[4];
; #pragma unroll
;   for (int mi = 0; mi < 4; ++mi) { gpv[mi] = __builtin_nontemporal_load((const u32x4*)(GP + mi * 4)); gav[mi] = __builtin_nontemporal_load((const u32x4*)(GA + mi * 4)); }
;   gemm_tile((const bf16_t*)(p.ws + W_POOLED) + (size_t)row0 * 512, 512, (const bf16_t*)(p.ws + W_WPO) + ((size_t)layer * 1024 + col0) * 512, 512, 128, 512, acc, lds);
.LBB0_277:
	v_mov_b32_e32 v99, v158
	v_mov_b32_e32 v2, v158
	s_lshl_b32 s8, s6, 1
	v_readfirstlane_b32 s5, v2
	s_ashr_i32 s19, s5, 7
	s_bfe_u32 s20, s5, 0x10006
	s_lshl_b32 s5, s7, 5
	s_lshl_b32 s4, s7, 7
	s_lshl_b32 s7, s19, 4
	s_add_i32 s5, s8, s5
	s_add_i32 s5, s5, s7
	s_or_b32 s8, s5, s20
	s_ashr_i32 s9, s8, 31
	v_and_b32_e32 v0, 63, v99
	s_lshl_b64 s[8:9], s[8:9], 12
	v_lshl_or_b32 v2, v0, 6, s8
	v_mov_b32_e32 v3, s9
	v_readlane_b32 s8, v240, 41
	v_readlane_b32 s9, v240, 42
	s_ashr_i32 s5, s4, 31
	s_lshl_b32 s6, s6, 7
	v_lshl_add_u64 v[6:7], s[8:9], 0, v[2:3]
	v_readlane_b32 s8, v240, 43
	v_readlane_b32 s9, v240, 44
	v_mov_b32_e32 v30, v158
	v_readlane_b32 s22, v240, 35
	v_lshl_add_u64 v[10:11], s[8:9], 0, v[2:3]
	s_lshl_b64 s[8:9], s[4:5], 10
	s_add_u32 s10, s74, s8
	s_addc_u32 s11, s75, s9
	s_ashr_i32 s7, s6, 31
	s_lshl_b64 s[12:13], s[6:7], 9
	s_add_u32 s12, s12, s94
	global_load_dwordx4 v[2:5], v[6:7], off offset:48 nt
	global_load_dwordx4 v[14:17], v[6:7], off offset:32 nt
	global_load_dwordx4 v[54:57], v[6:7], off offset:16 nt
	global_load_dwordx4 v[38:41], v[6:7], off nt
	s_nop 0
	global_load_dwordx4 v[6:9], v[10:11], off offset:48 nt
	global_load_dwordx4 v[18:21], v[10:11], off offset:32 nt
	global_load_dwordx4 v[58:61], v[10:11], off offset:16 nt
	global_load_dwordx4 v[46:49], v[10:11], off nt
	s_addc_u32 s13, s13, s95
	s_lshl_b64 s[12:13], s[12:13], 1
	v_ashrrev_i32_e32 v12, 3, v30
	v_lshrrev_b32_e32 v0, 4, v30
	v_ashrrev_i32_e32 v13, 31, v12
	v_xor_b32_e32 v0, v0, v30
	v_readlane_b32 s23, v240, 36
	s_add_u32 s22, s22, s12
	v_lshlrev_b64 v[10:11], 10, v[12:13]
	v_lshlrev_b32_e32 v0, 4, v0
	s_addc_u32 s23, s23, s13
	v_lshl_add_u64 v[10:11], s[10:11], 0, v[10:11]
	v_and_b32_e32 v0, 0x70, v0
	v_lshlrev_b32_e32 v35, 9, v12
	v_lshl_add_u64 v[10:11], v[10:11], 0, v[0:1]
	v_lshl_add_u64 v[26:27], s[22:23], 0, v[0:1]
	v_and_b32_e32 v0, 0xfe00, v35
	v_lshlrev_b32_e32 v34, 4, v30
	v_lshlrev_b32_e32 v0, 1, v0
	v_add_u32_e32 v22, 0x4000, v34
	v_readfirstlane_b32 s5, v34
	v_lshl_add_u64 v[12:13], v[26:27], 0, v[0:1]
	v_add_u32_e32 v0, 0x1000, v34
	s_mov_b32 m0, s5
	v_readfirstlane_b32 s10, v22
	v_readfirstlane_b32 s11, v0
	v_add_u32_e32 v0, 0x4000, v35
	global_load_lds_dwordx4 v[10:11], off
	s_mov_b32 m0, s10
	s_mov_b64 s[40:41], 0x8000
	v_and_b32_e32 v0, 0xfe00, v0
	global_load_lds_dwordx4 v[12:13], off
	v_lshl_add_u64 v[22:23], v[10:11], 0, s[40:41]
	s_mov_b32 m0, s11
	v_lshlrev_b32_e32 v0, 1, v0
	global_load_lds_dwordx4 v[22:23], off
	v_lshl_add_u64 v[22:23], v[26:27], 0, v[0:1]
	v_add_u32_e32 v0, 0x5000, v34
	s_mov_b32 s33, 0x8000
	v_readfirstlane_b32 s21, v0
	v_add_u32_e32 v0, 0x2000, v34
	s_mov_b32 m0, s21
	s_mov_b64 s[42:43], 0x10000
	v_readfirstlane_b32 s22, v0
	v_bitop3_b32 v0, v35, s33, v167 bitop3:0x6c
	global_load_lds_dwordx4 v[22:23], off
	v_lshl_add_u64 v[24:25], v[10:11], 0, s[42:43]
	s_mov_b32 m0, s22
	v_lshlrev_b32_e32 v0, 1, v0
	global_load_lds_dwordx4 v[24:25], off
	v_lshl_add_u64 v[24:25], v[26:27], 0, v[0:1]
	v_add_u32_e32 v0, 0x6000, v34
	v_readfirstlane_b32 s26, v30
	v_readfirstlane_b32 s23, v0
	v_add_u32_e32 v0, 0x3000, v34
	s_lshl_b32 s27, s26, 7
	v_readfirstlane_b32 s24, v0
	v_add_u32_e32 v0, 0xc000, v35
	v_and_b32_e32 v0, 0xfe00, v0
	v_lshlrev_b32_e32 v0, 1, v0
	v_lshl_add_u64 v[26:27], v[26:27], 0, v[0:1]
	v_add_u32_e32 v0, 0x7000, v34
	s_lshl_b32 s26, s26, 6
	v_readfirstlane_b32 s25, v0
	v_lshlrev_b32_e32 v0, 7, v30
	v_bfe_u32 v31, v30, 4, 2
	v_bfe_u32 v33, v30, 1, 3
	s_mov_b32 m0, s23
	s_mov_b64 s[50:51], 0x18000
	s_and_b32 s27, s27, 0x2000
	v_and_b32_e32 v0, 0x780, v0
	s_and_b32 s26, s26, 0xffffe000
	v_lshrrev_b32_e32 v32, 1, v30
	global_load_lds_dwordx4 v[24:25], off
	v_lshl_add_u64 v[28:29], v[10:11], 0, s[50:51]
	s_mov_b32 m0, s24
	v_or_b32_e32 v30, s27, v0
	v_or_b32_e32 v37, s26, v0
	v_bitop3_b32 v0, v31, v33, 4 bitop3:0x36
	global_load_lds_dwordx4 v[28:29], off
	v_bitop3_b32 v28, v32, v31, 7 bitop3:0x6c
	v_lshlrev_b32_e32 v31, 4, v0
	v_add_u32_e32 v0, 0x8000, v34
	s_mov_b32 m0, s25
	s_mov_b64 s[38:39], 0x80
	v_add_u32_e32 v32, 0xc000, v34
	v_readfirstlane_b32 s29, v0
	global_load_lds_dwordx4 v[26:27], off
	v_lshlrev_b32_e32 v36, 4, v28
	v_lshl_add_u64 v[28:29], v[10:11], 0, s[38:39]
	s_mov_b32 m0, s29
	v_readfirstlane_b32 s26, v32
	v_add_u32_e32 v0, 0x9000, v34
	s_waitcnt vmcnt(0) lgkmcnt(0)
	s_barrier
; #define MFMA16(a, b, c) __builtin_amdgcn_mfma_f32_16x16x32_bf16((a), (b), (c), 0, 0, 0)
; DI void gemm_tile(const bf16_t* __restrict__ A, int lda, const bf16_t* __restrict__ Bt, int ldb, int bvalid, int K, f32x4 (&acc)[4][4], char* lds, bool preloaded = false) {
;     ...
;   auto compute = [&](int st) {
;     const char* base = lds + st * 32768;
;     bf16x8 af[2][4], bfr[2][4];
; #pragma unroll
;     for (int s = 0; s < 2; ++s) {
;       const int ch = ((4 * s + fq) ^ fx) << 4;
; #pragma unroll
;       for (int mi = 0; mi < 4; ++mi) af[s][mi] = *(const bf16x8*)(base + (wm * 64 + mi * 16 + fr) * 128 + ch);
; #pragma unroll
;       for (int ni = 0; ni < 4; ++ni) bfr[s][ni] = *(const bf16x8*)(base + 16384 + (wn * 64 + ni * 16 + fr) * 128 + ch);
;     }
;     __builtin_amdgcn_s_setprio(1);
; #pragma unroll
;     for (int s = 0; s < 2; ++s)
; #pragma unroll
;       for (int mi = 0; mi < 4; ++mi)
; #pragma unroll
;         for (int ni = 0; ni < 4; ++ni) acc[mi][ni] = MFMA16(af[s][mi], bfr[s][ni], acc[mi][ni]);
;     __builtin_amdgcn_s_setprio(0);
;   };
;   const int nk = K >> 6;
;   if (!preloaded) { GLDS(0, 0) }
;   __syncthreads();
;   for (int kt = 0; kt < nk; ++kt) {
;     if (kt + 1 < nk) { GLDS((kt + 1) & 1, (kt + 1) << 6) }
;     compute(kt & 1);
;     __syncthreads();
;   }
	global_load_lds_dwordx4 v[28:29], off
	v_lshl_add_u64 v[28:29], v[12:13], 0, s[38:39]
	s_mov_b32 m0, s26
	s_mov_b64 s[58:59], 0x8080
	v_readfirstlane_b32 s27, v0
	v_add_u32_e32 v0, 0xd000, v34
	global_load_lds_dwordx4 v[28:29], off
	v_lshl_add_u64 v[28:29], v[10:11], 0, s[58:59]
	s_mov_b32 m0, s27
	v_readfirstlane_b32 s28, v0
	v_add_u32_e32 v0, 0xa000, v34
	global_load_lds_dwordx4 v[28:29], off
	v_lshl_add_u64 v[28:29], v[22:23], 0, s[38:39]
	s_mov_b32 m0, s28
	s_mov_b64 s[62:63], 0x10080
	v_readfirstlane_b32 s30, v0
	v_add_u32_e32 v0, 0xe000, v34
	global_load_lds_dwordx4 v[28:29], off
	v_lshl_add_u64 v[28:29], v[10:11], 0, s[62:63]
	s_mov_b32 m0, s30
	v_readfirstlane_b32 s31, v0
	v_add_u32_e32 v0, 0xb000, v34
	global_load_lds_dwordx4 v[28:29], off
	v_lshl_add_u64 v[28:29], v[24:25], 0, s[38:39]
	s_mov_b32 m0, s31
	s_mov_b64 s[68:69], 0x18080
	v_readfirstlane_b32 s34, v0
	v_add_u32_e32 v0, 0xf000, v34
	global_load_lds_dwordx4 v[28:29], off
	v_lshl_add_u64 v[28:29], v[10:11], 0, s[68:69]
	s_mov_b32 m0, s34
	v_readfirstlane_b32 s35, v0
	global_load_lds_dwordx4 v[28:29], off
	v_lshl_add_u64 v[28:29], v[26:27], 0, s[38:39]
	s_mov_b32 m0, s35
	v_or_b32_e32 v0, v36, v37
	global_load_lds_dwordx4 v[28:29], off
	v_or_b32_e32 v28, v36, v30
	v_or_b32_e32 v29, v31, v37
	v_or_b32_e32 v30, v31, v30
	ds_read_b128 v[32:35], v0
	ds_read_b128 v[42:45], v0 offset:2048
	ds_read_b128 v[50:53], v0 offset:4096
	ds_read_b128 v[62:65], v0 offset:6144
	ds_read_b128 v[66:69], v28 offset:16384
	ds_read_b128 v[70:73], v28 offset:18432
	ds_read_b128 v[74:77], v28 offset:20480
	ds_read_b128 v[78:81], v28 offset:22528
	ds_read_b128 v[82:85], v29
	ds_read_b128 v[86:89], v29 offset:2048
	ds_read_b128 v[90:93], v29 offset:4096
	ds_read_b128 v[94:97], v29 offset:6144
	ds_read_b128 v[100:103], v30 offset:16384
	ds_read_b128 v[104:107], v30 offset:18432
	ds_read_b128 v[108:111], v30 offset:20480
	ds_read_b128 v[112:115], v30 offset:22528
	v_and_b32_e32 v98, 15, v99
	s_setprio 1
	s_waitcnt lgkmcnt(8)
	v_mfma_f32_16x16x32_bf16 v[116:119], v[32:35], v[66:69], 0
	v_mfma_f32_16x16x32_bf16 v[120:123], v[32:35], v[70:73], 0
	v_mfma_f32_16x16x32_bf16 v[124:127], v[32:35], v[74:77], 0
	v_mfma_f32_16x16x32_bf16 v[32:35], v[32:35], v[78:81], 0
	v_mfma_f32_16x16x32_bf16 v[128:131], v[42:45], v[66:69], 0
	v_mfma_f32_16x16x32_bf16 v[132:135], v[42:45], v[70:73], 0
	v_mfma_f32_16x16x32_bf16 v[136:139], v[42:45], v[74:77], 0
	v_mfma_f32_16x16x32_bf16 v[42:45], v[42:45], v[78:81], 0
	v_mfma_f32_16x16x32_bf16 v[140:143], v[50:53], v[66:69], 0
	v_mfma_f32_16x16x32_bf16 v[144:147], v[50:53], v[70:73], 0
	v_mfma_f32_16x16x32_bf16 v[148:151], v[50:53], v[74:77], 0
	v_mfma_f32_16x16x32_bf16 v[50:53], v[50:53], v[78:81], 0
	v_mfma_f32_16x16x32_bf16 v[66:69], v[62:65], v[66:69], 0
	v_mfma_f32_16x16x32_bf16 v[70:73], v[62:65], v[70:73], 0
	v_mfma_f32_16x16x32_bf16 v[74:77], v[62:65], v[74:77], 0
	v_mfma_f32_16x16x32_bf16 v[62:65], v[62:65], v[78:81], 0
	s_waitcnt lgkmcnt(0)
	v_mfma_f32_16x16x32_bf16 v[78:81], v[82:85], v[100:103], v[116:119]
	v_mfma_f32_16x16x32_bf16 v[116:119], v[82:85], v[104:107], v[120:123]
	v_mfma_f32_16x16x32_bf16 v[120:123], v[82:85], v[108:111], v[124:127]
	v_mfma_f32_16x16x32_bf16 v[32:35], v[82:85], v[112:115], v[32:35]
	v_mfma_f32_16x16x32_bf16 v[82:85], v[86:89], v[100:103], v[128:131]
	v_mfma_f32_16x16x32_bf16 v[124:127], v[86:89], v[104:107], v[132:135]
	v_mfma_f32_16x16x32_bf16 v[128:131], v[86:89], v[108:111], v[136:139]
	v_mfma_f32_16x16x32_bf16 v[42:45], v[86:89], v[112:115], v[42:45]
	v_mfma_f32_16x16x32_bf16 v[86:89], v[90:93], v[100:103], v[140:143]
	v_mfma_f32_16x16x32_bf16 v[132:135], v[90:93], v[104:107], v[144:147]
	v_mfma_f32_16x16x32_bf16 v[136:139], v[90:93], v[108:111], v[148:151]
	v_mfma_f32_16x16x32_bf16 v[50:53], v[90:93], v[112:115], v[50:53]
	v_mfma_f32_16x16x32_bf16 v[66:69], v[94:97], v[100:103], v[66:69]
	v_mfma_f32_16x16x32_bf16 v[70:73], v[94:97], v[104:107], v[70:73]
	v_mfma_f32_16x16x32_bf16 v[74:77], v[94:97], v[108:111], v[74:77]
	v_mfma_f32_16x16x32_bf16 v[62:65], v[94:97], v[112:115], v[62:65]
	s_setprio 0
	s_mov_b64 s[36:37], 0x100
	s_mov_b32 m0, s5
	v_lshl_add_u64 v[36:37], v[10:11], 0, s[36:37]
	s_waitcnt vmcnt(0)
	s_barrier
	global_load_lds_dwordx4 v[36:37], off
	v_lshl_add_u64 v[36:37], v[12:13], 0, s[36:37]
	s_mov_b32 m0, s10
	s_mov_b64 s[70:71], 0x8100
	global_load_lds_dwordx4 v[36:37], off
	v_lshl_add_u64 v[36:37], v[10:11], 0, s[70:71]
	s_mov_b32 m0, s11
	s_mov_b64 s[92:93], 0x10100
	global_load_lds_dwordx4 v[36:37], off
	v_lshl_add_u64 v[36:37], v[22:23], 0, s[36:37]
	s_mov_b32 m0, s21
	s_mov_b64 s[0:1], 0x18100
	global_load_lds_dwordx4 v[36:37], off
	v_lshl_add_u64 v[36:37], v[10:11], 0, s[92:93]
	s_mov_b32 m0, s22
	s_nop 0
	global_load_lds_dwordx4 v[36:37], off
	v_lshl_add_u64 v[36:37], v[24:25], 0, s[36:37]
	s_mov_b32 m0, s23
	s_nop 0
	global_load_lds_dwordx4 v[36:37], off
	v_lshl_add_u64 v[36:37], v[10:11], 0, s[0:1]
	s_mov_b32 m0, s24
	s_nop 0
	global_load_lds_dwordx4 v[36:37], off
	v_lshl_add_u64 v[36:37], v[26:27], 0, s[36:37]
	s_mov_b32 m0, s25
	s_nop 0
	global_load_lds_dwordx4 v[36:37], off
	ds_read_b128 v[90:93], v0 offset:32768
	ds_read_b128 v[94:97], v0 offset:34816
	ds_read_b128 v[100:103], v0 offset:36864
	ds_read_b128 v[104:107], v0 offset:38912
	ds_read_b128 v[108:111], v28 offset:49152
	ds_read_b128 v[112:115], v28 offset:51200
	ds_read_b128 v[140:143], v28 offset:53248
	ds_read_b128 v[144:147], v28 offset:55296
	ds_read_b128 v[148:151], v29 offset:32768
	ds_read_b128 v[152:155], v29 offset:34816
	ds_read_b128 v[180:183], v29 offset:36864
	ds_read_b128 v[184:187], v29 offset:38912
	ds_read_b128 v[188:191], v30 offset:49152
	ds_read_b128 v[192:195], v30 offset:51200
	ds_read_b128 v[196:199], v30 offset:53248
	ds_read_b128 v[200:203], v30 offset:55296
	s_setprio 1
	s_waitcnt lgkmcnt(8)
; #define MFMA16(a, b, c) __builtin_amdgcn_mfma_f32_16x16x32_bf16((a), (b), (c), 0, 0, 0)
; DI void gemm_tile(const bf16_t* __restrict__ A, int lda, const bf16_t* __restrict__ Bt, int ldb, int bvalid, int K, f32x4 (&acc)[4][4], char* lds, bool preloaded = false) {
;     ...
;   auto compute = [&](int st) {
;     const char* base = lds + st * 32768;
;     bf16x8 af[2][4], bfr[2][4];
; #pragma unroll
;     for (int s = 0; s < 2; ++s) {
;       const int ch = ((4 * s + fq) ^ fx) << 4;
; #pragma unroll
;       for (int mi = 0; mi < 4; ++mi) af[s][mi] = *(const bf16x8*)(base + (wm * 64 + mi * 16 + fr) * 128 + ch);
; #pragma unroll
;       for (int ni = 0; ni < 4; ++ni) bfr[s][ni] = *(const bf16x8*)(base + 16384 + (wn * 64 + ni * 16 + fr) * 128 + ch);
;     }
;     __builtin_amdgcn_s_setprio(1);
; #pragma unroll
;     for (int s = 0; s < 2; ++s)
; #pragma unroll
;       for (int mi = 0; mi < 4; ++mi)
; #pragma unroll
;         for (int ni = 0; ni < 4; ++ni) acc[mi][ni] = MFMA16(af[s][mi], bfr[s][ni], acc[mi][ni]);
;     __builtin_amdgcn_s_setprio(0);
;   };
;   const int nk = K >> 6;
;   if (!preloaded) { GLDS(0, 0) }
;   __syncthreads();
;   for (int kt = 0; kt < nk; ++kt) {
;     if (kt + 1 < nk) { GLDS((kt + 1) & 1, (kt + 1) << 6) }
;     compute(kt & 1);
;     __syncthreads();
;   }
	v_mfma_f32_16x16x32_bf16 v[78:81], v[90:93], v[108:111], v[78:81]
	v_mfma_f32_16x16x32_bf16 v[116:119], v[90:93], v[112:115], v[116:119]
	v_mfma_f32_16x16x32_bf16 v[120:123], v[90:93], v[140:143], v[120:123]
	v_mfma_f32_16x16x32_bf16 v[32:35], v[90:93], v[144:147], v[32:35]
	v_mfma_f32_16x16x32_bf16 v[82:85], v[94:97], v[108:111], v[82:85]
	v_mfma_f32_16x16x32_bf16 v[90:93], v[94:97], v[112:115], v[124:127]
	v_mfma_f32_16x16x32_bf16 v[124:127], v[94:97], v[140:143], v[128:131]
	v_mfma_f32_16x16x32_bf16 v[42:45], v[94:97], v[144:147], v[42:45]
	v_mfma_f32_16x16x32_bf16 v[86:89], v[100:103], v[108:111], v[86:89]
	v_mfma_f32_16x16x32_bf16 v[94:97], v[100:103], v[112:115], v[132:135]
	v_mfma_f32_16x16x32_bf16 v[128:131], v[100:103], v[140:143], v[136:139]
	v_mfma_f32_16x16x32_bf16 v[50:53], v[100:103], v[144:147], v[50:53]
	v_mfma_f32_16x16x32_bf16 v[66:69], v[104:107], v[108:111], v[66:69]
	v_mfma_f32_16x16x32_bf16 v[70:73], v[104:107], v[112:115], v[70:73]
	v_mfma_f32_16x16x32_bf16 v[74:77], v[104:107], v[140:143], v[74:77]
	v_mfma_f32_16x16x32_bf16 v[62:65], v[104:107], v[144:147], v[62:65]
	s_waitcnt lgkmcnt(0)
	v_mfma_f32_16x16x32_bf16 v[78:81], v[148:151], v[188:191], v[78:81]
	v_mfma_f32_16x16x32_bf16 v[100:103], v[148:151], v[192:195], v[116:119]
	v_mfma_f32_16x16x32_bf16 v[104:107], v[148:151], v[196:199], v[120:123]
	v_mfma_f32_16x16x32_bf16 v[32:35], v[148:151], v[200:203], v[32:35]
	v_mfma_f32_16x16x32_bf16 v[82:85], v[152:155], v[188:191], v[82:85]
	v_mfma_f32_16x16x32_bf16 v[90:93], v[152:155], v[192:195], v[90:93]
	v_mfma_f32_16x16x32_bf16 v[108:111], v[152:155], v[196:199], v[124:127]
	v_mfma_f32_16x16x32_bf16 v[42:45], v[152:155], v[200:203], v[42:45]
	v_mfma_f32_16x16x32_bf16 v[86:89], v[180:183], v[188:191], v[86:89]
	v_mfma_f32_16x16x32_bf16 v[94:97], v[180:183], v[192:195], v[94:97]
	v_mfma_f32_16x16x32_bf16 v[112:115], v[180:183], v[196:199], v[128:131]
	v_mfma_f32_16x16x32_bf16 v[50:53], v[180:183], v[200:203], v[50:53]
	v_mfma_f32_16x16x32_bf16 v[66:69], v[184:187], v[188:191], v[66:69]
	v_mfma_f32_16x16x32_bf16 v[70:73], v[184:187], v[192:195], v[70:73]
	v_mfma_f32_16x16x32_bf16 v[74:77], v[184:187], v[196:199], v[74:77]
	v_mfma_f32_16x16x32_bf16 v[62:65], v[184:187], v[200:203], v[62:65]
	s_setprio 0
	s_mov_b64 s[0:1], 0x180
	s_mov_b32 m0, s29
	v_lshl_add_u64 v[36:37], v[10:11], 0, s[0:1]
	s_waitcnt vmcnt(0)
	s_barrier
	global_load_lds_dwordx4 v[36:37], off
	v_lshl_add_u64 v[36:37], v[12:13], 0, s[0:1]
	s_mov_b32 m0, s26
	s_mov_b64 s[2:3], 0x8180
	global_load_lds_dwordx4 v[36:37], off
	v_lshl_add_u64 v[36:37], v[10:11], 0, s[2:3]
	s_mov_b32 m0, s27
	s_mov_b64 s[2:3], 0x10180
	global_load_lds_dwordx4 v[36:37], off
	v_lshl_add_u64 v[36:37], v[22:23], 0, s[0:1]
	s_mov_b32 m0, s28
	s_nop 0
	global_load_lds_dwordx4 v[36:37], off
	v_lshl_add_u64 v[36:37], v[10:11], 0, s[2:3]
	s_mov_b32 m0, s30
	s_mov_b64 s[2:3], 0x18180
	global_load_lds_dwordx4 v[36:37], off
	v_lshl_add_u64 v[36:37], v[24:25], 0, s[0:1]
	s_mov_b32 m0, s31
	s_nop 0
	global_load_lds_dwordx4 v[36:37], off
	v_lshl_add_u64 v[36:37], v[10:11], 0, s[2:3]
	s_mov_b32 m0, s34
	s_nop 0
	global_load_lds_dwordx4 v[36:37], off
	v_lshl_add_u64 v[36:37], v[26:27], 0, s[0:1]
	s_mov_b32 m0, s35
	s_nop 0
	global_load_lds_dwordx4 v[36:37], off
	ds_read_b128 v[116:119], v0
	ds_read_b128 v[120:123], v0 offset:2048
	ds_read_b128 v[124:127], v0 offset:4096
	ds_read_b128 v[128:131], v0 offset:6144
	ds_read_b128 v[132:135], v28 offset:16384
	ds_read_b128 v[136:139], v28 offset:18432
	ds_read_b128 v[140:143], v28 offset:20480
	ds_read_b128 v[144:147], v28 offset:22528
	ds_read_b128 v[148:151], v29
	ds_read_b128 v[152:155], v29 offset:2048
	ds_read_b128 v[180:183], v29 offset:4096
	ds_read_b128 v[184:187], v29 offset:6144
	ds_read_b128 v[188:191], v30 offset:16384
	ds_read_b128 v[192:195], v30 offset:18432
	ds_read_b128 v[196:199], v30 offset:20480
	ds_read_b128 v[200:203], v30 offset:22528
	s_setprio 1
	s_waitcnt lgkmcnt(8)
	v_mfma_f32_16x16x32_bf16 v[78:81], v[116:119], v[132:135], v[78:81]
	v_mfma_f32_16x16x32_bf16 v[100:103], v[116:119], v[136:139], v[100:103]
	v_mfma_f32_16x16x32_bf16 v[104:107], v[116:119], v[140:143], v[104:107]
	v_mfma_f32_16x16x32_bf16 v[32:35], v[116:119], v[144:147], v[32:35]
	v_mfma_f32_16x16x32_bf16 v[82:85], v[120:123], v[132:135], v[82:85]
	v_mfma_f32_16x16x32_bf16 v[90:93], v[120:123], v[136:139], v[90:93]
	v_mfma_f32_16x16x32_bf16 v[108:111], v[120:123], v[140:143], v[108:111]
	v_mfma_f32_16x16x32_bf16 v[42:45], v[120:123], v[144:147], v[42:45]
	v_mfma_f32_16x16x32_bf16 v[86:89], v[124:127], v[132:135], v[86:89]
	v_mfma_f32_16x16x32_bf16 v[94:97], v[124:127], v[136:139], v[94:97]
	v_mfma_f32_16x16x32_bf16 v[112:115], v[124:127], v[140:143], v[112:115]
	v_mfma_f32_16x16x32_bf16 v[50:53], v[124:127], v[144:147], v[50:53]
	v_mfma_f32_16x16x32_bf16 v[66:69], v[128:131], v[132:135], v[66:69]
	v_mfma_f32_16x16x32_bf16 v[70:73], v[128:131], v[136:139], v[70:73]
	v_mfma_f32_16x16x32_bf16 v[74:77], v[128:131], v[140:143], v[74:77]
	v_mfma_f32_16x16x32_bf16 v[62:65], v[128:131], v[144:147], v[62:65]
	s_waitcnt lgkmcnt(0)
	v_mfma_f32_16x16x32_bf16 v[78:81], v[148:151], v[188:191], v[78:81]
	v_mfma_f32_16x16x32_bf16 v[100:103], v[148:151], v[192:195], v[100:103]
	v_mfma_f32_16x16x32_bf16 v[104:107], v[148:151], v[196:199], v[104:107]
	v_mfma_f32_16x16x32_bf16 v[32:35], v[148:151], v[200:203], v[32:35]
	v_mfma_f32_16x16x32_bf16 v[82:85], v[152:155], v[188:191], v[82:85]
	v_mfma_f32_16x16x32_bf16 v[90:93], v[152:155], v[192:195], v[90:93]
	v_mfma_f32_16x16x32_bf16 v[108:111], v[152:155], v[196:199], v[108:111]
	v_mfma_f32_16x16x32_bf16 v[42:45], v[152:155], v[200:203], v[42:45]
	v_mfma_f32_16x16x32_bf16 v[86:89], v[180:183], v[188:191], v[86:89]
	v_mfma_f32_16x16x32_bf16 v[94:97], v[180:183], v[192:195], v[94:97]
	v_mfma_f32_16x16x32_bf16 v[112:115], v[180:183], v[196:199], v[112:115]
	v_mfma_f32_16x16x32_bf16 v[50:53], v[180:183], v[200:203], v[50:53]
	v_mfma_f32_16x16x32_bf16 v[66:69], v[184:187], v[188:191], v[66:69]
	v_mfma_f32_16x16x32_bf16 v[70:73], v[184:187], v[192:195], v[70:73]
	v_mfma_f32_16x16x32_bf16 v[74:77], v[184:187], v[196:199], v[74:77]
	v_mfma_f32_16x16x32_bf16 v[62:65], v[184:187], v[200:203], v[62:65]
	s_setprio 0
	s_mov_b64 s[36:37], 0x200
	s_mov_b32 m0, s5
	v_lshl_add_u64 v[36:37], v[10:11], 0, s[36:37]
	s_waitcnt vmcnt(0)
	s_barrier
; #define MFMA16(a, b, c) __builtin_amdgcn_mfma_f32_16x16x32_bf16((a), (b), (c), 0, 0, 0)
; DI void gemm_tile(const bf16_t* __restrict__ A, int lda, const bf16_t* __restrict__ Bt, int ldb, int bvalid, int K, f32x4 (&acc)[4][4], char* lds, bool preloaded = false) {
;     ...
;   auto compute = [&](int st) {
;     const char* base = lds + st * 32768;
;     bf16x8 af[2][4], bfr[2][4];
; #pragma unroll
;     for (int s = 0; s < 2; ++s) {
;       const int ch = ((4 * s + fq) ^ fx) << 4;
; #pragma unroll
;       for (int mi = 0; mi < 4; ++mi) af[s][mi] = *(const bf16x8*)(base + (wm * 64 + mi * 16 + fr) * 128 + ch);
; #pragma unroll
;       for (int ni = 0; ni < 4; ++ni) bfr[s][ni] = *(const bf16x8*)(base + 16384 + (wn * 64 + ni * 16 + fr) * 128 + ch);
;     }
;     __builtin_amdgcn_s_setprio(1);
; #pragma unroll
;     for (int s = 0; s < 2; ++s)
; #pragma unroll
;       for (int mi = 0; mi < 4; ++mi)
; #pragma unroll
;         for (int ni = 0; ni < 4; ++ni) acc[mi][ni] = MFMA16(af[s][mi], bfr[s][ni], acc[mi][ni]);
;     __builtin_amdgcn_s_setprio(0);
;   };
;   const int nk = K >> 6;
;   if (!preloaded) { GLDS(0, 0) }
;   __syncthreads();
;   for (int kt = 0; kt < nk; ++kt) {
;     if (kt + 1 < nk) { GLDS((kt + 1) & 1, (kt + 1) << 6) }
;     compute(kt & 1);
;     __syncthreads();
;   }
	global_load_lds_dwordx4 v[36:37], off
	v_lshl_add_u64 v[36:37], v[12:13], 0, s[36:37]
	s_mov_b32 m0, s10
	s_mov_b64 s[2:3], 0x8200
	global_load_lds_dwordx4 v[36:37], off
	v_lshl_add_u64 v[36:37], v[10:11], 0, s[2:3]
	s_mov_b32 m0, s11
	s_mov_b64 s[2:3], 0x10200
	global_load_lds_dwordx4 v[36:37], off
	v_lshl_add_u64 v[36:37], v[22:23], 0, s[36:37]
	s_mov_b32 m0, s21
	s_nop 0
	global_load_lds_dwordx4 v[36:37], off
	v_lshl_add_u64 v[36:37], v[10:11], 0, s[2:3]
	s_mov_b32 m0, s22
	s_mov_b64 s[2:3], 0x18200
	global_load_lds_dwordx4 v[36:37], off
	v_lshl_add_u64 v[36:37], v[24:25], 0, s[36:37]
	s_mov_b32 m0, s23
	s_nop 0
	global_load_lds_dwordx4 v[36:37], off
	v_lshl_add_u64 v[36:37], v[10:11], 0, s[2:3]
	s_mov_b32 m0, s24
	s_nop 0
	global_load_lds_dwordx4 v[36:37], off
	v_lshl_add_u64 v[36:37], v[26:27], 0, s[36:37]
	s_mov_b32 m0, s25
	s_nop 0
	global_load_lds_dwordx4 v[36:37], off
	ds_read_b128 v[116:119], v0 offset:32768
	ds_read_b128 v[120:123], v0 offset:34816
	ds_read_b128 v[124:127], v0 offset:36864
	ds_read_b128 v[128:131], v0 offset:38912
	ds_read_b128 v[132:135], v28 offset:49152
	ds_read_b128 v[136:139], v28 offset:51200
	ds_read_b128 v[140:143], v28 offset:53248
	ds_read_b128 v[144:147], v28 offset:55296
	ds_read_b128 v[148:151], v29 offset:32768
	ds_read_b128 v[152:155], v29 offset:34816
	ds_read_b128 v[180:183], v29 offset:36864
	ds_read_b128 v[184:187], v29 offset:38912
	ds_read_b128 v[188:191], v30 offset:49152
	ds_read_b128 v[192:195], v30 offset:51200
	ds_read_b128 v[196:199], v30 offset:53248
	ds_read_b128 v[200:203], v30 offset:55296
	s_setprio 1
	s_waitcnt lgkmcnt(8)
	v_mfma_f32_16x16x32_bf16 v[78:81], v[116:119], v[132:135], v[78:81]
	v_mfma_f32_16x16x32_bf16 v[100:103], v[116:119], v[136:139], v[100:103]
	v_mfma_f32_16x16x32_bf16 v[104:107], v[116:119], v[140:143], v[104:107]
	v_mfma_f32_16x16x32_bf16 v[32:35], v[116:119], v[144:147], v[32:35]
	v_mfma_f32_16x16x32_bf16 v[82:85], v[120:123], v[132:135], v[82:85]
	v_mfma_f32_16x16x32_bf16 v[90:93], v[120:123], v[136:139], v[90:93]
	v_mfma_f32_16x16x32_bf16 v[108:111], v[120:123], v[140:143], v[108:111]
	v_mfma_f32_16x16x32_bf16 v[42:45], v[120:123], v[144:147], v[42:45]
	v_mfma_f32_16x16x32_bf16 v[86:89], v[124:127], v[132:135], v[86:89]
	v_mfma_f32_16x16x32_bf16 v[94:97], v[124:127], v[136:139], v[94:97]
	v_mfma_f32_16x16x32_bf16 v[112:115], v[124:127], v[140:143], v[112:115]
	v_mfma_f32_16x16x32_bf16 v[50:53], v[124:127], v[144:147], v[50:53]
	v_mfma_f32_16x16x32_bf16 v[66:69], v[128:131], v[132:135], v[66:69]
	v_mfma_f32_16x16x32_bf16 v[70:73], v[128:131], v[136:139], v[70:73]
	v_mfma_f32_16x16x32_bf16 v[74:77], v[128:131], v[140:143], v[74:77]
	v_mfma_f32_16x16x32_bf16 v[62:65], v[128:131], v[144:147], v[62:65]
	s_waitcnt lgkmcnt(0)
	v_mfma_f32_16x16x32_bf16 v[78:81], v[148:151], v[188:191], v[78:81]
	v_mfma_f32_16x16x32_bf16 v[100:103], v[148:151], v[192:195], v[100:103]
	v_mfma_f32_16x16x32_bf16 v[104:107], v[148:151], v[196:199], v[104:107]
	v_mfma_f32_16x16x32_bf16 v[32:35], v[148:151], v[200:203], v[32:35]
	v_mfma_f32_16x16x32_bf16 v[82:85], v[152:155], v[188:191], v[82:85]
	v_mfma_f32_16x16x32_bf16 v[90:93], v[152:155], v[192:195], v[90:93]
	v_mfma_f32_16x16x32_bf16 v[108:111], v[152:155], v[196:199], v[108:111]
	v_mfma_f32_16x16x32_bf16 v[42:45], v[152:155], v[200:203], v[42:45]
	v_mfma_f32_16x16x32_bf16 v[86:89], v[180:183], v[188:191], v[86:89]
	v_mfma_f32_16x16x32_bf16 v[94:97], v[180:183], v[192:195], v[94:97]
	v_mfma_f32_16x16x32_bf16 v[112:115], v[180:183], v[196:199], v[112:115]
	v_mfma_f32_16x16x32_bf16 v[50:53], v[180:183], v[200:203], v[50:53]
	v_mfma_f32_16x16x32_bf16 v[66:69], v[184:187], v[188:191], v[66:69]
	v_mfma_f32_16x16x32_bf16 v[70:73], v[184:187], v[192:195], v[70:73]
	v_mfma_f32_16x16x32_bf16 v[74:77], v[184:187], v[196:199], v[74:77]
	v_mfma_f32_16x16x32_bf16 v[62:65], v[184:187], v[200:203], v[62:65]
	s_setprio 0
	s_mov_b64 s[2:3], 0x280
	s_mov_b32 m0, s29
	v_lshl_add_u64 v[36:37], v[10:11], 0, s[2:3]
	s_waitcnt vmcnt(0)
	s_barrier
	global_load_lds_dwordx4 v[36:37], off
	v_lshl_add_u64 v[36:37], v[12:13], 0, s[2:3]
	s_mov_b32 m0, s26
	s_mov_b64 s[14:15], 0x8280
	global_load_lds_dwordx4 v[36:37], off
	v_lshl_add_u64 v[36:37], v[10:11], 0, s[14:15]
	s_mov_b32 m0, s27
	s_mov_b64 s[14:15], 0x10280
	global_load_lds_dwordx4 v[36:37], off
	v_lshl_add_u64 v[36:37], v[22:23], 0, s[2:3]
	s_mov_b32 m0, s28
	s_nop 0
	global_load_lds_dwordx4 v[36:37], off
	v_lshl_add_u64 v[36:37], v[10:11], 0, s[14:15]
	s_mov_b32 m0, s30
	s_mov_b64 s[14:15], 0x18280
	global_load_lds_dwordx4 v[36:37], off
	v_lshl_add_u64 v[36:37], v[24:25], 0, s[2:3]
	s_mov_b32 m0, s31
	s_nop 0
	global_load_lds_dwordx4 v[36:37], off
	v_lshl_add_u64 v[36:37], v[10:11], 0, s[14:15]
	s_mov_b32 m0, s34
	s_nop 0
	global_load_lds_dwordx4 v[36:37], off
	v_lshl_add_u64 v[36:37], v[26:27], 0, s[2:3]
	s_mov_b32 m0, s35
	s_nop 0
	global_load_lds_dwordx4 v[36:37], off
	ds_read_b128 v[116:119], v0
	ds_read_b128 v[120:123], v0 offset:2048
	ds_read_b128 v[124:127], v0 offset:4096
	ds_read_b128 v[128:131], v0 offset:6144
	ds_read_b128 v[132:135], v28 offset:16384
	ds_read_b128 v[136:139], v28 offset:18432
	ds_read_b128 v[140:143], v28 offset:20480
	ds_read_b128 v[144:147], v28 offset:22528
	ds_read_b128 v[148:151], v29
	ds_read_b128 v[152:155], v29 offset:2048
	ds_read_b128 v[180:183], v29 offset:4096
	ds_read_b128 v[184:187], v29 offset:6144
	ds_read_b128 v[188:191], v30 offset:16384
	ds_read_b128 v[192:195], v30 offset:18432
	ds_read_b128 v[196:199], v30 offset:20480
	ds_read_b128 v[200:203], v30 offset:22528
	s_setprio 1
	s_waitcnt lgkmcnt(8)
; #define MFMA16(a, b, c) __builtin_amdgcn_mfma_f32_16x16x32_bf16((a), (b), (c), 0, 0, 0)
; DI void gemm_tile(const bf16_t* __restrict__ A, int lda, const bf16_t* __restrict__ Bt, int ldb, int bvalid, int K, f32x4 (&acc)[4][4], char* lds, bool preloaded = false) {
;     ...
;   auto compute = [&](int st) {
;     const char* base = lds + st * 32768;
;     bf16x8 af[2][4], bfr[2][4];
; #pragma unroll
;     for (int s = 0; s < 2; ++s) {
;       const int ch = ((4 * s + fq) ^ fx) << 4;
; #pragma unroll
;       for (int mi = 0; mi < 4; ++mi) af[s][mi] = *(const bf16x8*)(base + (wm * 64 + mi * 16 + fr) * 128 + ch);
; #pragma unroll
;       for (int ni = 0; ni < 4; ++ni) bfr[s][ni] = *(const bf16x8*)(base + 16384 + (wn * 64 + ni * 16 + fr) * 128 + ch);
;     }
;     __builtin_amdgcn_s_setprio(1);
; #pragma unroll
;     for (int s = 0; s < 2; ++s)
; #pragma unroll
;       for (int mi = 0; mi < 4; ++mi)
; #pragma unroll
;         for (int ni = 0; ni < 4; ++ni) acc[mi][ni] = MFMA16(af[s][mi], bfr[s][ni], acc[mi][ni]);
;     __builtin_amdgcn_s_setprio(0);
;   };
;   const int nk = K >> 6;
;   if (!preloaded) { GLDS(0, 0) }
;   __syncthreads();
;   for (int kt = 0; kt < nk; ++kt) {
;     if (kt + 1 < nk) { GLDS((kt + 1) & 1, (kt + 1) << 6) }
;     compute(kt & 1);
;     __syncthreads();
;   }
	v_mfma_f32_16x16x32_bf16 v[78:81], v[116:119], v[132:135], v[78:81]
	v_mfma_f32_16x16x32_bf16 v[100:103], v[116:119], v[136:139], v[100:103]
	v_mfma_f32_16x16x32_bf16 v[104:107], v[116:119], v[140:143], v[104:107]
	v_mfma_f32_16x16x32_bf16 v[32:35], v[116:119], v[144:147], v[32:35]
	v_mfma_f32_16x16x32_bf16 v[82:85], v[120:123], v[132:135], v[82:85]
	v_mfma_f32_16x16x32_bf16 v[90:93], v[120:123], v[136:139], v[90:93]
	v_mfma_f32_16x16x32_bf16 v[108:111], v[120:123], v[140:143], v[108:111]
	v_mfma_f32_16x16x32_bf16 v[42:45], v[120:123], v[144:147], v[42:45]
	v_mfma_f32_16x16x32_bf16 v[86:89], v[124:127], v[132:135], v[86:89]
	v_mfma_f32_16x16x32_bf16 v[94:97], v[124:127], v[136:139], v[94:97]
	v_mfma_f32_16x16x32_bf16 v[112:115], v[124:127], v[140:143], v[112:115]
	v_mfma_f32_16x16x32_bf16 v[50:53], v[124:127], v[144:147], v[50:53]
	v_mfma_f32_16x16x32_bf16 v[66:69], v[128:131], v[132:135], v[66:69]
	v_mfma_f32_16x16x32_bf16 v[70:73], v[128:131], v[136:139], v[70:73]
	v_mfma_f32_16x16x32_bf16 v[74:77], v[128:131], v[140:143], v[74:77]
	v_mfma_f32_16x16x32_bf16 v[62:65], v[128:131], v[144:147], v[62:65]
	s_waitcnt lgkmcnt(0)
	v_mfma_f32_16x16x32_bf16 v[78:81], v[148:151], v[188:191], v[78:81]
	v_mfma_f32_16x16x32_bf16 v[100:103], v[148:151], v[192:195], v[100:103]
	v_mfma_f32_16x16x32_bf16 v[104:107], v[148:151], v[196:199], v[104:107]
	v_mfma_f32_16x16x32_bf16 v[32:35], v[148:151], v[200:203], v[32:35]
	v_mfma_f32_16x16x32_bf16 v[82:85], v[152:155], v[188:191], v[82:85]
	v_mfma_f32_16x16x32_bf16 v[90:93], v[152:155], v[192:195], v[90:93]
	v_mfma_f32_16x16x32_bf16 v[108:111], v[152:155], v[196:199], v[108:111]
	v_mfma_f32_16x16x32_bf16 v[42:45], v[152:155], v[200:203], v[42:45]
	v_mfma_f32_16x16x32_bf16 v[86:89], v[180:183], v[188:191], v[86:89]
	v_mfma_f32_16x16x32_bf16 v[94:97], v[180:183], v[192:195], v[94:97]
	v_mfma_f32_16x16x32_bf16 v[112:115], v[180:183], v[196:199], v[112:115]
	v_mfma_f32_16x16x32_bf16 v[50:53], v[180:183], v[200:203], v[50:53]
	v_mfma_f32_16x16x32_bf16 v[66:69], v[184:187], v[188:191], v[66:69]
	v_mfma_f32_16x16x32_bf16 v[70:73], v[184:187], v[192:195], v[70:73]
	v_mfma_f32_16x16x32_bf16 v[74:77], v[184:187], v[196:199], v[74:77]
	v_mfma_f32_16x16x32_bf16 v[62:65], v[184:187], v[200:203], v[62:65]
	s_setprio 0
	s_mov_b64 s[14:15], 0x300
	s_mov_b32 m0, s5
	v_lshl_add_u64 v[36:37], v[10:11], 0, s[14:15]
	s_waitcnt vmcnt(0)
	s_barrier
	global_load_lds_dwordx4 v[36:37], off
	v_lshl_add_u64 v[36:37], v[12:13], 0, s[14:15]
	s_mov_b32 m0, s10
	s_mov_b64 s[64:65], 0x8300
	global_load_lds_dwordx4 v[36:37], off
	v_lshl_add_u64 v[36:37], v[10:11], 0, s[64:65]
	s_mov_b32 m0, s11
	s_mov_b64 s[10:11], 0x10300
	global_load_lds_dwordx4 v[36:37], off
	v_lshl_add_u64 v[36:37], v[22:23], 0, s[14:15]
	s_mov_b32 m0, s21
	s_nop 0
	global_load_lds_dwordx4 v[36:37], off
	v_lshl_add_u64 v[36:37], v[10:11], 0, s[10:11]
	s_mov_b32 m0, s22
	s_mov_b64 s[10:11], 0x18300
	global_load_lds_dwordx4 v[36:37], off
	v_lshl_add_u64 v[36:37], v[24:25], 0, s[14:15]
	s_mov_b32 m0, s23
	s_nop 0
	global_load_lds_dwordx4 v[36:37], off
	v_lshl_add_u64 v[36:37], v[10:11], 0, s[10:11]
	s_mov_b32 m0, s24
	s_nop 0
	global_load_lds_dwordx4 v[36:37], off
	v_lshl_add_u64 v[36:37], v[26:27], 0, s[14:15]
	s_mov_b32 m0, s25
	s_nop 0
	global_load_lds_dwordx4 v[36:37], off
	ds_read_b128 v[116:119], v0 offset:32768
	ds_read_b128 v[120:123], v0 offset:34816
	ds_read_b128 v[124:127], v0 offset:36864
	ds_read_b128 v[128:131], v0 offset:38912
	ds_read_b128 v[132:135], v28 offset:49152
	ds_read_b128 v[136:139], v28 offset:51200
	ds_read_b128 v[140:143], v28 offset:53248
	ds_read_b128 v[144:147], v28 offset:55296
	ds_read_b128 v[148:151], v29 offset:32768
	ds_read_b128 v[152:155], v29 offset:34816
	ds_read_b128 v[180:183], v29 offset:36864
	ds_read_b128 v[184:187], v29 offset:38912
	ds_read_b128 v[188:191], v30 offset:49152
	ds_read_b128 v[192:195], v30 offset:51200
	ds_read_b128 v[196:199], v30 offset:53248
	ds_read_b128 v[200:203], v30 offset:55296
	s_setprio 1
	s_waitcnt lgkmcnt(8)
	v_mfma_f32_16x16x32_bf16 v[78:81], v[116:119], v[132:135], v[78:81]
	v_mfma_f32_16x16x32_bf16 v[100:103], v[116:119], v[136:139], v[100:103]
	v_mfma_f32_16x16x32_bf16 v[104:107], v[116:119], v[140:143], v[104:107]
	v_mfma_f32_16x16x32_bf16 v[32:35], v[116:119], v[144:147], v[32:35]
	v_mfma_f32_16x16x32_bf16 v[82:85], v[120:123], v[132:135], v[82:85]
	v_mfma_f32_16x16x32_bf16 v[90:93], v[120:123], v[136:139], v[90:93]
	v_mfma_f32_16x16x32_bf16 v[108:111], v[120:123], v[140:143], v[108:111]
	v_mfma_f32_16x16x32_bf16 v[42:45], v[120:123], v[144:147], v[42:45]
	v_mfma_f32_16x16x32_bf16 v[86:89], v[124:127], v[132:135], v[86:89]
	v_mfma_f32_16x16x32_bf16 v[94:97], v[124:127], v[136:139], v[94:97]
	v_mfma_f32_16x16x32_bf16 v[112:115], v[124:127], v[140:143], v[112:115]
	v_mfma_f32_16x16x32_bf16 v[50:53], v[124:127], v[144:147], v[50:53]
	v_mfma_f32_16x16x32_bf16 v[66:69], v[128:131], v[132:135], v[66:69]
	v_mfma_f32_16x16x32_bf16 v[70:73], v[128:131], v[136:139], v[70:73]
	v_mfma_f32_16x16x32_bf16 v[74:77], v[128:131], v[140:143], v[74:77]
	v_mfma_f32_16x16x32_bf16 v[62:65], v[128:131], v[144:147], v[62:65]
	s_waitcnt lgkmcnt(0)
	v_mfma_f32_16x16x32_bf16 v[78:81], v[148:151], v[188:191], v[78:81]
	v_mfma_f32_16x16x32_bf16 v[100:103], v[148:151], v[192:195], v[100:103]
	v_mfma_f32_16x16x32_bf16 v[104:107], v[148:151], v[196:199], v[104:107]
	v_mfma_f32_16x16x32_bf16 v[32:35], v[148:151], v[200:203], v[32:35]
	v_mfma_f32_16x16x32_bf16 v[82:85], v[152:155], v[188:191], v[82:85]
	v_mfma_f32_16x16x32_bf16 v[90:93], v[152:155], v[192:195], v[90:93]
	v_mfma_f32_16x16x32_bf16 v[108:111], v[152:155], v[196:199], v[108:111]
	v_mfma_f32_16x16x32_bf16 v[42:45], v[152:155], v[200:203], v[42:45]
	v_mfma_f32_16x16x32_bf16 v[86:89], v[180:183], v[188:191], v[86:89]
	v_mfma_f32_16x16x32_bf16 v[94:97], v[180:183], v[192:195], v[94:97]
	v_mfma_f32_16x16x32_bf16 v[112:115], v[180:183], v[196:199], v[112:115]
	v_mfma_f32_16x16x32_bf16 v[50:53], v[180:183], v[200:203], v[50:53]
	v_mfma_f32_16x16x32_bf16 v[66:69], v[184:187], v[188:191], v[66:69]
	v_mfma_f32_16x16x32_bf16 v[70:73], v[184:187], v[192:195], v[70:73]
	v_mfma_f32_16x16x32_bf16 v[74:77], v[184:187], v[196:199], v[74:77]
	v_mfma_f32_16x16x32_bf16 v[62:65], v[184:187], v[200:203], v[62:65]
	s_setprio 0
	s_mov_b64 s[64:65], 0x380
	s_mov_b32 m0, s29
	v_lshl_add_u64 v[36:37], v[10:11], 0, s[64:65]
	s_waitcnt vmcnt(0)
	s_barrier
; #define MFMA16(a, b, c) __builtin_amdgcn_mfma_f32_16x16x32_bf16((a), (b), (c), 0, 0, 0)
; DI void gemm_tile(const bf16_t* __restrict__ A, int lda, const bf16_t* __restrict__ Bt, int ldb, int bvalid, int K, f32x4 (&acc)[4][4], char* lds, bool preloaded = false) {
;     ...
;   auto compute = [&](int st) {
;     const char* base = lds + st * 32768;
;     bf16x8 af[2][4], bfr[2][4];
; #pragma unroll
;     for (int s = 0; s < 2; ++s) {
;       const int ch = ((4 * s + fq) ^ fx) << 4;
; #pragma unroll
;       for (int mi = 0; mi < 4; ++mi) af[s][mi] = *(const bf16x8*)(base + (wm * 64 + mi * 16 + fr) * 128 + ch);
; #pragma unroll
;       for (int ni = 0; ni < 4; ++ni) bfr[s][ni] = *(const bf16x8*)(base + 16384 + (wn * 64 + ni * 16 + fr) * 128 + ch);
;     }
;     __builtin_amdgcn_s_setprio(1);
; #pragma unroll
;     for (int s = 0; s < 2; ++s)
; #pragma unroll
;       for (int mi = 0; mi < 4; ++mi)
; #pragma unroll
;         for (int ni = 0; ni < 4; ++ni) acc[mi][ni] = MFMA16(af[s][mi], bfr[s][ni], acc[mi][ni]);
;     __builtin_amdgcn_s_setprio(0);
;   };
;   const int nk = K >> 6;
;   if (!preloaded) { GLDS(0, 0) }
;   __syncthreads();
;   for (int kt = 0; kt < nk; ++kt) {
;     if (kt + 1 < nk) { GLDS((kt + 1) & 1, (kt + 1) << 6) }
;     compute(kt & 1);
;     __syncthreads();
;   }
	global_load_lds_dwordx4 v[36:37], off
	v_lshl_add_u64 v[12:13], v[12:13], 0, s[64:65]
	s_mov_b32 m0, s26
	s_mov_b64 s[10:11], 0x8380
	global_load_lds_dwordx4 v[12:13], off
	v_lshl_add_u64 v[12:13], v[10:11], 0, s[10:11]
	s_mov_b32 m0, s27
	s_mov_b64 s[10:11], 0x10380
	global_load_lds_dwordx4 v[12:13], off
	v_lshl_add_u64 v[12:13], v[22:23], 0, s[64:65]
	s_mov_b32 m0, s28
	s_nop 0
	global_load_lds_dwordx4 v[12:13], off
	v_lshl_add_u64 v[12:13], v[10:11], 0, s[10:11]
	s_mov_b32 m0, s30
	s_mov_b64 s[10:11], 0x18380
	global_load_lds_dwordx4 v[12:13], off
	v_lshl_add_u64 v[12:13], v[24:25], 0, s[64:65]
	s_mov_b32 m0, s31
	v_lshl_add_u64 v[10:11], v[10:11], 0, s[10:11]
	global_load_lds_dwordx4 v[12:13], off
	s_mov_b32 m0, s34
	s_nop 0
	global_load_lds_dwordx4 v[10:11], off
	v_lshl_add_u64 v[10:11], v[26:27], 0, s[64:65]
	s_mov_b32 m0, s35
	s_nop 0
	global_load_lds_dwordx4 v[10:11], off
	ds_read_b128 v[10:13], v0
	ds_read_b128 v[22:25], v0 offset:2048
	ds_read_b128 v[116:119], v0 offset:4096
	ds_read_b128 v[120:123], v0 offset:6144
	ds_read_b128 v[124:127], v28 offset:16384
	ds_read_b128 v[128:131], v28 offset:18432
	ds_read_b128 v[132:135], v28 offset:20480
	ds_read_b128 v[136:139], v28 offset:22528
	ds_read_b128 v[140:143], v29
	ds_read_b128 v[144:147], v29 offset:2048
	ds_read_b128 v[148:151], v29 offset:4096
	ds_read_b128 v[152:155], v29 offset:6144
	ds_read_b128 v[180:183], v30 offset:16384
	ds_read_b128 v[184:187], v30 offset:18432
	ds_read_b128 v[188:191], v30 offset:20480
	ds_read_b128 v[192:195], v30 offset:22528
	s_setprio 1
	s_waitcnt lgkmcnt(8)
	v_mfma_f32_16x16x32_bf16 v[78:81], v[10:13], v[124:127], v[78:81]
	v_mfma_f32_16x16x32_bf16 v[100:103], v[10:13], v[128:131], v[100:103]
	v_mfma_f32_16x16x32_bf16 v[104:107], v[10:13], v[132:135], v[104:107]
	v_mfma_f32_16x16x32_bf16 v[10:13], v[10:13], v[136:139], v[32:35]
	v_mfma_f32_16x16x32_bf16 v[32:35], v[22:25], v[124:127], v[82:85]
	v_mfma_f32_16x16x32_bf16 v[82:85], v[22:25], v[128:131], v[90:93]
	v_mfma_f32_16x16x32_bf16 v[90:93], v[22:25], v[132:135], v[108:111]
	v_mfma_f32_16x16x32_bf16 v[22:25], v[22:25], v[136:139], v[42:45]
	v_mfma_f32_16x16x32_bf16 v[42:45], v[116:119], v[124:127], v[86:89]
	v_mfma_f32_16x16x32_bf16 v[86:89], v[116:119], v[128:131], v[94:97]
	v_mfma_f32_16x16x32_bf16 v[94:97], v[116:119], v[132:135], v[112:115]
	v_mfma_f32_16x16x32_bf16 v[50:53], v[116:119], v[136:139], v[50:53]
	v_mfma_f32_16x16x32_bf16 v[66:69], v[120:123], v[124:127], v[66:69]
	v_mfma_f32_16x16x32_bf16 v[70:73], v[120:123], v[128:131], v[70:73]
	v_mfma_f32_16x16x32_bf16 v[74:77], v[120:123], v[132:135], v[74:77]
	v_mfma_f32_16x16x32_bf16 v[62:65], v[120:123], v[136:139], v[62:65]
	s_waitcnt lgkmcnt(0)
	v_mfma_f32_16x16x32_bf16 v[78:81], v[140:143], v[180:183], v[78:81]
	v_mfma_f32_16x16x32_bf16 v[100:103], v[140:143], v[184:187], v[100:103]
	v_mfma_f32_16x16x32_bf16 v[104:107], v[140:143], v[188:191], v[104:107]
	v_mfma_f32_16x16x32_bf16 v[10:13], v[140:143], v[192:195], v[10:13]
	v_mfma_f32_16x16x32_bf16 v[32:35], v[144:147], v[180:183], v[32:35]
	v_mfma_f32_16x16x32_bf16 v[82:85], v[144:147], v[184:187], v[82:85]
	v_mfma_f32_16x16x32_bf16 v[90:93], v[144:147], v[188:191], v[90:93]
	v_mfma_f32_16x16x32_bf16 v[22:25], v[144:147], v[192:195], v[22:25]
	v_mfma_f32_16x16x32_bf16 v[42:45], v[148:151], v[180:183], v[42:45]
	v_mfma_f32_16x16x32_bf16 v[86:89], v[148:151], v[184:187], v[86:89]
	v_mfma_f32_16x16x32_bf16 v[94:97], v[148:151], v[188:191], v[94:97]
	v_mfma_f32_16x16x32_bf16 v[50:53], v[148:151], v[192:195], v[50:53]
	v_mfma_f32_16x16x32_bf16 v[66:69], v[152:155], v[180:183], v[66:69]
	v_mfma_f32_16x16x32_bf16 v[70:73], v[152:155], v[184:187], v[70:73]
	v_mfma_f32_16x16x32_bf16 v[74:77], v[152:155], v[188:191], v[74:77]
	v_mfma_f32_16x16x32_bf16 v[62:65], v[152:155], v[192:195], v[62:65]
	s_setprio 0
	s_waitcnt vmcnt(0)
	s_barrier
	ds_read_b128 v[108:111], v0 offset:32768
	ds_read_b128 v[112:115], v0 offset:34816
	ds_read_b128 v[116:119], v0 offset:36864
	ds_read_b128 v[120:123], v0 offset:38912
	ds_read_b128 v[124:127], v28 offset:49152
	ds_read_b128 v[128:131], v28 offset:51200
	ds_read_b128 v[132:135], v28 offset:53248
	ds_read_b128 v[136:139], v28 offset:55296
	ds_read_b128 v[140:143], v29 offset:32768
	ds_read_b128 v[144:147], v29 offset:34816
	ds_read_b128 v[148:151], v29 offset:36864
	ds_read_b128 v[26:29], v29 offset:38912
	ds_read_b128 v[152:155], v30 offset:49152
	ds_read_b128 v[180:183], v30 offset:51200
	ds_read_b128 v[184:187], v30 offset:53248
	ds_read_b128 v[188:191], v30 offset:55296
	s_setprio 1
	s_waitcnt lgkmcnt(11)
	v_mfma_f32_16x16x32_bf16 v[78:81], v[108:111], v[124:127], v[78:81]
	s_waitcnt lgkmcnt(10)
	v_mfma_f32_16x16x32_bf16 v[100:103], v[108:111], v[128:131], v[100:103]
	s_waitcnt lgkmcnt(9)
	v_mfma_f32_16x16x32_bf16 v[104:107], v[108:111], v[132:135], v[104:107]
	s_waitcnt lgkmcnt(8)
	v_mfma_f32_16x16x32_bf16 v[108:111], v[108:111], v[136:139], v[10:13]
	v_mfma_f32_16x16x32_bf16 v[34:37], v[112:115], v[124:127], v[32:35]
	v_mfma_f32_16x16x32_bf16 v[82:85], v[112:115], v[128:131], v[82:85]
	v_mfma_f32_16x16x32_bf16 v[192:195], v[112:115], v[132:135], v[90:93]
	v_mfma_f32_16x16x32_bf16 v[112:115], v[112:115], v[136:139], v[22:25]
	v_mfma_f32_16x16x32_bf16 v[42:45], v[116:119], v[124:127], v[42:45]
	v_mfma_f32_16x16x32_bf16 v[196:199], v[116:119], v[128:131], v[86:89]
	v_mfma_f32_16x16x32_bf16 v[200:203], v[116:119], v[132:135], v[94:97]
	v_mfma_f32_16x16x32_bf16 v[50:53], v[116:119], v[136:139], v[50:53]
	v_mfma_f32_16x16x32_bf16 v[116:119], v[120:123], v[124:127], v[66:69]
	v_mfma_f32_16x16x32_bf16 v[124:127], v[120:123], v[128:131], v[70:73]
	v_mfma_f32_16x16x32_bf16 v[128:131], v[120:123], v[132:135], v[74:77]
	v_mfma_f32_16x16x32_bf16 v[120:123], v[120:123], v[136:139], v[62:65]
	s_waitcnt lgkmcnt(3)
	v_mfma_f32_16x16x32_bf16 v[10:13], v[140:143], v[152:155], v[78:81]
	s_waitcnt lgkmcnt(2)
	v_mfma_f32_16x16x32_bf16 v[22:25], v[140:143], v[180:183], v[100:103]
	s_waitcnt lgkmcnt(1)
	v_mfma_f32_16x16x32_bf16 v[30:33], v[140:143], v[184:187], v[104:107]
	s_waitcnt lgkmcnt(0)
	v_mfma_f32_16x16x32_bf16 v[94:97], v[140:143], v[188:191], v[108:111]
	v_mfma_f32_16x16x32_bf16 v[90:93], v[144:147], v[152:155], v[34:37]
	v_mfma_f32_16x16x32_bf16 v[62:65], v[144:147], v[180:183], v[82:85]
	v_mfma_f32_16x16x32_bf16 v[70:73], v[144:147], v[184:187], v[192:195]
	v_mfma_f32_16x16x32_bf16 v[86:89], v[144:147], v[188:191], v[112:115]
	v_mfma_f32_16x16x32_bf16 v[82:85], v[148:151], v[152:155], v[42:45]
	v_mfma_f32_16x16x32_bf16 v[78:81], v[148:151], v[180:183], v[196:199]
	v_mfma_f32_16x16x32_bf16 v[74:77], v[148:151], v[184:187], v[200:203]
	v_mfma_f32_16x16x32_bf16 v[66:69], v[148:151], v[188:191], v[50:53]
	v_mfma_f32_16x16x32_bf16 v[50:53], v[26:29], v[152:155], v[116:119]
	v_mfma_f32_16x16x32_bf16 v[42:45], v[26:29], v[180:183], v[124:127]
	v_mfma_f32_16x16x32_bf16 v[34:37], v[26:29], v[184:187], v[128:131]
	v_mfma_f32_16x16x32_bf16 v[26:29], v[26:29], v[188:191], v[120:123]
	s_setprio 0
	v_mov_b32_e32 v106, v158
	s_barrier
; DI int tidx() { int t = __builtin_amdgcn_workitem_id_x(); asm volatile("" : "+v"(t)); return t; }
; DI void gemm_prefetch0(const bf16_t* __restrict__ A, int lda, const bf16_t* __restrict__ Bt, int ldb, int bvalid, char* lds) {
;   const int tid = tidx();
;   const int lr = tid >> 3, lc = tid & 7;
;   const bf16_t* ap = A + (size_t)lr * lda + ((lc ^ ((lr >> 1) & 7)) << 3);
;   const bf16_t* bp = Bt + ((lc ^ ((lr >> 1) & 7)) << 3);
;   typedef __attribute__((address_space(1))) const unsigned gptr_t;
;   typedef __attribute__((address_space(3))) unsigned lptr_t;
;   const unsigned lbase = (unsigned)(size_t)lds + (unsigned)tid * 16u;
; #pragma unroll
;   for (int i = 0; i < 4; ++i) {
;     __builtin_amdgcn_global_load_lds((gptr_t*)(ap + (size_t)(32 * i) * lda), (lptr_t*)(lbase + i * 4096), 16, 0, 0);
;     __builtin_amdgcn_global_load_lds((gptr_t*)(bp + (size_t)((lr + 32 * i) & (bvalid - 1)) * ldb), (lptr_t*)(lbase + 16384 + i * 4096), 16, 0, 0);
;   }
; DI void phaseD_tile(const P& p, int layer, int mt, int nt, char* lds) {
;     ...
;   gemm_prefetch0((const bf16_t*)(p.ws + W_ZA) + (size_t)row0 * 512, 512, (const bf16_t*)(p.ws + W_WAO) + ((size_t)layer * 1024 + col0) * 512, 512, 128, lds);
; #pragma unroll
;   for (int mi = 0; mi < 4; ++mi)
; #pragma unroll
;     for (int ni = 0; ni < 4; ++ni)
; #pragma unroll
;       for (int j = 0; j < 4; ++j) acc[mi][ni][j] *= (float)((gpv[mi][ni] >> (8 * j)) & 255u) / fmaxf((float)((gav[mi][ni] >> (8 * j)) & 255u), 1.f);
	s_add_u32 s10, s97, s8
	v_readlane_b32 s5, v240, 45
	s_addc_u32 s11, s5, s9
	v_ashrrev_i32_e32 v100, 3, v106
	v_lshrrev_b32_e32 v0, 4, v106
	v_readlane_b32 s8, v240, 33
	v_ashrrev_i32_e32 v101, 31, v100
	v_xor_b32_e32 v0, v0, v106
	v_readlane_b32 s9, v240, 34
	s_add_u32 s8, s8, s12
	v_lshlrev_b64 v[102:103], 10, v[100:101]
	v_lshlrev_b32_e32 v0, 4, v0
	s_addc_u32 s9, s9, s13
	v_lshl_add_u64 v[102:103], s[10:11], 0, v[102:103]
	v_and_b32_e32 v0, 0x70, v0
	v_lshlrev_b32_e32 v107, 9, v100
	v_lshl_add_u64 v[102:103], v[102:103], 0, v[0:1]
	v_lshl_add_u64 v[104:105], s[8:9], 0, v[0:1]
	v_lshlrev_b32_e32 v106, 4, v106
	v_and_b32_e32 v0, 0xfe00, v107
	v_add_u32_e32 v108, 0x4000, v106
	v_readfirstlane_b32 s5, v106
	v_lshlrev_b32_e32 v0, 1, v0
	s_mov_b32 m0, s5
	v_lshl_add_u64 v[100:101], v[104:105], 0, v[0:1]
	v_readfirstlane_b32 s5, v108
	v_add_u32_e32 v0, 0x1000, v106
	global_load_lds_dwordx4 v[102:103], off
	s_mov_b32 m0, s5
	v_readfirstlane_b32 s5, v0
	v_add_u32_e32 v0, 0x4000, v107
	v_and_b32_e32 v0, 0xfe00, v0
	global_load_lds_dwordx4 v[100:101], off
	v_lshl_add_u64 v[100:101], v[102:103], 0, s[40:41]
	s_mov_b32 m0, s5
	v_lshlrev_b32_e32 v0, 1, v0
	global_load_lds_dwordx4 v[100:101], off
	v_lshl_add_u64 v[100:101], v[104:105], 0, v[0:1]
	v_add_u32_e32 v0, 0x5000, v106
	s_mov_b64 s[30:31], 0x100
	v_readfirstlane_b32 s5, v0
	v_add_u32_e32 v0, 0x2000, v106
	s_mov_b32 m0, s5
	v_readfirstlane_b32 s5, v0
	v_bitop3_b32 v0, v107, s33, v167 bitop3:0x6c
	global_load_lds_dwordx4 v[100:101], off
	v_lshl_add_u64 v[100:101], v[102:103], 0, s[42:43]
	s_mov_b32 m0, s5
	v_lshlrev_b32_e32 v0, 1, v0
	global_load_lds_dwordx4 v[100:101], off
	v_lshl_add_u64 v[100:101], v[104:105], 0, v[0:1]
	v_add_u32_e32 v0, 0x6000, v106
	s_nop 0
	v_readfirstlane_b32 s5, v0
	v_add_u32_e32 v0, 0x3000, v106
	s_mov_b32 m0, s5
	v_readfirstlane_b32 s5, v0
	v_add_u32_e32 v0, 0xc000, v107
	v_and_b32_e32 v0, 0xfe00, v0
	global_load_lds_dwordx4 v[100:101], off
	v_lshl_add_u64 v[100:101], v[102:103], 0, s[50:51]
	s_mov_b32 m0, s5
	v_lshlrev_b32_e32 v0, 1, v0
	global_load_lds_dwordx4 v[100:101], off
	v_lshl_add_u64 v[100:101], v[104:105], 0, v[0:1]
	v_add_u32_e32 v0, 0x7000, v106
	v_cvt_f32_ubyte2_e32 v104, v38
	v_readfirstlane_b32 s5, v0
	s_mov_b32 m0, s5
	v_cvt_f32_ubyte0_e32 v0, v46
	global_load_lds_dwordx4 v[100:101], off
	v_max_f32_e32 v100, 1.0, v0
	v_cvt_f32_ubyte1_e32 v0, v46
	v_max_f32_e32 v101, 1.0, v0
	v_cvt_f32_ubyte2_e32 v0, v46
	v_max_f32_e32 v102, 1.0, v0
	v_cvt_f32_ubyte3_e32 v0, v46
	v_max_f32_e32 v103, 1.0, v0
	v_cvt_f32_ubyte0_e32 v0, v38
	v_cvt_f32_ubyte1_e32 v46, v38
	v_cvt_f32_ubyte3_e32 v38, v38
	v_rcp_f32_e32 v105, v103
	s_nop 0
	v_mul_f32_e32 v105, v38, v105
	v_rcp_f32_e32 v38, v102
	s_nop 0
	v_mul_f32_e32 v104, v104, v38
	v_pk_mul_f32 v[12:13], v[104:105], v[12:13]
	v_rcp_f32_e32 v38, v101
	s_nop 0
	v_mul_f32_e32 v107, v46, v38
	v_rcp_f32_e32 v38, v100
	s_nop 0
	v_mul_f32_e32 v106, v0, v38
	v_cvt_f32_ubyte0_e32 v0, v47
	v_max_f32_e32 v104, 1.0, v0
	v_cvt_f32_ubyte1_e32 v0, v47
	v_max_f32_e32 v105, 1.0, v0
	v_cvt_f32_ubyte2_e32 v0, v47
	v_pk_mul_f32 v[10:11], v[106:107], v[10:11]
	v_max_f32_e32 v106, 1.0, v0
	v_cvt_f32_ubyte3_e32 v0, v47
	v_max_f32_e32 v107, 1.0, v0
	v_cvt_f32_ubyte0_e32 v0, v39
	v_cvt_f32_ubyte1_e32 v46, v39
	v_cvt_f32_ubyte2_e32 v38, v39
	v_cvt_f32_ubyte3_e32 v39, v39
	v_rcp_f32_e32 v47, v107
	s_nop 0
	v_mul_f32_e32 v39, v39, v47
	v_rcp_f32_e32 v47, v106
	s_nop 0
	v_mul_f32_e32 v38, v38, v47
	v_pk_mul_f32 v[24:25], v[38:39], v[24:25]
	v_cvt_f32_ubyte3_e32 v39, v40
	v_cvt_f32_ubyte2_e32 v38, v40
	v_rcp_f32_e32 v47, v105
	s_nop 0
	v_mul_f32_e32 v47, v46, v47
	v_rcp_f32_e32 v46, v104
	s_nop 0
	v_mul_f32_e32 v46, v0, v46
	v_cvt_f32_ubyte0_e32 v0, v48
	v_max_f32_e32 v108, 1.0, v0
	v_cvt_f32_ubyte1_e32 v0, v48
	v_max_f32_e32 v109, 1.0, v0
	v_cvt_f32_ubyte2_e32 v0, v48
	v_max_f32_e32 v110, 1.0, v0
	v_cvt_f32_ubyte3_e32 v0, v48
	v_max_f32_e32 v111, 1.0, v0
	v_pk_mul_f32 v[22:23], v[46:47], v[22:23]
	v_cvt_f32_ubyte0_e32 v0, v40
	v_cvt_f32_ubyte1_e32 v46, v40
	v_rcp_f32_e32 v40, v111
	s_nop 0
	v_mul_f32_e32 v39, v39, v40
	v_rcp_f32_e32 v40, v110
	s_nop 0
	v_mul_f32_e32 v38, v38, v40
	v_pk_mul_f32 v[32:33], v[38:39], v[32:33]
	v_cvt_f32_ubyte1_e32 v38, v41
	v_cvt_f32_ubyte2_e32 v39, v41
	v_rcp_f32_e32 v40, v109
	s_nop 0
	v_mul_f32_e32 v47, v46, v40
	v_rcp_f32_e32 v40, v108
	s_nop 0
	v_mul_f32_e32 v46, v0, v40
	v_cvt_f32_ubyte0_e32 v0, v49
	v_max_f32_e32 v112, 1.0, v0
	v_cvt_f32_ubyte1_e32 v0, v49
	v_max_f32_e32 v113, 1.0, v0
	v_cvt_f32_ubyte2_e32 v0, v49
	v_max_f32_e32 v114, 1.0, v0
	v_cvt_f32_ubyte3_e32 v0, v49
	v_max_f32_e32 v115, 1.0, v0
	v_cvt_f32_ubyte3_e32 v40, v41
	v_cvt_f32_ubyte0_e32 v0, v41
	v_pk_mul_f32 v[30:31], v[46:47], v[30:31]
	v_rcp_f32_e32 v41, v115
	s_nop 0
	v_mul_f32_e32 v41, v40, v41
	v_rcp_f32_e32 v40, v114
	s_nop 0
	v_mul_f32_e32 v40, v39, v40
	v_pk_mul_f32 v[40:41], v[40:41], v[96:97]
	v_rcp_f32_e32 v39, v113
	s_nop 0
	v_mul_f32_e32 v39, v38, v39
	v_rcp_f32_e32 v38, v112
	s_nop 0
	v_mul_f32_e32 v38, v0, v38
	v_cvt_f32_ubyte0_e32 v0, v58
	v_pk_mul_f32 v[38:39], v[38:39], v[94:95]
	v_max_f32_e32 v94, 1.0, v0
	v_cvt_f32_ubyte1_e32 v0, v58
	v_max_f32_e32 v95, 1.0, v0
	v_cvt_f32_ubyte2_e32 v0, v58
	v_max_f32_e32 v96, 1.0, v0
	v_cvt_f32_ubyte3_e32 v0, v58
	v_max_f32_e32 v97, 1.0, v0
	v_cvt_f32_ubyte3_e32 v48, v54
	v_cvt_f32_ubyte0_e32 v0, v54
	v_cvt_f32_ubyte1_e32 v46, v54
	v_cvt_f32_ubyte2_e32 v47, v54
	v_rcp_f32_e32 v49, v97
	s_nop 0
	v_mul_f32_e32 v49, v48, v49
	v_rcp_f32_e32 v48, v96
	s_nop 0
	v_mul_f32_e32 v48, v47, v48
	v_pk_mul_f32 v[48:49], v[48:49], v[92:93]
	v_rcp_f32_e32 v47, v95
	s_nop 0
	v_mul_f32_e32 v47, v46, v47
; DI void phaseD_tile(const P& p, int layer, int mt, int nt, char* lds) {
;     ...
; #pragma unroll
;   for (int mi = 0; mi < 4; ++mi)
; #pragma unroll
;     for (int ni = 0; ni < 4; ++ni)
; #pragma unroll
;       for (int j = 0; j < 4; ++j) acc[mi][ni][j] *= (float)((gpv[mi][ni] >> (8 * j)) & 255u) / fmaxf((float)((gav[mi][ni] >> (8 * j)) & 255u), 1.f);
	v_rcp_f32_e32 v46, v94
	s_nop 0
	v_mul_f32_e32 v46, v0, v46
	v_cvt_f32_ubyte0_e32 v0, v59
	v_pk_mul_f32 v[46:47], v[46:47], v[90:91]
	v_max_f32_e32 v90, 1.0, v0
	v_cvt_f32_ubyte1_e32 v0, v59
	v_max_f32_e32 v91, 1.0, v0
	v_cvt_f32_ubyte2_e32 v0, v59
	v_max_f32_e32 v92, 1.0, v0
	v_cvt_f32_ubyte3_e32 v0, v59
	v_max_f32_e32 v93, 1.0, v0
	v_cvt_f32_ubyte0_e32 v0, v55
	v_cvt_f32_ubyte1_e32 v58, v55
	v_cvt_f32_ubyte2_e32 v54, v55
	v_cvt_f32_ubyte3_e32 v55, v55
	v_rcp_f32_e32 v59, v93
	s_nop 0
	v_mul_f32_e32 v55, v55, v59
	v_rcp_f32_e32 v59, v92
	s_nop 0
	v_mul_f32_e32 v54, v54, v59
	v_pk_mul_f32 v[64:65], v[54:55], v[64:65]
	v_cvt_f32_ubyte3_e32 v55, v56
	v_cvt_f32_ubyte2_e32 v54, v56
	v_rcp_f32_e32 v59, v91
	s_nop 0
	v_mul_f32_e32 v59, v58, v59
	v_rcp_f32_e32 v58, v90
	s_nop 0
	v_mul_f32_e32 v58, v0, v58
	v_cvt_f32_ubyte0_e32 v0, v60
	v_max_f32_e32 v116, 1.0, v0
	v_cvt_f32_ubyte1_e32 v0, v60
	v_max_f32_e32 v117, 1.0, v0
	v_cvt_f32_ubyte2_e32 v0, v60
	v_max_f32_e32 v118, 1.0, v0
	v_cvt_f32_ubyte3_e32 v0, v60
	v_max_f32_e32 v119, 1.0, v0
	v_pk_mul_f32 v[62:63], v[58:59], v[62:63]
	v_cvt_f32_ubyte0_e32 v0, v56
	v_cvt_f32_ubyte1_e32 v58, v56
	v_rcp_f32_e32 v56, v119
	s_nop 0
	v_mul_f32_e32 v55, v55, v56
	v_rcp_f32_e32 v56, v118
	s_nop 0
	v_mul_f32_e32 v54, v54, v56
	v_pk_mul_f32 v[72:73], v[54:55], v[72:73]
	v_cvt_f32_ubyte1_e32 v54, v57
	v_cvt_f32_ubyte2_e32 v55, v57
	v_rcp_f32_e32 v56, v117
	s_nop 0
	v_mul_f32_e32 v59, v58, v56
	v_rcp_f32_e32 v56, v116
	s_nop 0
	v_mul_f32_e32 v58, v0, v56
	v_cvt_f32_ubyte0_e32 v0, v61
	v_max_f32_e32 v120, 1.0, v0
	v_cvt_f32_ubyte1_e32 v0, v61
	v_max_f32_e32 v121, 1.0, v0
	v_cvt_f32_ubyte2_e32 v0, v61
	v_max_f32_e32 v122, 1.0, v0
	v_cvt_f32_ubyte3_e32 v0, v61
	v_max_f32_e32 v123, 1.0, v0
	v_cvt_f32_ubyte3_e32 v56, v57
	v_cvt_f32_ubyte0_e32 v0, v57
	v_pk_mul_f32 v[70:71], v[58:59], v[70:71]
	v_rcp_f32_e32 v57, v123
	s_nop 0
	v_mul_f32_e32 v57, v56, v57
	v_rcp_f32_e32 v56, v122
	s_nop 0
	v_mul_f32_e32 v56, v55, v56
	v_pk_mul_f32 v[56:57], v[56:57], v[88:89]
	v_rcp_f32_e32 v55, v121
	s_nop 0
	v_mul_f32_e32 v55, v54, v55
	v_rcp_f32_e32 v54, v120
	s_nop 0
	v_mul_f32_e32 v54, v0, v54
	v_cvt_f32_ubyte0_e32 v0, v18
	v_pk_mul_f32 v[54:55], v[54:55], v[86:87]
	v_max_f32_e32 v86, 1.0, v0
	v_cvt_f32_ubyte1_e32 v0, v18
	v_max_f32_e32 v87, 1.0, v0
	v_cvt_f32_ubyte2_e32 v0, v18
	v_max_f32_e32 v88, 1.0, v0
	v_cvt_f32_ubyte3_e32 v0, v18
	v_max_f32_e32 v89, 1.0, v0
	v_cvt_f32_ubyte0_e32 v0, v14
	v_cvt_f32_ubyte1_e32 v18, v14
	v_cvt_f32_ubyte2_e32 v58, v14
	v_cvt_f32_ubyte3_e32 v14, v14
	v_rcp_f32_e32 v59, v89
	s_nop 0
	v_mul_f32_e32 v61, v14, v59
	v_rcp_f32_e32 v14, v88
	s_nop 0
	v_mul_f32_e32 v60, v58, v14
	v_pk_mul_f32 v[60:61], v[60:61], v[84:85]
	v_rcp_f32_e32 v14, v87
	s_nop 0
	v_mul_f32_e32 v59, v18, v14
	v_rcp_f32_e32 v14, v86
	s_nop 0
	v_mul_f32_e32 v58, v0, v14
	v_cvt_f32_ubyte0_e32 v0, v19
	v_pk_mul_f32 v[58:59], v[58:59], v[82:83]
	v_max_f32_e32 v82, 1.0, v0
	v_cvt_f32_ubyte1_e32 v0, v19
	v_max_f32_e32 v83, 1.0, v0
	v_cvt_f32_ubyte2_e32 v0, v19
	v_max_f32_e32 v84, 1.0, v0
	v_cvt_f32_ubyte3_e32 v0, v19
	v_max_f32_e32 v85, 1.0, v0
	v_cvt_f32_ubyte0_e32 v0, v15
	v_cvt_f32_ubyte1_e32 v18, v15
	v_cvt_f32_ubyte2_e32 v14, v15
	v_cvt_f32_ubyte3_e32 v15, v15
	v_rcp_f32_e32 v19, v85
	s_nop 0
	v_mul_f32_e32 v15, v15, v19
	v_rcp_f32_e32 v19, v84
	s_nop 0
	v_mul_f32_e32 v14, v14, v19
	v_pk_mul_f32 v[80:81], v[14:15], v[80:81]
	v_cvt_f32_ubyte3_e32 v15, v16
	v_cvt_f32_ubyte2_e32 v14, v16
	v_rcp_f32_e32 v19, v83
	s_nop 0
	v_mul_f32_e32 v19, v18, v19
	v_rcp_f32_e32 v18, v82
	s_nop 0
	v_mul_f32_e32 v18, v0, v18
	v_cvt_f32_ubyte0_e32 v0, v20
	v_max_f32_e32 v124, 1.0, v0
	v_cvt_f32_ubyte1_e32 v0, v20
	v_max_f32_e32 v125, 1.0, v0
	v_cvt_f32_ubyte2_e32 v0, v20
	v_max_f32_e32 v126, 1.0, v0
	v_cvt_f32_ubyte3_e32 v0, v20
	v_max_f32_e32 v127, 1.0, v0
	v_pk_mul_f32 v[78:79], v[18:19], v[78:79]
	v_cvt_f32_ubyte0_e32 v0, v16
	v_cvt_f32_ubyte1_e32 v18, v16
	v_rcp_f32_e32 v16, v127
	s_nop 0
	v_mul_f32_e32 v15, v15, v16
	v_rcp_f32_e32 v16, v126
	s_nop 0
	v_mul_f32_e32 v14, v14, v16
	v_pk_mul_f32 v[76:77], v[14:15], v[76:77]
	v_cvt_f32_ubyte1_e32 v14, v17
	v_cvt_f32_ubyte2_e32 v15, v17
	v_rcp_f32_e32 v16, v125
	s_nop 0
	v_mul_f32_e32 v19, v18, v16
	v_rcp_f32_e32 v16, v124
	s_nop 0
	v_mul_f32_e32 v18, v0, v16
	v_cvt_f32_ubyte0_e32 v0, v21
	v_max_f32_e32 v128, 1.0, v0
	v_cvt_f32_ubyte1_e32 v0, v21
	v_max_f32_e32 v129, 1.0, v0
	v_cvt_f32_ubyte2_e32 v0, v21
	v_max_f32_e32 v130, 1.0, v0
	v_cvt_f32_ubyte3_e32 v0, v21
	v_max_f32_e32 v131, 1.0, v0
	v_cvt_f32_ubyte3_e32 v16, v17
	v_cvt_f32_ubyte0_e32 v0, v17
	v_pk_mul_f32 v[74:75], v[18:19], v[74:75]
	v_rcp_f32_e32 v17, v131
	s_nop 0
	v_mul_f32_e32 v17, v16, v17
	v_rcp_f32_e32 v16, v130
	s_nop 0
	v_mul_f32_e32 v16, v15, v16
	v_pk_mul_f32 v[16:17], v[16:17], v[68:69]
	v_rcp_f32_e32 v15, v129
	s_nop 0
	v_mul_f32_e32 v15, v14, v15
	v_rcp_f32_e32 v14, v128
	s_nop 0
	v_mul_f32_e32 v14, v0, v14
	v_cvt_f32_ubyte0_e32 v0, v6
	v_pk_mul_f32 v[14:15], v[14:15], v[66:67]
	v_max_f32_e32 v66, 1.0, v0
	v_cvt_f32_ubyte1_e32 v0, v6
	v_max_f32_e32 v67, 1.0, v0
	v_cvt_f32_ubyte2_e32 v0, v6
	v_max_f32_e32 v68, 1.0, v0
	v_cvt_f32_ubyte3_e32 v0, v6
	v_max_f32_e32 v69, 1.0, v0
	v_cvt_f32_ubyte0_e32 v0, v2
	v_cvt_f32_ubyte1_e32 v6, v2
	v_cvt_f32_ubyte2_e32 v18, v2
	v_cvt_f32_ubyte3_e32 v2, v2
	v_rcp_f32_e32 v19, v69
	s_nop 0
	v_mul_f32_e32 v21, v2, v19
	v_rcp_f32_e32 v2, v68
	s_nop 0
	v_mul_f32_e32 v20, v18, v2
	v_pk_mul_f32 v[20:21], v[20:21], v[52:53]
	v_rcp_f32_e32 v2, v67
	s_nop 0
	v_mul_f32_e32 v19, v6, v2
	v_rcp_f32_e32 v2, v66
	s_nop 0
	v_mul_f32_e32 v18, v0, v2
	v_cvt_f32_ubyte0_e32 v0, v7
	v_max_f32_e32 v52, 1.0, v0
; DI void gemm_tile(const bf16_t* __restrict__ A, int lda, const bf16_t* __restrict__ Bt, int ldb, int bvalid, int K, f32x4 (&acc)[4][4], char* lds, bool preloaded = false) {
;     ...
;   auto compute = [&](int st) {
;     const char* base = lds + st * 32768;
;     bf16x8 af[2][4], bfr[2][4];
; #pragma unroll
;     for (int s = 0; s < 2; ++s) {
;       const int ch = ((4 * s + fq) ^ fx) << 4;
; #pragma unroll
;       for (int mi = 0; mi < 4; ++mi) af[s][mi] = *(const bf16x8*)(base + (wm * 64 + mi * 16 + fr) * 128 + ch);
; #pragma unroll
;       for (int ni = 0; ni < 4; ++ni) bfr[s][ni] = *(const bf16x8*)(base + 16384 + (wn * 64 + ni * 16 + fr) * 128 + ch);
; DI void phaseD_tile(const P& p, int layer, int mt, int nt, char* lds) {
;     ...
; #pragma unroll
;   for (int mi = 0; mi < 4; ++mi)
; #pragma unroll
;     for (int ni = 0; ni < 4; ++ni)
; #pragma unroll
;       for (int j = 0; j < 4; ++j) acc[mi][ni][j] *= (float)((gpv[mi][ni] >> (8 * j)) & 255u) / fmaxf((float)((gav[mi][ni] >> (8 * j)) & 255u), 1.f);
;   gemm_tile((const bf16_t*)(p.ws + W_ZA) + (size_t)row0 * 512, 512, (const bf16_t*)(p.ws + W_WAO) + ((size_t)layer * 1024 + col0) * 512, 512, 128, 512, acc, lds, true);
	v_cvt_f32_ubyte1_e32 v0, v7
	v_max_f32_e32 v53, 1.0, v0
	v_cvt_f32_ubyte2_e32 v0, v7
	v_max_f32_e32 v132, 1.0, v0
	v_cvt_f32_ubyte3_e32 v0, v7
	v_max_f32_e32 v133, 1.0, v0
	v_cvt_f32_ubyte0_e32 v0, v3
	v_cvt_f32_ubyte1_e32 v6, v3
	v_cvt_f32_ubyte2_e32 v2, v3
	v_cvt_f32_ubyte3_e32 v3, v3
	v_pk_mul_f32 v[18:19], v[18:19], v[50:51]
	v_rcp_f32_e32 v7, v133
	s_nop 0
	v_mul_f32_e32 v3, v3, v7
	v_rcp_f32_e32 v7, v132
	s_nop 0
	v_mul_f32_e32 v2, v2, v7
	v_pk_mul_f32 v[44:45], v[2:3], v[44:45]
	v_cvt_f32_ubyte3_e32 v3, v4
	v_cvt_f32_ubyte2_e32 v2, v4
	v_rcp_f32_e32 v7, v53
	s_nop 0
	v_mul_f32_e32 v7, v6, v7
	v_rcp_f32_e32 v6, v52
	s_nop 0
	v_mul_f32_e32 v6, v0, v6
	v_cvt_f32_ubyte0_e32 v0, v8
	v_max_f32_e32 v134, 1.0, v0
	v_cvt_f32_ubyte1_e32 v0, v8
	v_max_f32_e32 v135, 1.0, v0
	v_cvt_f32_ubyte2_e32 v0, v8
	v_max_f32_e32 v136, 1.0, v0
	v_cvt_f32_ubyte3_e32 v0, v8
	v_max_f32_e32 v137, 1.0, v0
	v_pk_mul_f32 v[42:43], v[6:7], v[42:43]
	v_cvt_f32_ubyte0_e32 v0, v4
	v_cvt_f32_ubyte1_e32 v6, v4
	v_rcp_f32_e32 v4, v137
	s_nop 0
	v_mul_f32_e32 v3, v3, v4
	v_rcp_f32_e32 v4, v136
	s_nop 0
	v_mul_f32_e32 v2, v2, v4
	v_pk_mul_f32 v[36:37], v[2:3], v[36:37]
	v_cvt_f32_ubyte1_e32 v2, v5
	v_cvt_f32_ubyte2_e32 v3, v5
	v_rcp_f32_e32 v4, v135
	s_nop 0
	v_mul_f32_e32 v7, v6, v4
	v_rcp_f32_e32 v4, v134
	s_nop 0
	v_mul_f32_e32 v6, v0, v4
	v_cvt_f32_ubyte0_e32 v0, v9
	v_max_f32_e32 v138, 1.0, v0
	v_cvt_f32_ubyte1_e32 v0, v9
	v_max_f32_e32 v139, 1.0, v0
	v_cvt_f32_ubyte2_e32 v0, v9
	v_max_f32_e32 v140, 1.0, v0
	v_cvt_f32_ubyte3_e32 v0, v9
	v_max_f32_e32 v141, 1.0, v0
	v_cvt_f32_ubyte3_e32 v4, v5
	v_cvt_f32_ubyte0_e32 v0, v5
	v_pk_mul_f32 v[34:35], v[6:7], v[34:35]
	v_rcp_f32_e32 v5, v141
	s_nop 0
	v_mul_f32_e32 v5, v4, v5
	v_rcp_f32_e32 v4, v140
	s_nop 0
	v_mul_f32_e32 v4, v3, v4
	v_pk_mul_f32 v[4:5], v[4:5], v[28:29]
	v_rcp_f32_e32 v3, v139
	s_nop 0
	v_mul_f32_e32 v3, v2, v3
	v_rcp_f32_e32 v2, v138
	s_nop 0
	v_mul_f32_e32 v2, v0, v2
	v_pk_mul_f32 v[2:3], v[2:3], v[26:27]
	v_mov_b32_e32 v26, v158
	s_waitcnt vmcnt(0) lgkmcnt(0)
	v_ashrrev_i32_e32 v8, 3, v26
	v_lshrrev_b32_e32 v0, 4, v26
	v_ashrrev_i32_e32 v9, 31, v8
	v_xor_b32_e32 v0, v0, v26
	v_lshlrev_b64 v[6:7], 10, v[8:9]
	v_lshlrev_b32_e32 v0, 4, v0
	v_readfirstlane_b32 s5, v26
	v_lshl_add_u64 v[6:7], s[10:11], 0, v[6:7]
	v_and_b32_e32 v0, 0x70, v0
	v_lshl_add_u64 v[6:7], v[6:7], 0, v[0:1]
	v_lshl_add_u64 v[50:51], s[8:9], 0, v[0:1]
	s_lshl_b32 s8, s5, 7
	v_lshlrev_b32_e32 v0, 7, v26
	s_lshl_b32 s5, s5, 6
	v_bfe_u32 v27, v26, 4, 2
	v_bfe_u32 v29, v26, 1, 3
	s_and_b32 s8, s8, 0x2000
	v_and_b32_e32 v0, 0x780, v0
	s_and_b32 s5, s5, 0xffffe000
	v_lshlrev_b32_e32 v156, 4, v26
	v_or_b32_e32 v157, s8, v0
	v_or_b32_e32 v179, s5, v0
	v_bitop3_b32 v0, v27, v29, 4 bitop3:0x36
	v_lshrrev_b32_e32 v28, 1, v26
	v_lshlrev_b32_e32 v220, 4, v0
	v_lshlrev_b32_e32 v0, 9, v8
	v_add_u32_e32 v143, 0x8000, v156
	v_bitop3_b32 v9, v28, v27, 7 bitop3:0x6c
	v_and_b32_e32 v26, 0xfe00, v0
	v_add_u32_e32 v8, 0x4000, v0
	v_bitop3_b32 v146, v0, s33, v167 bitop3:0x6c
	v_add_u32_e32 v0, 0xc000, v0
	v_readfirstlane_b32 s13, v143
	v_lshlrev_b32_e32 v145, 4, v9
	v_and_b32_e32 v28, 0xfe00, v8
	v_and_b32_e32 v148, 0xfe00, v0
	v_lshl_add_u64 v[8:9], v[6:7], 0, s[38:39]
	v_add_u32_e32 v142, 0xc000, v156
	s_mov_b32 m0, s13
	v_lshlrev_b32_e32 v0, 1, v26
	s_barrier
	global_load_lds_dwordx4 v[8:9], off
	v_lshl_add_u64 v[8:9], v[50:51], 0, v[0:1]
	v_readfirstlane_b32 s12, v142
	v_add_u32_e32 v144, 0x9000, v156
	v_lshl_add_u64 v[26:27], v[8:9], 0, s[38:39]
	s_mov_b32 m0, s12
	v_readfirstlane_b32 s21, v144
	global_load_lds_dwordx4 v[26:27], off
	v_lshl_add_u64 v[26:27], v[6:7], 0, s[58:59]
	s_mov_b32 m0, s21
	v_lshlrev_b32_e32 v0, 1, v28
	global_load_lds_dwordx4 v[26:27], off
	v_lshl_add_u64 v[26:27], v[50:51], 0, v[0:1]
	v_add_u32_e32 v0, 0xd000, v156
	v_lshl_add_u64 v[28:29], v[26:27], 0, s[38:39]
	v_readfirstlane_b32 s5, v0
	v_add_u32_e32 v0, 0xa000, v156
	s_mov_b32 m0, s5
	v_readfirstlane_b32 s8, v0
	global_load_lds_dwordx4 v[28:29], off
	v_lshl_add_u64 v[28:29], v[6:7], 0, s[62:63]
	s_mov_b32 m0, s8
	v_lshlrev_b32_e32 v0, 1, v146
	global_load_lds_dwordx4 v[28:29], off
	v_lshl_add_u64 v[28:29], v[50:51], 0, v[0:1]
	v_add_u32_e32 v0, 0xe000, v156
	v_lshl_add_u64 v[146:147], v[28:29], 0, s[38:39]
	v_readfirstlane_b32 s9, v0
	v_add_u32_e32 v0, 0xb000, v156
	s_mov_b32 m0, s9
	v_readfirstlane_b32 s10, v0
	v_lshlrev_b32_e32 v0, 1, v148
	v_lshl_add_u64 v[50:51], v[50:51], 0, v[0:1]
	v_add_u32_e32 v0, 0xf000, v156
	global_load_lds_dwordx4 v[146:147], off
	v_lshl_add_u64 v[146:147], v[6:7], 0, s[68:69]
	s_mov_b32 m0, s10
	v_readfirstlane_b32 s11, v0
	global_load_lds_dwordx4 v[146:147], off
	v_lshl_add_u64 v[146:147], v[50:51], 0, s[38:39]
	s_mov_b32 m0, s11
	v_or_b32_e32 v0, v145, v179
	global_load_lds_dwordx4 v[146:147], off
	v_or_b32_e32 v145, v145, v157
	v_or_b32_e32 v146, v220, v179
	v_or_b32_e32 v147, v220, v157
	ds_read_b128 v[148:151], v0
	ds_read_b128 v[152:155], v0 offset:2048
	ds_read_b128 v[180:183], v0 offset:4096
	ds_read_b128 v[184:187], v0 offset:6144
	ds_read_b128 v[188:191], v145 offset:16384
	ds_read_b128 v[192:195], v145 offset:18432
	ds_read_b128 v[196:199], v145 offset:20480
	ds_read_b128 v[200:203], v145 offset:22528
	ds_read_b128 v[204:207], v146
	ds_read_b128 v[208:211], v146 offset:2048
	ds_read_b128 v[212:215], v146 offset:4096
	ds_read_b128 v[216:219], v146 offset:6144
	ds_read_b128 v[220:223], v147 offset:16384
	ds_read_b128 v[224:227], v147 offset:18432
	ds_read_b128 v[228:231], v147 offset:20480
	ds_read_b128 v[232:235], v147 offset:22528
	s_setprio 1
	s_waitcnt lgkmcnt(8)
; #define MFMA16(a, b, c) __builtin_amdgcn_mfma_f32_16x16x32_bf16((a), (b), (c), 0, 0, 0)
; DI void gemm_tile(const bf16_t* __restrict__ A, int lda, const bf16_t* __restrict__ Bt, int ldb, int bvalid, int K, f32x4 (&acc)[4][4], char* lds, bool preloaded = false) {
;     ...
;   auto compute = [&](int st) {
;     const char* base = lds + st * 32768;
;     bf16x8 af[2][4], bfr[2][4];
; #pragma unroll
;     for (int s = 0; s < 2; ++s) {
;       const int ch = ((4 * s + fq) ^ fx) << 4;
; #pragma unroll
;       for (int mi = 0; mi < 4; ++mi) af[s][mi] = *(const bf16x8*)(base + (wm * 64 + mi * 16 + fr) * 128 + ch);
; #pragma unroll
;       for (int ni = 0; ni < 4; ++ni) bfr[s][ni] = *(const bf16x8*)(base + 16384 + (wn * 64 + ni * 16 + fr) * 128 + ch);
;     }
;     __builtin_amdgcn_s_setprio(1);
; #pragma unroll
;     for (int s = 0; s < 2; ++s)
; #pragma unroll
;       for (int mi = 0; mi < 4; ++mi)
; #pragma unroll
;         for (int ni = 0; ni < 4; ++ni) acc[mi][ni] = MFMA16(af[s][mi], bfr[s][ni], acc[mi][ni]);
;     __builtin_amdgcn_s_setprio(0);
;   };
;   const int nk = K >> 6;
;   if (!preloaded) { GLDS(0, 0) }
;   __syncthreads();
;   for (int kt = 0; kt < nk; ++kt) {
;     if (kt + 1 < nk) { GLDS((kt + 1) & 1, (kt + 1) << 6) }
;     compute(kt & 1);
;     __syncthreads();
;   }
; DI void phaseD_tile(const P& p, int layer, int mt, int nt, char* lds) {
;     ...
;   gemm_tile((const bf16_t*)(p.ws + W_ZA) + (size_t)row0 * 512, 512, (const bf16_t*)(p.ws + W_WAO) + ((size_t)layer * 1024 + col0) * 512, 512, 128, 512, acc, lds, true);
	v_mfma_f32_16x16x32_bf16 v[2:5], v[184:187], v[200:203], v[2:5]
	v_mfma_f32_16x16x32_bf16 v[10:13], v[148:151], v[188:191], v[10:13]
	v_mfma_f32_16x16x32_bf16 v[22:25], v[148:151], v[192:195], v[22:25]
	v_mfma_f32_16x16x32_bf16 v[30:33], v[148:151], v[196:199], v[30:33]
	v_mfma_f32_16x16x32_bf16 v[38:41], v[148:151], v[200:203], v[38:41]
	v_mfma_f32_16x16x32_bf16 v[46:49], v[152:155], v[188:191], v[46:49]
	v_mfma_f32_16x16x32_bf16 v[62:65], v[152:155], v[192:195], v[62:65]
	v_mfma_f32_16x16x32_bf16 v[70:73], v[152:155], v[196:199], v[70:73]
	v_mfma_f32_16x16x32_bf16 v[54:57], v[152:155], v[200:203], v[54:57]
	v_mfma_f32_16x16x32_bf16 v[58:61], v[180:183], v[188:191], v[58:61]
	v_mfma_f32_16x16x32_bf16 v[78:81], v[180:183], v[192:195], v[78:81]
	v_mfma_f32_16x16x32_bf16 v[74:77], v[180:183], v[196:199], v[74:77]
	v_mfma_f32_16x16x32_bf16 v[14:17], v[180:183], v[200:203], v[14:17]
	v_mfma_f32_16x16x32_bf16 v[18:21], v[184:187], v[188:191], v[18:21]
	v_mfma_f32_16x16x32_bf16 v[42:45], v[184:187], v[192:195], v[42:45]
	v_mfma_f32_16x16x32_bf16 v[34:37], v[184:187], v[196:199], v[34:37]
	s_waitcnt lgkmcnt(0)
	v_mfma_f32_16x16x32_bf16 v[2:5], v[216:219], v[232:235], v[2:5]
	v_mfma_f32_16x16x32_bf16 v[10:13], v[204:207], v[220:223], v[10:13]
	v_mfma_f32_16x16x32_bf16 v[22:25], v[204:207], v[224:227], v[22:25]
	v_mfma_f32_16x16x32_bf16 v[30:33], v[204:207], v[228:231], v[30:33]
	v_mfma_f32_16x16x32_bf16 v[38:41], v[204:207], v[232:235], v[38:41]
	v_mfma_f32_16x16x32_bf16 v[46:49], v[208:211], v[220:223], v[46:49]
	v_mfma_f32_16x16x32_bf16 v[62:65], v[208:211], v[224:227], v[62:65]
	v_mfma_f32_16x16x32_bf16 v[70:73], v[208:211], v[228:231], v[70:73]
	v_mfma_f32_16x16x32_bf16 v[54:57], v[208:211], v[232:235], v[54:57]
	v_mfma_f32_16x16x32_bf16 v[58:61], v[212:215], v[220:223], v[58:61]
	v_mfma_f32_16x16x32_bf16 v[78:81], v[212:215], v[224:227], v[78:81]
	v_mfma_f32_16x16x32_bf16 v[74:77], v[212:215], v[228:231], v[74:77]
	v_mfma_f32_16x16x32_bf16 v[14:17], v[212:215], v[232:235], v[14:17]
	v_mfma_f32_16x16x32_bf16 v[18:21], v[216:219], v[220:223], v[18:21]
	v_mfma_f32_16x16x32_bf16 v[42:45], v[216:219], v[224:227], v[42:45]
	v_mfma_f32_16x16x32_bf16 v[34:37], v[216:219], v[228:231], v[34:37]
	s_setprio 0
	v_add_u32_e32 v150, 0x4000, v156
	v_readfirstlane_b32 s25, v156
	v_lshl_add_u64 v[148:149], v[6:7], 0, s[30:31]
	s_mov_b32 m0, s25
	v_readfirstlane_b32 s22, v150
	v_add_u32_e32 v150, 0x1000, v156
	s_waitcnt vmcnt(0)
	s_barrier
	global_load_lds_dwordx4 v[148:149], off
	v_lshl_add_u64 v[148:149], v[8:9], 0, s[30:31]
	s_mov_b32 m0, s22
	v_readfirstlane_b32 s23, v150
	v_add_u32_e32 v150, 0x5000, v156
	global_load_lds_dwordx4 v[148:149], off
	v_lshl_add_u64 v[148:149], v[6:7], 0, s[70:71]
	s_mov_b32 m0, s23
	v_readfirstlane_b32 s24, v150
	v_add_u32_e32 v150, 0x2000, v156
	global_load_lds_dwordx4 v[148:149], off
	v_lshl_add_u64 v[148:149], v[26:27], 0, s[30:31]
	s_mov_b32 m0, s24
	v_readfirstlane_b32 s26, v150
	v_add_u32_e32 v150, 0x6000, v156
	global_load_lds_dwordx4 v[148:149], off
	v_lshl_add_u64 v[148:149], v[6:7], 0, s[92:93]
	s_mov_b32 m0, s26
	v_readfirstlane_b32 s27, v150
	global_load_lds_dwordx4 v[148:149], off
	v_lshl_add_u64 v[148:149], v[28:29], 0, s[30:31]
	s_mov_b32 m0, s27
	s_mov_b64 s[28:29], 0x18100
	v_add_u32_e32 v150, 0x3000, v156
	global_load_lds_dwordx4 v[148:149], off
	v_lshl_add_u64 v[148:149], v[6:7], 0, s[28:29]
	v_readfirstlane_b32 s28, v150
	v_add_u32_e32 v150, 0x7000, v156
	s_mov_b32 m0, s28
	v_readfirstlane_b32 s29, v150
	global_load_lds_dwordx4 v[148:149], off
	v_lshl_add_u64 v[148:149], v[50:51], 0, s[30:31]
	s_mov_b32 m0, s29
	s_nop 0
	global_load_lds_dwordx4 v[148:149], off
	ds_read_b128 v[148:151], v0 offset:32768
	ds_read_b128 v[152:155], v0 offset:34816
	ds_read_b128 v[180:183], v0 offset:36864
	ds_read_b128 v[184:187], v0 offset:38912
	ds_read_b128 v[188:191], v145 offset:49152
	ds_read_b128 v[192:195], v145 offset:51200
	ds_read_b128 v[196:199], v145 offset:53248
	ds_read_b128 v[200:203], v145 offset:55296
	ds_read_b128 v[204:207], v146 offset:32768
	ds_read_b128 v[208:211], v146 offset:34816
	ds_read_b128 v[212:215], v146 offset:36864
	ds_read_b128 v[216:219], v146 offset:38912
	ds_read_b128 v[220:223], v147 offset:49152
	ds_read_b128 v[224:227], v147 offset:51200
	ds_read_b128 v[228:231], v147 offset:53248
	ds_read_b128 v[232:235], v147 offset:55296
	s_setprio 1
	s_waitcnt lgkmcnt(8)
	v_mfma_f32_16x16x32_bf16 v[2:5], v[184:187], v[200:203], v[2:5]
	v_mfma_f32_16x16x32_bf16 v[10:13], v[148:151], v[188:191], v[10:13]
	v_mfma_f32_16x16x32_bf16 v[22:25], v[148:151], v[192:195], v[22:25]
	v_mfma_f32_16x16x32_bf16 v[30:33], v[148:151], v[196:199], v[30:33]
	v_mfma_f32_16x16x32_bf16 v[38:41], v[148:151], v[200:203], v[38:41]
	v_mfma_f32_16x16x32_bf16 v[46:49], v[152:155], v[188:191], v[46:49]
	v_mfma_f32_16x16x32_bf16 v[62:65], v[152:155], v[192:195], v[62:65]
	v_mfma_f32_16x16x32_bf16 v[70:73], v[152:155], v[196:199], v[70:73]
	v_mfma_f32_16x16x32_bf16 v[54:57], v[152:155], v[200:203], v[54:57]
	v_mfma_f32_16x16x32_bf16 v[58:61], v[180:183], v[188:191], v[58:61]
	v_mfma_f32_16x16x32_bf16 v[78:81], v[180:183], v[192:195], v[78:81]
	v_mfma_f32_16x16x32_bf16 v[74:77], v[180:183], v[196:199], v[74:77]
	v_mfma_f32_16x16x32_bf16 v[14:17], v[180:183], v[200:203], v[14:17]
	v_mfma_f32_16x16x32_bf16 v[18:21], v[184:187], v[188:191], v[18:21]
	v_mfma_f32_16x16x32_bf16 v[42:45], v[184:187], v[192:195], v[42:45]
	v_mfma_f32_16x16x32_bf16 v[34:37], v[184:187], v[196:199], v[34:37]
	s_waitcnt lgkmcnt(0)
	v_mfma_f32_16x16x32_bf16 v[2:5], v[216:219], v[232:235], v[2:5]
	v_mfma_f32_16x16x32_bf16 v[10:13], v[204:207], v[220:223], v[10:13]
	v_mfma_f32_16x16x32_bf16 v[22:25], v[204:207], v[224:227], v[22:25]
	v_mfma_f32_16x16x32_bf16 v[30:33], v[204:207], v[228:231], v[30:33]
	v_mfma_f32_16x16x32_bf16 v[38:41], v[204:207], v[232:235], v[38:41]
	v_mfma_f32_16x16x32_bf16 v[46:49], v[208:211], v[220:223], v[46:49]
	v_mfma_f32_16x16x32_bf16 v[62:65], v[208:211], v[224:227], v[62:65]
	v_mfma_f32_16x16x32_bf16 v[70:73], v[208:211], v[228:231], v[70:73]
	v_mfma_f32_16x16x32_bf16 v[54:57], v[208:211], v[232:235], v[54:57]
	v_mfma_f32_16x16x32_bf16 v[58:61], v[212:215], v[220:223], v[58:61]
	v_mfma_f32_16x16x32_bf16 v[78:81], v[212:215], v[224:227], v[78:81]
	v_mfma_f32_16x16x32_bf16 v[74:77], v[212:215], v[228:231], v[74:77]
	v_mfma_f32_16x16x32_bf16 v[14:17], v[212:215], v[232:235], v[14:17]
	v_mfma_f32_16x16x32_bf16 v[18:21], v[216:219], v[220:223], v[18:21]
	v_mfma_f32_16x16x32_bf16 v[42:45], v[216:219], v[224:227], v[42:45]
	v_mfma_f32_16x16x32_bf16 v[34:37], v[216:219], v[228:231], v[34:37]
	s_setprio 0
	s_mov_b32 m0, s13
	v_lshl_add_u64 v[148:149], v[6:7], 0, s[0:1]
	s_waitcnt vmcnt(0)
	s_barrier
; #define MFMA16(a, b, c) __builtin_amdgcn_mfma_f32_16x16x32_bf16((a), (b), (c), 0, 0, 0)
; DI void gemm_tile(const bf16_t* __restrict__ A, int lda, const bf16_t* __restrict__ Bt, int ldb, int bvalid, int K, f32x4 (&acc)[4][4], char* lds, bool preloaded = false) {
;     ...
;   auto compute = [&](int st) {
;     const char* base = lds + st * 32768;
;     bf16x8 af[2][4], bfr[2][4];
; #pragma unroll
;     for (int s = 0; s < 2; ++s) {
;       const int ch = ((4 * s + fq) ^ fx) << 4;
; #pragma unroll
;       for (int mi = 0; mi < 4; ++mi) af[s][mi] = *(const bf16x8*)(base + (wm * 64 + mi * 16 + fr) * 128 + ch);
; #pragma unroll
;       for (int ni = 0; ni < 4; ++ni) bfr[s][ni] = *(const bf16x8*)(base + 16384 + (wn * 64 + ni * 16 + fr) * 128 + ch);
;     }
;     __builtin_amdgcn_s_setprio(1);
; #pragma unroll
;     for (int s = 0; s < 2; ++s)
; #pragma unroll
;       for (int mi = 0; mi < 4; ++mi)
; #pragma unroll
;         for (int ni = 0; ni < 4; ++ni) acc[mi][ni] = MFMA16(af[s][mi], bfr[s][ni], acc[mi][ni]);
;     __builtin_amdgcn_s_setprio(0);
;   };
;   const int nk = K >> 6;
;   if (!preloaded) { GLDS(0, 0) }
;   __syncthreads();
;   for (int kt = 0; kt < nk; ++kt) {
;     if (kt + 1 < nk) { GLDS((kt + 1) & 1, (kt + 1) << 6) }
;     compute(kt & 1);
;     __syncthreads();
;   }
; DI void phaseD_tile(const P& p, int layer, int mt, int nt, char* lds) {
;     ...
;   gemm_tile((const bf16_t*)(p.ws + W_ZA) + (size_t)row0 * 512, 512, (const bf16_t*)(p.ws + W_WAO) + ((size_t)layer * 1024 + col0) * 512, 512, 128, 512, acc, lds, true);
	global_load_lds_dwordx4 v[148:149], off
	v_lshl_add_u64 v[148:149], v[8:9], 0, s[0:1]
	s_mov_b32 m0, s12
	s_mov_b64 s[30:31], 0x8180
	global_load_lds_dwordx4 v[148:149], off
	v_lshl_add_u64 v[148:149], v[6:7], 0, s[30:31]
	s_mov_b32 m0, s21
	s_mov_b64 s[30:31], 0x10180
	global_load_lds_dwordx4 v[148:149], off
	v_lshl_add_u64 v[148:149], v[26:27], 0, s[0:1]
	s_mov_b32 m0, s5
	s_nop 0
	global_load_lds_dwordx4 v[148:149], off
	v_lshl_add_u64 v[148:149], v[6:7], 0, s[30:31]
	s_mov_b32 m0, s8
	s_mov_b64 s[30:31], 0x18180
	global_load_lds_dwordx4 v[148:149], off
	v_lshl_add_u64 v[148:149], v[28:29], 0, s[0:1]
	s_mov_b32 m0, s9
	s_nop 0
	global_load_lds_dwordx4 v[148:149], off
	v_lshl_add_u64 v[148:149], v[6:7], 0, s[30:31]
	s_mov_b32 m0, s10
	s_nop 0
	global_load_lds_dwordx4 v[148:149], off
	v_lshl_add_u64 v[148:149], v[50:51], 0, s[0:1]
	s_mov_b32 m0, s11
	s_nop 0
	global_load_lds_dwordx4 v[148:149], off
	ds_read_b128 v[148:151], v0
	ds_read_b128 v[152:155], v0 offset:2048
	ds_read_b128 v[180:183], v0 offset:4096
	ds_read_b128 v[184:187], v0 offset:6144
	ds_read_b128 v[188:191], v145 offset:16384
	ds_read_b128 v[192:195], v145 offset:18432
	ds_read_b128 v[196:199], v145 offset:20480
	ds_read_b128 v[200:203], v145 offset:22528
	ds_read_b128 v[204:207], v146
	ds_read_b128 v[208:211], v146 offset:2048
	ds_read_b128 v[212:215], v146 offset:4096
	ds_read_b128 v[216:219], v146 offset:6144
	ds_read_b128 v[220:223], v147 offset:16384
	ds_read_b128 v[224:227], v147 offset:18432
	ds_read_b128 v[228:231], v147 offset:20480
	ds_read_b128 v[232:235], v147 offset:22528
	s_setprio 1
	s_waitcnt lgkmcnt(8)
	v_mfma_f32_16x16x32_bf16 v[2:5], v[184:187], v[200:203], v[2:5]
	v_mfma_f32_16x16x32_bf16 v[10:13], v[148:151], v[188:191], v[10:13]
	v_mfma_f32_16x16x32_bf16 v[22:25], v[148:151], v[192:195], v[22:25]
	v_mfma_f32_16x16x32_bf16 v[30:33], v[148:151], v[196:199], v[30:33]
	v_mfma_f32_16x16x32_bf16 v[38:41], v[148:151], v[200:203], v[38:41]
	v_mfma_f32_16x16x32_bf16 v[46:49], v[152:155], v[188:191], v[46:49]
	v_mfma_f32_16x16x32_bf16 v[62:65], v[152:155], v[192:195], v[62:65]
	v_mfma_f32_16x16x32_bf16 v[70:73], v[152:155], v[196:199], v[70:73]
	v_mfma_f32_16x16x32_bf16 v[54:57], v[152:155], v[200:203], v[54:57]
	v_mfma_f32_16x16x32_bf16 v[58:61], v[180:183], v[188:191], v[58:61]
	v_mfma_f32_16x16x32_bf16 v[78:81], v[180:183], v[192:195], v[78:81]
	v_mfma_f32_16x16x32_bf16 v[74:77], v[180:183], v[196:199], v[74:77]
	v_mfma_f32_16x16x32_bf16 v[14:17], v[180:183], v[200:203], v[14:17]
	v_mfma_f32_16x16x32_bf16 v[18:21], v[184:187], v[188:191], v[18:21]
	v_mfma_f32_16x16x32_bf16 v[42:45], v[184:187], v[192:195], v[42:45]
	v_mfma_f32_16x16x32_bf16 v[34:37], v[184:187], v[196:199], v[34:37]
	s_waitcnt lgkmcnt(0)
	v_mfma_f32_16x16x32_bf16 v[2:5], v[216:219], v[232:235], v[2:5]
	v_mfma_f32_16x16x32_bf16 v[10:13], v[204:207], v[220:223], v[10:13]
	v_mfma_f32_16x16x32_bf16 v[22:25], v[204:207], v[224:227], v[22:25]
	v_mfma_f32_16x16x32_bf16 v[30:33], v[204:207], v[228:231], v[30:33]
	v_mfma_f32_16x16x32_bf16 v[38:41], v[204:207], v[232:235], v[38:41]
	v_mfma_f32_16x16x32_bf16 v[46:49], v[208:211], v[220:223], v[46:49]
	v_mfma_f32_16x16x32_bf16 v[62:65], v[208:211], v[224:227], v[62:65]
	v_mfma_f32_16x16x32_bf16 v[70:73], v[208:211], v[228:231], v[70:73]
	v_mfma_f32_16x16x32_bf16 v[54:57], v[208:211], v[232:235], v[54:57]
	v_mfma_f32_16x16x32_bf16 v[58:61], v[212:215], v[220:223], v[58:61]
	v_mfma_f32_16x16x32_bf16 v[78:81], v[212:215], v[224:227], v[78:81]
	v_mfma_f32_16x16x32_bf16 v[74:77], v[212:215], v[228:231], v[74:77]
	v_mfma_f32_16x16x32_bf16 v[14:17], v[212:215], v[232:235], v[14:17]
	v_mfma_f32_16x16x32_bf16 v[18:21], v[216:219], v[220:223], v[18:21]
	v_mfma_f32_16x16x32_bf16 v[42:45], v[216:219], v[224:227], v[42:45]
	v_mfma_f32_16x16x32_bf16 v[34:37], v[216:219], v[228:231], v[34:37]
	s_setprio 0
	s_mov_b32 m0, s25
	v_lshl_add_u64 v[148:149], v[6:7], 0, s[36:37]
	s_waitcnt vmcnt(0)
	s_barrier
	global_load_lds_dwordx4 v[148:149], off
	v_lshl_add_u64 v[148:149], v[8:9], 0, s[36:37]
	s_mov_b32 m0, s22
	s_mov_b64 s[0:1], 0x8200
	global_load_lds_dwordx4 v[148:149], off
	v_lshl_add_u64 v[148:149], v[6:7], 0, s[0:1]
	s_mov_b32 m0, s23
	s_mov_b64 s[0:1], 0x10200
	global_load_lds_dwordx4 v[148:149], off
	v_lshl_add_u64 v[148:149], v[26:27], 0, s[36:37]
	s_mov_b32 m0, s24
	s_nop 0
	global_load_lds_dwordx4 v[148:149], off
	v_lshl_add_u64 v[148:149], v[6:7], 0, s[0:1]
	s_mov_b32 m0, s26
	s_mov_b64 s[0:1], 0x18200
	global_load_lds_dwordx4 v[148:149], off
	v_lshl_add_u64 v[148:149], v[28:29], 0, s[36:37]
	s_mov_b32 m0, s27
	s_nop 0
	global_load_lds_dwordx4 v[148:149], off
	v_lshl_add_u64 v[148:149], v[6:7], 0, s[0:1]
	s_mov_b32 m0, s28
	s_nop 0
	global_load_lds_dwordx4 v[148:149], off
	v_lshl_add_u64 v[148:149], v[50:51], 0, s[36:37]
	s_mov_b32 m0, s29
	s_nop 0
	global_load_lds_dwordx4 v[148:149], off
	ds_read_b128 v[148:151], v0 offset:32768
	ds_read_b128 v[152:155], v0 offset:34816
	ds_read_b128 v[180:183], v0 offset:36864
	ds_read_b128 v[184:187], v0 offset:38912
	ds_read_b128 v[188:191], v145 offset:49152
	ds_read_b128 v[192:195], v145 offset:51200
	ds_read_b128 v[196:199], v145 offset:53248
	ds_read_b128 v[200:203], v145 offset:55296
	ds_read_b128 v[204:207], v146 offset:32768
	ds_read_b128 v[208:211], v146 offset:34816
	ds_read_b128 v[212:215], v146 offset:36864
	ds_read_b128 v[216:219], v146 offset:38912
	ds_read_b128 v[220:223], v147 offset:49152
	ds_read_b128 v[224:227], v147 offset:51200
	ds_read_b128 v[228:231], v147 offset:53248
	ds_read_b128 v[232:235], v147 offset:55296
	s_setprio 1
	s_waitcnt lgkmcnt(8)
; #define MFMA16(a, b, c) __builtin_amdgcn_mfma_f32_16x16x32_bf16((a), (b), (c), 0, 0, 0)
; DI void gemm_tile(const bf16_t* __restrict__ A, int lda, const bf16_t* __restrict__ Bt, int ldb, int bvalid, int K, f32x4 (&acc)[4][4], char* lds, bool preloaded = false) {
;     ...
;   auto compute = [&](int st) {
;     const char* base = lds + st * 32768;
;     bf16x8 af[2][4], bfr[2][4];
; #pragma unroll
;     for (int s = 0; s < 2; ++s) {
;       const int ch = ((4 * s + fq) ^ fx) << 4;
; #pragma unroll
;       for (int mi = 0; mi < 4; ++mi) af[s][mi] = *(const bf16x8*)(base + (wm * 64 + mi * 16 + fr) * 128 + ch);
; #pragma unroll
;       for (int ni = 0; ni < 4; ++ni) bfr[s][ni] = *(const bf16x8*)(base + 16384 + (wn * 64 + ni * 16 + fr) * 128 + ch);
;     }
;     __builtin_amdgcn_s_setprio(1);
; #pragma unroll
;     for (int s = 0; s < 2; ++s)
; #pragma unroll
;       for (int mi = 0; mi < 4; ++mi)
; #pragma unroll
;         for (int ni = 0; ni < 4; ++ni) acc[mi][ni] = MFMA16(af[s][mi], bfr[s][ni], acc[mi][ni]);
;     __builtin_amdgcn_s_setprio(0);
;   };
;   const int nk = K >> 6;
;   if (!preloaded) { GLDS(0, 0) }
;   __syncthreads();
;   for (int kt = 0; kt < nk; ++kt) {
;     if (kt + 1 < nk) { GLDS((kt + 1) & 1, (kt + 1) << 6) }
;     compute(kt & 1);
;     __syncthreads();
;   }
; DI void phaseD_tile(const P& p, int layer, int mt, int nt, char* lds) {
;     ...
;   gemm_tile((const bf16_t*)(p.ws + W_ZA) + (size_t)row0 * 512, 512, (const bf16_t*)(p.ws + W_WAO) + ((size_t)layer * 1024 + col0) * 512, 512, 128, 512, acc, lds, true);
	v_mfma_f32_16x16x32_bf16 v[2:5], v[184:187], v[200:203], v[2:5]
	v_mfma_f32_16x16x32_bf16 v[10:13], v[148:151], v[188:191], v[10:13]
	v_mfma_f32_16x16x32_bf16 v[22:25], v[148:151], v[192:195], v[22:25]
	v_mfma_f32_16x16x32_bf16 v[30:33], v[148:151], v[196:199], v[30:33]
	v_mfma_f32_16x16x32_bf16 v[38:41], v[148:151], v[200:203], v[38:41]
	v_mfma_f32_16x16x32_bf16 v[46:49], v[152:155], v[188:191], v[46:49]
	v_mfma_f32_16x16x32_bf16 v[62:65], v[152:155], v[192:195], v[62:65]
	v_mfma_f32_16x16x32_bf16 v[70:73], v[152:155], v[196:199], v[70:73]
	v_mfma_f32_16x16x32_bf16 v[54:57], v[152:155], v[200:203], v[54:57]
	v_mfma_f32_16x16x32_bf16 v[58:61], v[180:183], v[188:191], v[58:61]
	v_mfma_f32_16x16x32_bf16 v[78:81], v[180:183], v[192:195], v[78:81]
	v_mfma_f32_16x16x32_bf16 v[74:77], v[180:183], v[196:199], v[74:77]
	v_mfma_f32_16x16x32_bf16 v[14:17], v[180:183], v[200:203], v[14:17]
	v_mfma_f32_16x16x32_bf16 v[18:21], v[184:187], v[188:191], v[18:21]
	v_mfma_f32_16x16x32_bf16 v[42:45], v[184:187], v[192:195], v[42:45]
	v_mfma_f32_16x16x32_bf16 v[34:37], v[184:187], v[196:199], v[34:37]
	s_waitcnt lgkmcnt(0)
	v_mfma_f32_16x16x32_bf16 v[2:5], v[216:219], v[232:235], v[2:5]
	v_mfma_f32_16x16x32_bf16 v[10:13], v[204:207], v[220:223], v[10:13]
	v_mfma_f32_16x16x32_bf16 v[22:25], v[204:207], v[224:227], v[22:25]
	v_mfma_f32_16x16x32_bf16 v[30:33], v[204:207], v[228:231], v[30:33]
	v_mfma_f32_16x16x32_bf16 v[38:41], v[204:207], v[232:235], v[38:41]
	v_mfma_f32_16x16x32_bf16 v[46:49], v[208:211], v[220:223], v[46:49]
	v_mfma_f32_16x16x32_bf16 v[62:65], v[208:211], v[224:227], v[62:65]
	v_mfma_f32_16x16x32_bf16 v[70:73], v[208:211], v[228:231], v[70:73]
	v_mfma_f32_16x16x32_bf16 v[54:57], v[208:211], v[232:235], v[54:57]
	v_mfma_f32_16x16x32_bf16 v[58:61], v[212:215], v[220:223], v[58:61]
	v_mfma_f32_16x16x32_bf16 v[78:81], v[212:215], v[224:227], v[78:81]
	v_mfma_f32_16x16x32_bf16 v[74:77], v[212:215], v[228:231], v[74:77]
	v_mfma_f32_16x16x32_bf16 v[14:17], v[212:215], v[232:235], v[14:17]
	v_mfma_f32_16x16x32_bf16 v[18:21], v[216:219], v[220:223], v[18:21]
	v_mfma_f32_16x16x32_bf16 v[42:45], v[216:219], v[224:227], v[42:45]
	v_mfma_f32_16x16x32_bf16 v[34:37], v[216:219], v[228:231], v[34:37]
	s_setprio 0
	s_mov_b32 m0, s13
	v_lshl_add_u64 v[148:149], v[6:7], 0, s[2:3]
	s_waitcnt vmcnt(0)
	s_barrier
	global_load_lds_dwordx4 v[148:149], off
	v_lshl_add_u64 v[148:149], v[8:9], 0, s[2:3]
	s_mov_b32 m0, s12
	s_mov_b64 s[0:1], 0x8280
	global_load_lds_dwordx4 v[148:149], off
	v_lshl_add_u64 v[148:149], v[6:7], 0, s[0:1]
	s_mov_b32 m0, s21
	s_mov_b64 s[0:1], 0x10280
	global_load_lds_dwordx4 v[148:149], off
	v_lshl_add_u64 v[148:149], v[26:27], 0, s[2:3]
	s_mov_b32 m0, s5
	s_nop 0
	global_load_lds_dwordx4 v[148:149], off
	v_lshl_add_u64 v[148:149], v[6:7], 0, s[0:1]
	s_mov_b32 m0, s8
	s_mov_b64 s[0:1], 0x18280
	global_load_lds_dwordx4 v[148:149], off
	v_lshl_add_u64 v[148:149], v[28:29], 0, s[2:3]
	s_mov_b32 m0, s9
	s_nop 0
	global_load_lds_dwordx4 v[148:149], off
	v_lshl_add_u64 v[148:149], v[6:7], 0, s[0:1]
	s_mov_b32 m0, s10
	s_nop 0
	global_load_lds_dwordx4 v[148:149], off
	v_lshl_add_u64 v[148:149], v[50:51], 0, s[2:3]
	s_mov_b32 m0, s11
	s_nop 0
	global_load_lds_dwordx4 v[148:149], off
	ds_read_b128 v[148:151], v0
	ds_read_b128 v[152:155], v0 offset:2048
	ds_read_b128 v[180:183], v0 offset:4096
	ds_read_b128 v[184:187], v0 offset:6144
	ds_read_b128 v[188:191], v145 offset:16384
	ds_read_b128 v[192:195], v145 offset:18432
	ds_read_b128 v[196:199], v145 offset:20480
	ds_read_b128 v[200:203], v145 offset:22528
	ds_read_b128 v[204:207], v146
	ds_read_b128 v[208:211], v146 offset:2048
	ds_read_b128 v[212:215], v146 offset:4096
	ds_read_b128 v[216:219], v146 offset:6144
	ds_read_b128 v[220:223], v147 offset:16384
	ds_read_b128 v[224:227], v147 offset:18432
	ds_read_b128 v[228:231], v147 offset:20480
	ds_read_b128 v[232:235], v147 offset:22528
	s_setprio 1
	s_waitcnt lgkmcnt(8)
	v_mfma_f32_16x16x32_bf16 v[2:5], v[184:187], v[200:203], v[2:5]
	v_mfma_f32_16x16x32_bf16 v[10:13], v[148:151], v[188:191], v[10:13]
	v_mfma_f32_16x16x32_bf16 v[22:25], v[148:151], v[192:195], v[22:25]
	v_mfma_f32_16x16x32_bf16 v[30:33], v[148:151], v[196:199], v[30:33]
	v_mfma_f32_16x16x32_bf16 v[38:41], v[148:151], v[200:203], v[38:41]
	v_mfma_f32_16x16x32_bf16 v[46:49], v[152:155], v[188:191], v[46:49]
	v_mfma_f32_16x16x32_bf16 v[62:65], v[152:155], v[192:195], v[62:65]
	v_mfma_f32_16x16x32_bf16 v[70:73], v[152:155], v[196:199], v[70:73]
	v_mfma_f32_16x16x32_bf16 v[54:57], v[152:155], v[200:203], v[54:57]
	v_mfma_f32_16x16x32_bf16 v[58:61], v[180:183], v[188:191], v[58:61]
	v_mfma_f32_16x16x32_bf16 v[78:81], v[180:183], v[192:195], v[78:81]
	v_mfma_f32_16x16x32_bf16 v[74:77], v[180:183], v[196:199], v[74:77]
	v_mfma_f32_16x16x32_bf16 v[14:17], v[180:183], v[200:203], v[14:17]
	v_mfma_f32_16x16x32_bf16 v[18:21], v[184:187], v[188:191], v[18:21]
	v_mfma_f32_16x16x32_bf16 v[42:45], v[184:187], v[192:195], v[42:45]
	v_mfma_f32_16x16x32_bf16 v[34:37], v[184:187], v[196:199], v[34:37]
	s_waitcnt lgkmcnt(0)
	v_mfma_f32_16x16x32_bf16 v[2:5], v[216:219], v[232:235], v[2:5]
	v_mfma_f32_16x16x32_bf16 v[10:13], v[204:207], v[220:223], v[10:13]
	v_mfma_f32_16x16x32_bf16 v[22:25], v[204:207], v[224:227], v[22:25]
	v_mfma_f32_16x16x32_bf16 v[30:33], v[204:207], v[228:231], v[30:33]
	v_mfma_f32_16x16x32_bf16 v[38:41], v[204:207], v[232:235], v[38:41]
	v_mfma_f32_16x16x32_bf16 v[46:49], v[208:211], v[220:223], v[46:49]
	v_mfma_f32_16x16x32_bf16 v[62:65], v[208:211], v[224:227], v[62:65]
	v_mfma_f32_16x16x32_bf16 v[70:73], v[208:211], v[228:231], v[70:73]
	v_mfma_f32_16x16x32_bf16 v[54:57], v[208:211], v[232:235], v[54:57]
	v_mfma_f32_16x16x32_bf16 v[58:61], v[212:215], v[220:223], v[58:61]
	v_mfma_f32_16x16x32_bf16 v[78:81], v[212:215], v[224:227], v[78:81]
	v_mfma_f32_16x16x32_bf16 v[74:77], v[212:215], v[228:231], v[74:77]
	v_mfma_f32_16x16x32_bf16 v[14:17], v[212:215], v[232:235], v[14:17]
	v_mfma_f32_16x16x32_bf16 v[18:21], v[216:219], v[220:223], v[18:21]
	v_mfma_f32_16x16x32_bf16 v[42:45], v[216:219], v[224:227], v[42:45]
	v_mfma_f32_16x16x32_bf16 v[34:37], v[216:219], v[228:231], v[34:37]
	s_setprio 0
	s_mov_b32 m0, s25
	v_lshl_add_u64 v[148:149], v[6:7], 0, s[14:15]
	s_waitcnt vmcnt(0)
	s_barrier
; #define MFMA16(a, b, c) __builtin_amdgcn_mfma_f32_16x16x32_bf16((a), (b), (c), 0, 0, 0)
; DI void gemm_tile(const bf16_t* __restrict__ A, int lda, const bf16_t* __restrict__ Bt, int ldb, int bvalid, int K, f32x4 (&acc)[4][4], char* lds, bool preloaded = false) {
;     ...
;   auto compute = [&](int st) {
;     const char* base = lds + st * 32768;
;     bf16x8 af[2][4], bfr[2][4];
; #pragma unroll
;     for (int s = 0; s < 2; ++s) {
;       const int ch = ((4 * s + fq) ^ fx) << 4;
; #pragma unroll
;       for (int mi = 0; mi < 4; ++mi) af[s][mi] = *(const bf16x8*)(base + (wm * 64 + mi * 16 + fr) * 128 + ch);
; #pragma unroll
;       for (int ni = 0; ni < 4; ++ni) bfr[s][ni] = *(const bf16x8*)(base + 16384 + (wn * 64 + ni * 16 + fr) * 128 + ch);
;     }
;     __builtin_amdgcn_s_setprio(1);
; #pragma unroll
;     for (int s = 0; s < 2; ++s)
; #pragma unroll
;       for (int mi = 0; mi < 4; ++mi)
; #pragma unroll
;         for (int ni = 0; ni < 4; ++ni) acc[mi][ni] = MFMA16(af[s][mi], bfr[s][ni], acc[mi][ni]);
;     __builtin_amdgcn_s_setprio(0);
;   };
;   const int nk = K >> 6;
;   if (!preloaded) { GLDS(0, 0) }
;   __syncthreads();
;   for (int kt = 0; kt < nk; ++kt) {
;     if (kt + 1 < nk) { GLDS((kt + 1) & 1, (kt + 1) << 6) }
;     compute(kt & 1);
;     __syncthreads();
;   }
; DI void phaseD_tile(const P& p, int layer, int mt, int nt, char* lds) {
;     ...
;   gemm_tile((const bf16_t*)(p.ws + W_ZA) + (size_t)row0 * 512, 512, (const bf16_t*)(p.ws + W_WAO) + ((size_t)layer * 1024 + col0) * 512, 512, 128, 512, acc, lds, true);
	global_load_lds_dwordx4 v[148:149], off
	v_lshl_add_u64 v[148:149], v[8:9], 0, s[14:15]
	s_mov_b32 m0, s22
	s_mov_b64 s[0:1], 0x8300
	global_load_lds_dwordx4 v[148:149], off
	v_lshl_add_u64 v[148:149], v[6:7], 0, s[0:1]
	s_mov_b32 m0, s23
	s_mov_b64 s[0:1], 0x10300
	global_load_lds_dwordx4 v[148:149], off
	v_lshl_add_u64 v[148:149], v[26:27], 0, s[14:15]
	s_mov_b32 m0, s24
	s_nop 0
	global_load_lds_dwordx4 v[148:149], off
	v_lshl_add_u64 v[148:149], v[6:7], 0, s[0:1]
	s_mov_b32 m0, s26
	s_mov_b64 s[0:1], 0x18300
	global_load_lds_dwordx4 v[148:149], off
	v_lshl_add_u64 v[148:149], v[28:29], 0, s[14:15]
	s_mov_b32 m0, s27
	s_nop 0
	global_load_lds_dwordx4 v[148:149], off
	v_lshl_add_u64 v[148:149], v[6:7], 0, s[0:1]
	s_mov_b32 m0, s28
	s_nop 0
	global_load_lds_dwordx4 v[148:149], off
	v_lshl_add_u64 v[148:149], v[50:51], 0, s[14:15]
	s_mov_b32 m0, s29
	s_nop 0
	global_load_lds_dwordx4 v[148:149], off
	ds_read_b128 v[148:151], v0 offset:32768
	ds_read_b128 v[152:155], v0 offset:34816
	ds_read_b128 v[180:183], v0 offset:36864
	ds_read_b128 v[184:187], v0 offset:38912
	ds_read_b128 v[188:191], v145 offset:49152
	ds_read_b128 v[192:195], v145 offset:51200
	ds_read_b128 v[196:199], v145 offset:53248
	ds_read_b128 v[200:203], v145 offset:55296
	ds_read_b128 v[204:207], v146 offset:32768
	ds_read_b128 v[208:211], v146 offset:34816
	ds_read_b128 v[212:215], v146 offset:36864
	ds_read_b128 v[216:219], v146 offset:38912
	ds_read_b128 v[220:223], v147 offset:49152
	ds_read_b128 v[224:227], v147 offset:51200
	ds_read_b128 v[228:231], v147 offset:53248
	ds_read_b128 v[232:235], v147 offset:55296
	s_setprio 1
	s_waitcnt lgkmcnt(8)
	v_mfma_f32_16x16x32_bf16 v[2:5], v[184:187], v[200:203], v[2:5]
	v_mfma_f32_16x16x32_bf16 v[10:13], v[148:151], v[188:191], v[10:13]
	v_mfma_f32_16x16x32_bf16 v[22:25], v[148:151], v[192:195], v[22:25]
	v_mfma_f32_16x16x32_bf16 v[30:33], v[148:151], v[196:199], v[30:33]
	v_mfma_f32_16x16x32_bf16 v[38:41], v[148:151], v[200:203], v[38:41]
	v_mfma_f32_16x16x32_bf16 v[46:49], v[152:155], v[188:191], v[46:49]
	v_mfma_f32_16x16x32_bf16 v[62:65], v[152:155], v[192:195], v[62:65]
	v_mfma_f32_16x16x32_bf16 v[70:73], v[152:155], v[196:199], v[70:73]
	v_mfma_f32_16x16x32_bf16 v[54:57], v[152:155], v[200:203], v[54:57]
	v_mfma_f32_16x16x32_bf16 v[58:61], v[180:183], v[188:191], v[58:61]
	v_mfma_f32_16x16x32_bf16 v[78:81], v[180:183], v[192:195], v[78:81]
	v_mfma_f32_16x16x32_bf16 v[74:77], v[180:183], v[196:199], v[74:77]
	v_mfma_f32_16x16x32_bf16 v[14:17], v[180:183], v[200:203], v[14:17]
	v_mfma_f32_16x16x32_bf16 v[18:21], v[184:187], v[188:191], v[18:21]
	v_mfma_f32_16x16x32_bf16 v[42:45], v[184:187], v[192:195], v[42:45]
	v_mfma_f32_16x16x32_bf16 v[34:37], v[184:187], v[196:199], v[34:37]
	s_waitcnt lgkmcnt(0)
	v_mfma_f32_16x16x32_bf16 v[2:5], v[216:219], v[232:235], v[2:5]
	v_mfma_f32_16x16x32_bf16 v[10:13], v[204:207], v[220:223], v[10:13]
	v_mfma_f32_16x16x32_bf16 v[22:25], v[204:207], v[224:227], v[22:25]
	v_mfma_f32_16x16x32_bf16 v[30:33], v[204:207], v[228:231], v[30:33]
	v_mfma_f32_16x16x32_bf16 v[38:41], v[204:207], v[232:235], v[38:41]
	v_mfma_f32_16x16x32_bf16 v[46:49], v[208:211], v[220:223], v[46:49]
	v_mfma_f32_16x16x32_bf16 v[62:65], v[208:211], v[224:227], v[62:65]
	v_mfma_f32_16x16x32_bf16 v[70:73], v[208:211], v[228:231], v[70:73]
	v_mfma_f32_16x16x32_bf16 v[54:57], v[208:211], v[232:235], v[54:57]
	v_mfma_f32_16x16x32_bf16 v[58:61], v[212:215], v[220:223], v[58:61]
	v_mfma_f32_16x16x32_bf16 v[78:81], v[212:215], v[224:227], v[78:81]
	v_mfma_f32_16x16x32_bf16 v[74:77], v[212:215], v[228:231], v[74:77]
	v_mfma_f32_16x16x32_bf16 v[14:17], v[212:215], v[232:235], v[14:17]
	v_mfma_f32_16x16x32_bf16 v[18:21], v[216:219], v[220:223], v[18:21]
	v_mfma_f32_16x16x32_bf16 v[42:45], v[216:219], v[224:227], v[42:45]
	v_mfma_f32_16x16x32_bf16 v[34:37], v[216:219], v[228:231], v[34:37]
	s_setprio 0
	v_readfirstlane_b32 s12, v143
	v_lshl_add_u64 v[148:149], v[6:7], 0, s[64:65]
	s_mov_b32 m0, s12
	v_readfirstlane_b32 s12, v142
	s_waitcnt vmcnt(0)
	s_barrier
	global_load_lds_dwordx4 v[148:149], off
	v_lshl_add_u64 v[8:9], v[8:9], 0, s[64:65]
	s_mov_b32 m0, s12
	s_mov_b64 s[0:1], 0x8380
	v_readfirstlane_b32 s12, v144
	global_load_lds_dwordx4 v[8:9], off
	v_lshl_add_u64 v[8:9], v[6:7], 0, s[0:1]
	s_mov_b32 m0, s12
	s_mov_b64 s[0:1], 0x10380
	global_load_lds_dwordx4 v[8:9], off
	v_lshl_add_u64 v[8:9], v[26:27], 0, s[64:65]
	s_mov_b32 m0, s5
	s_nop 0
	global_load_lds_dwordx4 v[8:9], off
	v_lshl_add_u64 v[8:9], v[6:7], 0, s[0:1]
	s_mov_b32 m0, s8
	s_mov_b64 s[0:1], 0x18380
	global_load_lds_dwordx4 v[8:9], off
	v_lshl_add_u64 v[8:9], v[28:29], 0, s[64:65]
	s_mov_b32 m0, s9
	v_lshl_add_u64 v[6:7], v[6:7], 0, s[0:1]
	global_load_lds_dwordx4 v[8:9], off
	s_mov_b32 m0, s10
	s_nop 0
	global_load_lds_dwordx4 v[6:7], off
	v_lshl_add_u64 v[6:7], v[50:51], 0, s[64:65]
	s_mov_b32 m0, s11
	s_nop 0
	global_load_lds_dwordx4 v[6:7], off
	ds_read_b128 v[6:9], v0
	ds_read_b128 v[26:29], v0 offset:2048
	ds_read_b128 v[148:151], v0 offset:4096
	ds_read_b128 v[152:155], v0 offset:6144
	ds_read_b128 v[180:183], v145 offset:16384
	ds_read_b128 v[184:187], v145 offset:18432
	ds_read_b128 v[188:191], v145 offset:20480
	ds_read_b128 v[192:195], v145 offset:22528
	ds_read_b128 v[196:199], v146
	ds_read_b128 v[200:203], v146 offset:2048
	ds_read_b128 v[204:207], v146 offset:4096
	ds_read_b128 v[208:211], v146 offset:6144
	ds_read_b128 v[212:215], v147 offset:16384
	ds_read_b128 v[216:219], v147 offset:18432
	ds_read_b128 v[220:223], v147 offset:20480
	ds_read_b128 v[224:227], v147 offset:22528
	s_setprio 1
	s_waitcnt lgkmcnt(8)
; #define MFMA16(a, b, c) __builtin_amdgcn_mfma_f32_16x16x32_bf16((a), (b), (c), 0, 0, 0)
; DI void gemm_tile(const bf16_t* __restrict__ A, int lda, const bf16_t* __restrict__ Bt, int ldb, int bvalid, int K, f32x4 (&acc)[4][4], char* lds, bool preloaded = false) {
;     ...
;   auto compute = [&](int st) {
;     const char* base = lds + st * 32768;
;     bf16x8 af[2][4], bfr[2][4];
; #pragma unroll
;     for (int s = 0; s < 2; ++s) {
;       const int ch = ((4 * s + fq) ^ fx) << 4;
; #pragma unroll
;       for (int mi = 0; mi < 4; ++mi) af[s][mi] = *(const bf16x8*)(base + (wm * 64 + mi * 16 + fr) * 128 + ch);
; #pragma unroll
;       for (int ni = 0; ni < 4; ++ni) bfr[s][ni] = *(const bf16x8*)(base + 16384 + (wn * 64 + ni * 16 + fr) * 128 + ch);
;     }
;     __builtin_amdgcn_s_setprio(1);
; #pragma unroll
;     for (int s = 0; s < 2; ++s)
; #pragma unroll
;       for (int mi = 0; mi < 4; ++mi)
; #pragma unroll
;         for (int ni = 0; ni < 4; ++ni) acc[mi][ni] = MFMA16(af[s][mi], bfr[s][ni], acc[mi][ni]);
;     __builtin_amdgcn_s_setprio(0);
;   };
;   const int nk = K >> 6;
;   if (!preloaded) { GLDS(0, 0) }
;   __syncthreads();
;   for (int kt = 0; kt < nk; ++kt) {
;     if (kt + 1 < nk) { GLDS((kt + 1) & 1, (kt + 1) << 6) }
;     compute(kt & 1);
;     __syncthreads();
;   }
; DI void phaseD_tile(const P& p, int layer, int mt, int nt, char* lds) {
;     ...
; #pragma unroll
;   for (int mi = 0; mi < 4; ++mi)
; #pragma unroll
;     for (int ni = 0; ni < 4; ++ni)
; #pragma unroll
;       for (int j = 0; j < 4; ++j) acc[mi][ni][j] *= fmaxf((float)((gav[mi][ni] >> (8 * j)) & 255u), 1.f) * (1.f / 255.f);
	v_mfma_f32_16x16x32_bf16 v[2:5], v[152:155], v[192:195], v[2:5]
	v_mfma_f32_16x16x32_bf16 v[10:13], v[6:9], v[180:183], v[10:13]
	v_mfma_f32_16x16x32_bf16 v[22:25], v[6:9], v[184:187], v[22:25]
	v_mfma_f32_16x16x32_bf16 v[30:33], v[6:9], v[188:191], v[30:33]
	v_mfma_f32_16x16x32_bf16 v[6:9], v[6:9], v[192:195], v[38:41]
	v_mfma_f32_16x16x32_bf16 v[38:41], v[26:29], v[180:183], v[46:49]
	v_mfma_f32_16x16x32_bf16 v[46:49], v[26:29], v[184:187], v[62:65]
	v_mfma_f32_16x16x32_bf16 v[62:65], v[26:29], v[188:191], v[70:73]
	v_mfma_f32_16x16x32_bf16 v[26:29], v[26:29], v[192:195], v[54:57]
	v_mfma_f32_16x16x32_bf16 v[54:57], v[148:151], v[180:183], v[58:61]
	v_mfma_f32_16x16x32_bf16 v[58:61], v[148:151], v[184:187], v[78:81]
	v_mfma_f32_16x16x32_bf16 v[70:73], v[148:151], v[188:191], v[74:77]
	v_mfma_f32_16x16x32_bf16 v[14:17], v[148:151], v[192:195], v[14:17]
	v_mfma_f32_16x16x32_bf16 v[18:21], v[152:155], v[180:183], v[18:21]
	v_mfma_f32_16x16x32_bf16 v[42:45], v[152:155], v[184:187], v[42:45]
	v_mfma_f32_16x16x32_bf16 v[34:37], v[152:155], v[188:191], v[34:37]
	s_waitcnt lgkmcnt(0)
	v_mfma_f32_16x16x32_bf16 v[2:5], v[208:211], v[224:227], v[2:5]
	v_mfma_f32_16x16x32_bf16 v[10:13], v[196:199], v[212:215], v[10:13]
	v_mfma_f32_16x16x32_bf16 v[22:25], v[196:199], v[216:219], v[22:25]
	v_mfma_f32_16x16x32_bf16 v[30:33], v[196:199], v[220:223], v[30:33]
	v_mfma_f32_16x16x32_bf16 v[6:9], v[196:199], v[224:227], v[6:9]
	v_mfma_f32_16x16x32_bf16 v[38:41], v[200:203], v[212:215], v[38:41]
	v_mfma_f32_16x16x32_bf16 v[46:49], v[200:203], v[216:219], v[46:49]
	v_mfma_f32_16x16x32_bf16 v[62:65], v[200:203], v[220:223], v[62:65]
	v_mfma_f32_16x16x32_bf16 v[26:29], v[200:203], v[224:227], v[26:29]
	v_mfma_f32_16x16x32_bf16 v[54:57], v[204:207], v[212:215], v[54:57]
	v_mfma_f32_16x16x32_bf16 v[58:61], v[204:207], v[216:219], v[58:61]
	v_mfma_f32_16x16x32_bf16 v[70:73], v[204:207], v[220:223], v[70:73]
	v_mfma_f32_16x16x32_bf16 v[14:17], v[204:207], v[224:227], v[14:17]
	v_mfma_f32_16x16x32_bf16 v[18:21], v[208:211], v[212:215], v[18:21]
	v_mfma_f32_16x16x32_bf16 v[42:45], v[208:211], v[216:219], v[42:45]
	v_mfma_f32_16x16x32_bf16 v[34:37], v[208:211], v[220:223], v[34:37]
	s_setprio 0
	s_waitcnt vmcnt(0)
	s_barrier
	ds_read_b128 v[74:77], v0 offset:32768
	ds_read_b128 v[78:81], v0 offset:34816
	ds_read_b128 v[148:151], v0 offset:36864
	ds_read_b128 v[152:155], v0 offset:38912
	ds_read_b128 v[180:183], v145 offset:49152
	ds_read_b128 v[184:187], v145 offset:51200
	ds_read_b128 v[188:191], v145 offset:53248
	ds_read_b128 v[142:145], v145 offset:55296
	ds_read_b128 v[192:195], v146 offset:32768
	ds_read_b128 v[196:199], v146 offset:34816
	ds_read_b128 v[200:203], v146 offset:36864
	ds_read_b128 v[204:207], v146 offset:38912
	ds_read_b128 v[208:211], v147 offset:49152
	ds_read_b128 v[212:215], v147 offset:51200
	ds_read_b128 v[216:219], v147 offset:53248
	ds_read_b128 v[220:223], v147 offset:55296
	s_setprio 1
	s_waitcnt lgkmcnt(8)
	v_mfma_f32_16x16x32_bf16 v[2:5], v[152:155], v[142:145], v[2:5]
	v_mfma_f32_16x16x32_bf16 v[10:13], v[74:77], v[180:183], v[10:13]
	v_mfma_f32_16x16x32_bf16 v[22:25], v[74:77], v[184:187], v[22:25]
	v_mfma_f32_16x16x32_bf16 v[30:33], v[74:77], v[188:191], v[30:33]
	v_mfma_f32_16x16x32_bf16 v[6:9], v[74:77], v[142:145], v[6:9]
	v_mfma_f32_16x16x32_bf16 v[38:41], v[78:81], v[180:183], v[38:41]
	v_mfma_f32_16x16x32_bf16 v[46:49], v[78:81], v[184:187], v[46:49]
	v_mfma_f32_16x16x32_bf16 v[62:65], v[78:81], v[188:191], v[62:65]
	v_mfma_f32_16x16x32_bf16 v[26:29], v[78:81], v[142:145], v[26:29]
	v_mfma_f32_16x16x32_bf16 v[54:57], v[148:151], v[180:183], v[54:57]
	v_mfma_f32_16x16x32_bf16 v[58:61], v[148:151], v[184:187], v[58:61]
	v_mfma_f32_16x16x32_bf16 v[70:73], v[148:151], v[188:191], v[70:73]
	v_mfma_f32_16x16x32_bf16 v[14:17], v[148:151], v[142:145], v[14:17]
	v_mfma_f32_16x16x32_bf16 v[18:21], v[152:155], v[180:183], v[18:21]
	v_mfma_f32_16x16x32_bf16 v[42:45], v[152:155], v[184:187], v[42:45]
	v_mfma_f32_16x16x32_bf16 v[34:37], v[152:155], v[188:191], v[34:37]
	s_waitcnt lgkmcnt(0)
	v_mfma_f32_16x16x32_bf16 v[2:5], v[204:207], v[220:223], v[2:5]
	v_mfma_f32_16x16x32_bf16 v[10:13], v[192:195], v[208:211], v[10:13]
	v_mfma_f32_16x16x32_bf16 v[22:25], v[192:195], v[212:215], v[22:25]
	v_mfma_f32_16x16x32_bf16 v[30:33], v[192:195], v[216:219], v[30:33]
	v_mfma_f32_16x16x32_bf16 v[6:9], v[192:195], v[220:223], v[6:9]
	v_mfma_f32_16x16x32_bf16 v[38:41], v[196:199], v[208:211], v[38:41]
	v_mfma_f32_16x16x32_bf16 v[46:49], v[196:199], v[212:215], v[46:49]
	v_mfma_f32_16x16x32_bf16 v[62:65], v[196:199], v[216:219], v[62:65]
	v_mfma_f32_16x16x32_bf16 v[26:29], v[196:199], v[220:223], v[26:29]
	v_mfma_f32_16x16x32_bf16 v[54:57], v[200:203], v[208:211], v[54:57]
	v_mfma_f32_16x16x32_bf16 v[58:61], v[200:203], v[212:215], v[58:61]
	v_mfma_f32_16x16x32_bf16 v[70:73], v[200:203], v[216:219], v[70:73]
	v_mfma_f32_16x16x32_bf16 v[14:17], v[200:203], v[220:223], v[14:17]
	v_mfma_f32_16x16x32_bf16 v[18:21], v[204:207], v[208:211], v[18:21]
	v_mfma_f32_16x16x32_bf16 v[42:45], v[204:207], v[212:215], v[42:45]
	v_mfma_f32_16x16x32_bf16 v[34:37], v[204:207], v[216:219], v[34:37]
	s_setprio 0
	v_mul_f32_e32 v0, 0x3b808081, v100
	v_mul_f32_e32 v10, v0, v10
	v_mul_f32_e32 v0, 0x3b808081, v101
	v_mul_f32_e32 v11, v0, v11
	v_mul_f32_e32 v0, 0x3b808081, v102
	v_mul_f32_e32 v12, v0, v12
	v_mul_f32_e32 v0, 0x3b808081, v103
	v_mul_f32_e32 v13, v0, v13
	v_mul_f32_e32 v0, 0x3b808081, v104
	v_mul_f32_e32 v22, v0, v22
	v_mul_f32_e32 v0, 0x3b808081, v105
	v_mul_f32_e32 v23, v0, v23
	v_mul_f32_e32 v0, 0x3b808081, v106
	v_mul_f32_e32 v24, v0, v24
; DI void stage_acc(const f32x4 (&acc)[4][4], float* tile, int wm, int wn, int fr, int fq) {
; #pragma unroll
;   for (int mi = 0; mi < 4; ++mi)
; #pragma unroll
;     for (int ni = 0; ni < 4; ++ni)
; #pragma unroll
;       for (int j = 0; j < 4; ++j) tile[(wm * 64 + mi * 16 + fq * 4 + j) * EPS + wn * 64 + ni * 16 + fr] = acc[mi][ni][j];
; DI void phaseD_tile(const P& p, int layer, int mt, int nt, char* lds) {
;     ...
;       for (int j = 0; j < 4; ++j) acc[mi][ni][j] *= fmaxf((float)((gav[mi][ni] >> (8 * j)) & 255u), 1.f) * (1.f / 255.f);
;   float* tile = (float*)lds;
;   stage_acc(acc, tile, wm, wn, fr, fq);
;   __syncthreads();
;   bf16_t* MG = (bf16_t*)(p.ws + W_MERGED);
; #pragma unroll 1
;   for (int ps = 0; ps < 16; ++ps) {
;     const int lr = ps * 8 + wm * 4 + fq;
;     const f32x4 v = *(const f32x4*)(tile + lr * EPS + wn * 64 + fr * 4);
	v_mul_f32_e32 v0, 0x3b808081, v107
	v_mul_f32_e32 v25, v0, v25
	v_mul_f32_e32 v0, 0x3b808081, v108
	v_mul_f32_e32 v30, v0, v30
	v_mul_f32_e32 v0, 0x3b808081, v109
	v_mul_f32_e32 v31, v0, v31
	v_mul_f32_e32 v0, 0x3b808081, v110
	v_mul_f32_e32 v32, v0, v32
	v_mul_f32_e32 v0, 0x3b808081, v111
	v_mul_f32_e32 v33, v0, v33
	v_mul_f32_e32 v0, 0x3b808081, v112
	v_mul_f32_e32 v6, v0, v6
	v_mul_f32_e32 v0, 0x3b808081, v113
	v_mul_f32_e32 v7, v0, v7
	v_mul_f32_e32 v0, 0x3b808081, v114
	v_mul_f32_e32 v8, v0, v8
	v_mul_f32_e32 v0, 0x3b808081, v115
	v_mul_f32_e32 v9, v0, v9
	v_mul_f32_e32 v0, 0x3b808081, v94
	v_mul_f32_e32 v38, v0, v38
	v_mul_f32_e32 v0, 0x3b808081, v95
	v_mul_f32_e32 v39, v0, v39
	v_mul_f32_e32 v0, 0x3b808081, v96
	v_mul_f32_e32 v40, v0, v40
	v_mul_f32_e32 v0, 0x3b808081, v97
	v_mul_f32_e32 v41, v0, v41
	v_mul_f32_e32 v0, 0x3b808081, v90
	v_mul_f32_e32 v46, v0, v46
	v_mul_f32_e32 v0, 0x3b808081, v91
	v_mul_f32_e32 v47, v0, v47
	v_mul_f32_e32 v0, 0x3b808081, v92
	v_mul_f32_e32 v48, v0, v48
	v_mul_f32_e32 v0, 0x3b808081, v93
	v_mul_f32_e32 v49, v0, v49
	v_mul_f32_e32 v0, 0x3b808081, v116
	v_mul_f32_e32 v50, v0, v62
	v_mul_f32_e32 v0, 0x3b808081, v117
	v_mul_f32_e32 v51, v0, v63
	v_mul_f32_e32 v0, 0x3b808081, v118
	v_mul_f32_e32 v62, v0, v64
	v_mul_f32_e32 v0, 0x3b808081, v119
	v_mul_f32_e32 v63, v0, v65
	v_mul_f32_e32 v0, 0x3b808081, v120
	v_mul_f32_e32 v26, v0, v26
	v_mul_f32_e32 v0, 0x3b808081, v121
	v_mul_f32_e32 v27, v0, v27
	v_mul_f32_e32 v0, 0x3b808081, v122
	v_mul_f32_e32 v28, v0, v28
	v_mul_f32_e32 v0, 0x3b808081, v123
	v_mul_f32_e32 v29, v0, v29
	v_mul_f32_e32 v0, 0x3b808081, v86
	v_mul_f32_e32 v54, v0, v54
	v_mul_f32_e32 v0, 0x3b808081, v87
	v_mul_f32_e32 v55, v0, v55
	v_mul_f32_e32 v0, 0x3b808081, v88
	v_mul_f32_e32 v56, v0, v56
	v_mul_f32_e32 v0, 0x3b808081, v89
	v_mul_f32_e32 v57, v0, v57
	v_mul_f32_e32 v0, 0x3b808081, v82
	v_mul_f32_e32 v58, v0, v58
	v_mul_f32_e32 v0, 0x3b808081, v83
	v_mul_f32_e32 v59, v0, v59
	v_mul_f32_e32 v0, 0x3b808081, v84
	v_mul_f32_e32 v60, v0, v60
	v_mul_f32_e32 v0, 0x3b808081, v85
	v_mul_f32_e32 v61, v0, v61
	v_mul_f32_e32 v0, 0x3b808081, v124
	v_mul_f32_e32 v64, v0, v70
	v_mul_f32_e32 v0, 0x3b808081, v125
	v_mul_f32_e32 v65, v0, v71
	v_mul_f32_e32 v0, 0x3b808081, v126
	v_mul_f32_e32 v70, v0, v72
	v_mul_f32_e32 v0, 0x3b808081, v127
	v_mul_f32_e32 v71, v0, v73
	v_mul_f32_e32 v0, 0x3b808081, v128
	v_mul_f32_e32 v14, v0, v14
	v_mul_f32_e32 v0, 0x3b808081, v129
	v_mul_f32_e32 v15, v0, v15
	v_mul_f32_e32 v0, 0x3b808081, v130
	v_mul_f32_e32 v16, v0, v16
	v_mul_f32_e32 v0, 0x3b808081, v131
	v_mul_f32_e32 v17, v0, v17
	v_mul_f32_e32 v0, 0x3b808081, v66
	v_mul_f32_e32 v18, v0, v18
	v_mul_f32_e32 v0, 0x3b808081, v67
	v_mul_f32_e32 v19, v0, v19
	v_mul_f32_e32 v0, 0x3b808081, v68
	v_mul_f32_e32 v20, v0, v20
	v_mul_f32_e32 v0, 0x3b808081, v69
	v_mul_f32_e32 v21, v0, v21
	v_mul_f32_e32 v0, 0x3b808081, v52
	v_mul_f32_e32 v42, v0, v42
	v_mul_f32_e32 v0, 0x3b808081, v53
	v_mul_f32_e32 v43, v0, v43
	v_mul_f32_e32 v0, 0x3b808081, v132
	v_mul_f32_e32 v44, v0, v44
	v_mul_f32_e32 v0, 0x3b808081, v133
	v_mul_f32_e32 v45, v0, v45
	v_mul_f32_e32 v0, 0x3b808081, v134
	v_mul_f32_e32 v34, v0, v34
	v_mul_f32_e32 v0, 0x3b808081, v135
	v_mul_f32_e32 v35, v0, v35
	v_mul_f32_e32 v0, 0x3b808081, v136
	v_mul_f32_e32 v36, v0, v36
	v_mul_f32_e32 v0, 0x3b808081, v137
	v_mul_f32_e32 v37, v0, v37
	v_mul_f32_e32 v0, 0x3b808081, v138
	v_mul_f32_e32 v52, v0, v2
	v_mul_f32_e32 v0, 0x3b808081, v139
	v_mul_f32_e32 v53, v0, v3
	v_mul_f32_e32 v0, 0x3b808081, v140
	v_mul_f32_e32 v4, v0, v4
	v_mul_f32_e32 v0, 0x3b808081, v141
	v_bfe_u32 v66, v99, 4, 2
	v_mul_f32_e32 v5, v0, v5
	v_lshlrev_b32_e32 v0, 2, v66
	s_lshl_b32 s5, s20, 8
	v_lshl_or_b32 v2, s19, 6, v0
	v_lshl_or_b32 v0, v98, 2, s5
	v_mad_u64_u32 v[2:3], s[8:9], v2, s56, v[0:1]
	v_add_u32_e32 v0, 0x400, v2
	s_lshl_b32 s8, s19, 2
	s_lshl_b64 s[6:7], s[6:7], 1
	s_mov_b64 s[58:59], s[60:61]
	s_barrier
	ds_write2_b32 v2, v10, v22 offset1:16
	ds_write2_b32 v2, v11, v23 offset0:132 offset1:148
	ds_write2_b32 v0, v12, v24 offset0:8 offset1:24
	ds_write2_b32 v0, v13, v25 offset0:140 offset1:156
	ds_write2_b32 v2, v30, v6 offset0:32 offset1:48
	ds_write2_b32 v2, v31, v7 offset0:164 offset1:180
	ds_write2_b32 v0, v32, v8 offset0:40 offset1:56
	ds_write2_b32 v0, v33, v9 offset0:172 offset1:188
	v_add_u32_e32 v0, 0x2000, v2
	v_add_u32_e32 v3, 0x2400, v2
	s_add_u32 s6, s58, s6
	ds_write2_b32 v0, v38, v46 offset0:64 offset1:80
	ds_write2_b32 v0, v39, v47 offset0:196 offset1:212
	ds_write2_b32 v3, v40, v48 offset0:72 offset1:88
	ds_write2_b32 v3, v41, v49 offset0:204 offset1:220
	ds_write2_b32 v0, v50, v26 offset0:96 offset1:112
	ds_write2_b32 v0, v51, v27 offset0:228 offset1:244
	ds_write2_b32 v3, v62, v28 offset0:104 offset1:120
	ds_write2_b32 v3, v63, v29 offset0:236 offset1:252
	v_add_u32_e32 v0, 0x4000, v2
	v_add_u32_e32 v3, 0x4400, v2
	v_add_u32_e32 v6, 0x4800, v2
	s_addc_u32 s7, s59, s7
	s_lshl_b32 s9, s20, 7
	ds_write2_b32 v0, v54, v58 offset0:128 offset1:144
	ds_write2_b32 v3, v55, v59 offset0:4 offset1:20
	ds_write2_b32 v3, v56, v60 offset0:136 offset1:152
	ds_write2_b32 v6, v57, v61 offset0:12 offset1:28
	ds_write2_b32 v0, v64, v14 offset0:160 offset1:176
	ds_write2_b32 v3, v65, v15 offset0:36 offset1:52
	ds_write2_b32 v3, v70, v16 offset0:168 offset1:184
	ds_write2_b32 v6, v71, v17 offset0:44 offset1:60
	v_add_u32_e32 v0, 0x6000, v2
	v_add_u32_e32 v3, 0x6400, v2
	v_add_u32_e32 v2, 0x6800, v2
	s_add_u32 s6, s6, s9
	s_mulk_i32 s19, 0x840
	ds_write2_b32 v0, v18, v42 offset0:192 offset1:208
	ds_write2_b32 v3, v19, v43 offset0:68 offset1:84
	ds_write2_b32 v3, v20, v44 offset0:200 offset1:216
	ds_write2_b32 v2, v21, v45 offset0:76 offset1:92
	ds_write2_b32 v0, v34, v52 offset0:224 offset1:240
	ds_write2_b32 v3, v35, v53 offset0:100 offset1:116
	ds_write2_b32 v3, v36, v4 offset0:232 offset1:248
	ds_write2_b32 v2, v37, v5 offset0:108 offset1:124
	s_addc_u32 s7, s7, 0
	v_lshlrev_b32_e32 v0, 3, v98
	s_add_i32 s8, s8, s4
	v_mul_u32_u24_e32 v4, 0x210, v66
	s_add_i32 s5, s5, s19
	v_lshlrev_b32_e32 v5, 4, v98
	v_lshl_add_u64 v[2:3], s[6:7], 0, v[0:1]
	v_or_b32_e32 v0, s8, v66
	v_add3_u32 v4, s5, v4, v5
	s_mov_b32 s4, 0
	s_movk_i32 s5, 0x880
	s_waitcnt lgkmcnt(0)
	s_barrier

; DI int tidx() { int t = __builtin_amdgcn_workitem_id_x(); asm volatile("" : "+v"(t)); return t; }
; DI void gemm_tile(const bf16_t* __restrict__ A, int lda, const bf16_t* __restrict__ Bt, int ldb, int bvalid, int K, f32x4 (&acc)[4][4], char* lds, bool preloaded = false) {
;   const int tid = tidx(), lane = tid & 63, wave = __builtin_amdgcn_readfirstlane(tid >> 6);
;   const int wm = wave >> 1, wn = wave & 1;
;   const int lr = tid >> 3, lc = tid & 7;
;   const int fr = lane & 15, fq = lane >> 4;
;   const int fx = (fr >> 1) & 7;
;   const bf16_t* ap = A + (size_t)lr * lda + ((lc ^ ((lr >> 1) & 7)) << 3);
;   const bf16_t* bp = Bt + ((lc ^ ((lr >> 1) & 7)) << 3);
;   typedef __attribute__((address_space(1))) const unsigned gptr_t;
;   typedef __attribute__((address_space(3))) unsigned lptr_t;
;   const unsigned lbase = (unsigned)(size_t)lds + (unsigned)tid * 16u;
;     ...
;   auto compute = [&](int st) {
;     const char* base = lds + st * 32768;
;     bf16x8 af[2][4], bfr[2][4];
; #pragma unroll
;     for (int s = 0; s < 2; ++s) {
;       const int ch = ((4 * s + fq) ^ fx) << 4;
; #pragma unroll
;       for (int mi = 0; mi < 4; ++mi) af[s][mi] = *(const bf16x8*)(base + (wm * 64 + mi * 16 + fr) * 128 + ch);
; #pragma unroll
;       for (int ni = 0; ni < 4; ++ni) bfr[s][ni] = *(const bf16x8*)(base + 16384 + (wn * 64 + ni * 16 + fr) * 128 + ch);
;     }
;     __builtin_amdgcn_s_setprio(1);
; #pragma unroll
;     for (int s = 0; s < 2; ++s)
; #pragma unroll
;       for (int mi = 0; mi < 4; ++mi)
; #pragma unroll
;         for (int ni = 0; ni < 4; ++ni) acc[mi][ni] = MFMA16(af[s][mi], bfr[s][ni], acc[mi][ni]);
;     __builtin_amdgcn_s_setprio(0);
;   };
;   const int nk = K >> 6;
;   if (!preloaded) { GLDS(0, 0) }
;   __syncthreads();
;   for (int kt = 0; kt < nk; ++kt) {
;     if (kt + 1 < nk) { GLDS((kt + 1) & 1, (kt + 1) << 6) }
;     compute(kt & 1);
; DI void mix_tile(const P& p, int layer, int tile, char* lds) {
;   const int lane = tidx() & 63, wave = __builtin_amdgcn_readfirstlane(tidx() >> 6);
;   const int mt = tile >> 2, g = tile & 3;
;   const int row0 = mt * 128;
;   f32x4 acc[4][4];
;   zero_acc(acc);
;   bf16_t* PA = (bf16_t*)(p.ws + W_POOLED);
;   gemm_tile(PA + (size_t)row0 * 512 + g * 128, 512, (const bf16_t*)(p.ws + W_WMIX) + (size_t)(layer * 4 + g) * 128 * 128, 128, 128, 128, acc, lds);
.LBB0_291:
	s_or_b64 exec, exec, s[10:11]
	s_waitcnt lgkmcnt(0)
	s_barrier
	ds_read_b32 v0, v159
	s_movk_i32 s10, 0x189
	s_waitcnt lgkmcnt(0)
	v_cmp_lt_i32_e32 vcc, s10, v0
	v_readfirstlane_b32 s16, v0
	s_mov_b64 s[10:11], -1
	s_cbranch_vccnz .LBB0_286
	s_cmp_gt_i32 s16, 7
	s_cbranch_scc0 .LBB0_315
	s_cmpk_gt_u32 s16, 0x107
	s_cbranch_scc0 .LBB0_295
	s_lshl_b32 s10, s16, 8
	s_add_i32 s10, s27, s10
	v_mov_b32_e32 v130, v158
	v_mov_b32_e32 v66, v158
	s_and_b32 s10, s10, 0xff80
	v_mov_b32_e32 v14, v158
	s_lshl_b32 s11, s10, 10
	s_add_u32 s12, s28, s11
	v_ashrrev_i32_e32 v2, 3, v14
	v_lshrrev_b32_e32 v0, 4, v14
	v_ashrrev_i32_e32 v3, 31, v2
	v_xor_b32_e32 v0, v0, v14
	s_addc_u32 s13, s29, 0
	v_lshlrev_b64 v[4:5], 10, v[2:3]
	v_lshlrev_b32_e32 v0, 4, v0
	v_lshl_add_u64 v[4:5], s[12:13], 0, v[4:5]
	v_and_b32_e32 v0, 0x70, v0
	v_lshlrev_b32_e32 v16, 7, v2
	v_lshl_add_u64 v[4:5], v[4:5], 0, v[0:1]
	v_lshl_add_u64 v[6:7], s[4:5], 0, v[0:1]
	v_lshlrev_b32_e32 v15, 4, v14
	v_and_b32_e32 v0, 0x3f80, v16
	v_add_u32_e32 v8, 0x4000, v15
	v_readfirstlane_b32 s11, v15
	v_lshlrev_b32_e32 v0, 1, v0
	s_mov_b32 m0, s11
	v_lshl_add_u64 v[2:3], v[6:7], 0, v[0:1]
	v_readfirstlane_b32 s11, v8
	v_add_u32_e32 v0, 0x1000, v15
	global_load_lds_dwordx4 v[4:5], off
	s_mov_b32 m0, s11
	v_readfirstlane_b32 s11, v0
	v_add_u32_e32 v0, 0x1000, v16
	s_mov_b64 s[36:37], 0x8000
	v_and_b32_e32 v0, 0x3f80, v0
	global_load_lds_dwordx4 v[2:3], off
	v_lshl_add_u64 v[8:9], v[4:5], 0, s[36:37]
	s_mov_b32 m0, s11
	v_lshlrev_b32_e32 v0, 1, v0
	global_load_lds_dwordx4 v[8:9], off
	v_lshl_add_u64 v[8:9], v[6:7], 0, v[0:1]
	v_add_u32_e32 v0, 0x5000, v15
	s_movk_i32 s17, 0x2000
	v_readfirstlane_b32 s11, v0
	v_add_u32_e32 v0, 0x2000, v15
	s_mov_b32 m0, s11
	s_mov_b64 s[38:39], 0x10000
	v_readfirstlane_b32 s11, v0
	v_bitop3_b32 v0, v16, s17, v168 bitop3:0x6c
	global_load_lds_dwordx4 v[8:9], off
	v_lshl_add_u64 v[10:11], v[4:5], 0, s[38:39]
	s_mov_b32 m0, s11
	v_lshlrev_b32_e32 v0, 1, v0
	global_load_lds_dwordx4 v[10:11], off
	v_lshl_add_u64 v[10:11], v[6:7], 0, v[0:1]
	v_add_u32_e32 v0, 0x6000, v15
	s_mov_b64 s[40:41], 0x18000
	v_readfirstlane_b32 s11, v0
	v_add_u32_e32 v0, 0x3000, v15
	s_mov_b32 m0, s11
	v_readfirstlane_b32 s11, v0
	v_add_u32_e32 v0, 0x3000, v16
	v_and_b32_e32 v0, 0x3f80, v0
	v_lshlrev_b32_e32 v0, 1, v0
	v_lshl_add_u64 v[6:7], v[6:7], 0, v[0:1]
	v_add_u32_e32 v0, 0x7000, v15
	global_load_lds_dwordx4 v[10:11], off
	v_lshl_add_u64 v[12:13], v[4:5], 0, s[40:41]
	s_mov_b32 m0, s11
	v_readfirstlane_b32 s11, v0
	v_add_u32_e32 v0, 0x8000, v15
	global_load_lds_dwordx4 v[12:13], off
	s_mov_b32 m0, s11
	s_mov_b64 s[12:13], 0x80
	v_add_u32_e32 v16, 0xc000, v15
	v_readfirstlane_b32 s11, v0
	global_load_lds_dwordx4 v[6:7], off
	v_lshl_add_u64 v[12:13], v[4:5], 0, s[12:13]
	s_mov_b32 m0, s11
	v_readfirstlane_b32 s11, v16
	v_add_u32_e32 v0, 0x9000, v15
	s_waitcnt vmcnt(0) lgkmcnt(0)
	s_barrier
	global_load_lds_dwordx4 v[12:13], off
	v_lshl_add_u64 v[2:3], v[2:3], 0, s[12:13]
	s_mov_b32 m0, s11
	s_mov_b64 s[14:15], 0x8080
	v_readfirstlane_b32 s11, v0
	v_add_u32_e32 v0, 0xd000, v15
	global_load_lds_dwordx4 v[2:3], off
	v_lshl_add_u64 v[2:3], v[4:5], 0, s[14:15]
	s_mov_b32 m0, s11
	v_readfirstlane_b32 s11, v0
	v_add_u32_e32 v0, 0xa000, v15
	global_load_lds_dwordx4 v[2:3], off
	v_lshl_add_u64 v[2:3], v[8:9], 0, s[12:13]
	s_mov_b32 m0, s11
	s_mov_b64 s[14:15], 0x10080
	v_readfirstlane_b32 s11, v0
	v_add_u32_e32 v0, 0xe000, v15
	global_load_lds_dwordx4 v[2:3], off
	v_lshl_add_u64 v[2:3], v[4:5], 0, s[14:15]
	s_mov_b32 m0, s11
	v_readfirstlane_b32 s11, v0
	v_add_u32_e32 v0, 0xb000, v15
	global_load_lds_dwordx4 v[2:3], off
	v_lshl_add_u64 v[2:3], v[10:11], 0, s[12:13]
	s_mov_b32 m0, s11
	s_mov_b64 s[14:15], 0x18080
	v_readfirstlane_b32 s11, v0
	v_add_u32_e32 v0, 0xf000, v15
	global_load_lds_dwordx4 v[2:3], off
	v_lshl_add_u64 v[2:3], v[4:5], 0, s[14:15]
	s_mov_b32 m0, s11
	v_readfirstlane_b32 s11, v0
	global_load_lds_dwordx4 v[2:3], off
	v_lshl_add_u64 v[2:3], v[6:7], 0, s[12:13]
	s_mov_b32 m0, s11
	v_readfirstlane_b32 s11, v14
	global_load_lds_dwordx4 v[2:3], off
	v_bfe_u32 v0, v14, 4, 2
	v_lshrrev_b32_e32 v2, 1, v14
	v_bfe_u32 v3, v14, 1, 3
	s_lshl_b32 s12, s11, 7
	v_lshlrev_b32_e32 v4, 7, v14
	s_lshl_b32 s11, s11, 6
	s_and_b32 s12, s12, 0x2000
	v_and_b32_e32 v4, 0x780, v4
	v_bitop3_b32 v2, v2, v0, 7 bitop3:0x6c
	s_and_b32 s11, s11, 0xffffe000
	v_bitop3_b32 v0, v0, v3, 4 bitop3:0x36
	v_or_b32_e32 v50, s12, v4
	v_lshlrev_b32_e32 v18, 4, v2
	v_or_b32_e32 v34, s11, v4
	v_lshlrev_b32_e32 v0, 4, v0
	v_or_b32_e32 v102, v18, v34
	v_or_b32_e32 v103, v18, v50
	v_or_b32_e32 v110, v0, v34
	v_or_b32_e32 v0, v0, v50
	ds_read_b128 v[2:5], v102
	ds_read_b128 v[6:9], v102 offset:2048
	ds_read_b128 v[10:13], v102 offset:4096
	ds_read_b128 v[14:17], v102 offset:6144
	ds_read_b128 v[18:21], v103 offset:16384
	ds_read_b128 v[22:25], v103 offset:18432
	ds_read_b128 v[26:29], v103 offset:20480
	ds_read_b128 v[30:33], v103 offset:22528
	ds_read_b128 v[34:37], v110
	ds_read_b128 v[38:41], v110 offset:2048
	ds_read_b128 v[42:45], v110 offset:4096
	ds_read_b128 v[46:49], v110 offset:6144
	ds_read_b128 v[50:53], v0 offset:16384
	ds_read_b128 v[54:57], v0 offset:18432
	ds_read_b128 v[58:61], v0 offset:20480
	ds_read_b128 v[62:65], v0 offset:22528
	v_readfirstlane_b32 s11, v66
	s_setprio 1
	s_waitcnt lgkmcnt(8)
; #define MFMA16(a, b, c) __builtin_amdgcn_mfma_f32_16x16x32_bf16((a), (b), (c), 0, 0, 0)
; DI void gemm_tile(const bf16_t* __restrict__ A, int lda, const bf16_t* __restrict__ Bt, int ldb, int bvalid, int K, f32x4 (&acc)[4][4], char* lds, bool preloaded = false) {
;     ...
;   auto compute = [&](int st) {
;     const char* base = lds + st * 32768;
;     bf16x8 af[2][4], bfr[2][4];
; #pragma unroll
;     for (int s = 0; s < 2; ++s) {
;       const int ch = ((4 * s + fq) ^ fx) << 4;
; #pragma unroll
;       for (int mi = 0; mi < 4; ++mi) af[s][mi] = *(const bf16x8*)(base + (wm * 64 + mi * 16 + fr) * 128 + ch);
; #pragma unroll
;       for (int ni = 0; ni < 4; ++ni) bfr[s][ni] = *(const bf16x8*)(base + 16384 + (wn * 64 + ni * 16 + fr) * 128 + ch);
;     }
;     __builtin_amdgcn_s_setprio(1);
; #pragma unroll
;     for (int s = 0; s < 2; ++s)
; #pragma unroll
;       for (int mi = 0; mi < 4; ++mi)
; #pragma unroll
;         for (int ni = 0; ni < 4; ++ni) acc[mi][ni] = MFMA16(af[s][mi], bfr[s][ni], acc[mi][ni]);
;     __builtin_amdgcn_s_setprio(0);
;   };
;   const int nk = K >> 6;
;   if (!preloaded) { GLDS(0, 0) }
;   __syncthreads();
;   for (int kt = 0; kt < nk; ++kt) {
;     if (kt + 1 < nk) { GLDS((kt + 1) & 1, (kt + 1) << 6) }
;     compute(kt & 1);
;     __syncthreads();
;   }
; DI void mix_tile(const P& p, int layer, int tile, char* lds) {
;     ...
;   const int wm = wave >> 1, wn = wave & 1, fr = lane & 15, fq = lane >> 4;
;   float* stg = (float*)lds;
;   stage_acc(acc, stg, wm, wn, fr, fq);
;   __syncthreads();
	v_mfma_f32_16x16x32_bf16 v[66:69], v[2:5], v[18:21], 0
	v_mfma_f32_16x16x32_bf16 v[70:73], v[2:5], v[22:25], 0
	v_mfma_f32_16x16x32_bf16 v[74:77], v[2:5], v[26:29], 0
	v_mfma_f32_16x16x32_bf16 v[2:5], v[2:5], v[30:33], 0
	v_mfma_f32_16x16x32_bf16 v[78:81], v[6:9], v[18:21], 0
	v_mfma_f32_16x16x32_bf16 v[82:85], v[6:9], v[22:25], 0
	v_mfma_f32_16x16x32_bf16 v[86:89], v[6:9], v[26:29], 0
	v_mfma_f32_16x16x32_bf16 v[6:9], v[6:9], v[30:33], 0
	v_mfma_f32_16x16x32_bf16 v[90:93], v[10:13], v[18:21], 0
	v_mfma_f32_16x16x32_bf16 v[94:97], v[10:13], v[22:25], 0
	v_mfma_f32_16x16x32_bf16 v[98:101], v[10:13], v[26:29], 0
	v_mfma_f32_16x16x32_bf16 v[10:13], v[10:13], v[30:33], 0
	v_mfma_f32_16x16x32_bf16 v[18:21], v[14:17], v[18:21], 0
	v_mfma_f32_16x16x32_bf16 v[22:25], v[14:17], v[22:25], 0
	v_mfma_f32_16x16x32_bf16 v[26:29], v[14:17], v[26:29], 0
	v_mfma_f32_16x16x32_bf16 v[14:17], v[14:17], v[30:33], 0
	s_waitcnt lgkmcnt(0)
	v_mfma_f32_16x16x32_bf16 v[30:33], v[34:37], v[50:53], v[66:69]
	v_mfma_f32_16x16x32_bf16 v[66:69], v[34:37], v[54:57], v[70:73]
	v_mfma_f32_16x16x32_bf16 v[70:73], v[34:37], v[58:61], v[74:77]
	v_mfma_f32_16x16x32_bf16 v[2:5], v[34:37], v[62:65], v[2:5]
	v_mfma_f32_16x16x32_bf16 v[34:37], v[38:41], v[50:53], v[78:81]
	v_mfma_f32_16x16x32_bf16 v[74:77], v[38:41], v[54:57], v[82:85]
	v_mfma_f32_16x16x32_bf16 v[78:81], v[38:41], v[58:61], v[86:89]
	v_mfma_f32_16x16x32_bf16 v[6:9], v[38:41], v[62:65], v[6:9]
	v_mfma_f32_16x16x32_bf16 v[38:41], v[42:45], v[50:53], v[90:93]
	v_mfma_f32_16x16x32_bf16 v[82:85], v[42:45], v[54:57], v[94:97]
	v_mfma_f32_16x16x32_bf16 v[86:89], v[42:45], v[58:61], v[98:101]
	v_mfma_f32_16x16x32_bf16 v[10:13], v[42:45], v[62:65], v[10:13]
	v_mfma_f32_16x16x32_bf16 v[18:21], v[46:49], v[50:53], v[18:21]
	v_mfma_f32_16x16x32_bf16 v[22:25], v[46:49], v[54:57], v[22:25]
	v_mfma_f32_16x16x32_bf16 v[26:29], v[46:49], v[58:61], v[26:29]
	v_mfma_f32_16x16x32_bf16 v[14:17], v[46:49], v[62:65], v[14:17]
	s_setprio 0
	s_waitcnt vmcnt(0)
	s_barrier
	ds_read_b128 v[42:45], v102 offset:32768
	ds_read_b128 v[46:49], v102 offset:34816
	ds_read_b128 v[50:53], v102 offset:36864
	ds_read_b128 v[54:57], v102 offset:38912
	ds_read_b128 v[58:61], v103 offset:49152
	ds_read_b128 v[62:65], v103 offset:51200
	ds_read_b128 v[90:93], v103 offset:53248
	ds_read_b128 v[94:97], v103 offset:55296
	ds_read_b128 v[98:101], v110 offset:32768
	ds_read_b128 v[102:105], v110 offset:34816
	ds_read_b128 v[106:109], v110 offset:36864
	ds_read_b128 v[110:113], v110 offset:38912
	ds_read_b128 v[114:117], v0 offset:49152
	ds_read_b128 v[118:121], v0 offset:51200
	ds_read_b128 v[122:125], v0 offset:53248
	ds_read_b128 v[126:129], v0 offset:55296
	s_setprio 1
	s_waitcnt lgkmcnt(11)
	v_mfma_f32_16x16x32_bf16 v[30:33], v[42:45], v[58:61], v[30:33]
	s_waitcnt lgkmcnt(10)
	v_mfma_f32_16x16x32_bf16 v[66:69], v[42:45], v[62:65], v[66:69]
	s_waitcnt lgkmcnt(9)
	v_mfma_f32_16x16x32_bf16 v[70:73], v[42:45], v[90:93], v[70:73]
	s_waitcnt lgkmcnt(8)
	v_mfma_f32_16x16x32_bf16 v[2:5], v[42:45], v[94:97], v[2:5]
	v_mfma_f32_16x16x32_bf16 v[34:37], v[46:49], v[58:61], v[34:37]
	v_mfma_f32_16x16x32_bf16 v[42:45], v[46:49], v[62:65], v[74:77]
	v_mfma_f32_16x16x32_bf16 v[74:77], v[46:49], v[90:93], v[78:81]
	v_mfma_f32_16x16x32_bf16 v[6:9], v[46:49], v[94:97], v[6:9]
	v_mfma_f32_16x16x32_bf16 v[38:41], v[50:53], v[58:61], v[38:41]
	v_mfma_f32_16x16x32_bf16 v[46:49], v[50:53], v[62:65], v[82:85]
	v_mfma_f32_16x16x32_bf16 v[78:81], v[50:53], v[90:93], v[86:89]
	v_mfma_f32_16x16x32_bf16 v[10:13], v[50:53], v[94:97], v[10:13]
	v_mfma_f32_16x16x32_bf16 v[18:21], v[54:57], v[58:61], v[18:21]
	v_mfma_f32_16x16x32_bf16 v[22:25], v[54:57], v[62:65], v[22:25]
	v_mfma_f32_16x16x32_bf16 v[26:29], v[54:57], v[90:93], v[26:29]
	v_mfma_f32_16x16x32_bf16 v[14:17], v[54:57], v[94:97], v[14:17]
	s_waitcnt lgkmcnt(3)
	v_mfma_f32_16x16x32_bf16 v[30:33], v[98:101], v[114:117], v[30:33]
	s_waitcnt lgkmcnt(2)
	v_mfma_f32_16x16x32_bf16 v[50:53], v[98:101], v[118:121], v[66:69]
	s_waitcnt lgkmcnt(1)
	v_mfma_f32_16x16x32_bf16 v[54:57], v[98:101], v[122:125], v[70:73]
	s_waitcnt lgkmcnt(0)
	v_mfma_f32_16x16x32_bf16 v[2:5], v[98:101], v[126:129], v[2:5]
	v_mfma_f32_16x16x32_bf16 v[34:37], v[102:105], v[114:117], v[34:37]
	v_mfma_f32_16x16x32_bf16 v[42:45], v[102:105], v[118:121], v[42:45]
	v_mfma_f32_16x16x32_bf16 v[58:61], v[102:105], v[122:125], v[74:77]
	v_mfma_f32_16x16x32_bf16 v[6:9], v[102:105], v[126:129], v[6:9]
	v_mfma_f32_16x16x32_bf16 v[38:41], v[106:109], v[114:117], v[38:41]
	v_mfma_f32_16x16x32_bf16 v[46:49], v[106:109], v[118:121], v[46:49]
	v_mfma_f32_16x16x32_bf16 v[62:65], v[106:109], v[122:125], v[78:81]
	v_mfma_f32_16x16x32_bf16 v[10:13], v[106:109], v[126:129], v[10:13]
	v_mfma_f32_16x16x32_bf16 v[18:21], v[110:113], v[114:117], v[18:21]
	v_mfma_f32_16x16x32_bf16 v[22:25], v[110:113], v[118:121], v[22:25]
	v_mfma_f32_16x16x32_bf16 v[26:29], v[110:113], v[122:125], v[26:29]
	v_mfma_f32_16x16x32_bf16 v[14:17], v[110:113], v[126:129], v[14:17]
	s_setprio 0
	s_ashr_i32 s14, s11, 7
	s_bfe_u32 s11, s11, 0x10006
	v_and_b32_e32 v68, 15, v130
	v_bfe_u32 v69, v130, 4, 2
	v_lshlrev_b32_e32 v0, 2, v69
	s_lshl_b32 s15, s11, 8
	v_lshlrev_b32_e32 v70, 2, v68
	v_lshl_or_b32 v66, s14, 6, v0
	v_or_b32_e32 v0, s15, v70
	v_mad_u64_u32 v[66:67], s[12:13], v66, s56, v[0:1]
	v_add_u32_e32 v0, 0x400, v66
	s_barrier
; DI unsigned pk2(float lo, float hi) { unsigned r; asm("v_cvt_pk_bf16_f32 %0, %1, %2" : "=v"(r) : "v"(lo), "v"(hi)); return r; }
; DI void stage_acc(const f32x4 (&acc)[4][4], float* tile, int wm, int wn, int fr, int fq) {
; #pragma unroll
;   for (int mi = 0; mi < 4; ++mi)
; #pragma unroll
;     for (int ni = 0; ni < 4; ++ni)
; #pragma unroll
;       for (int j = 0; j < 4; ++j) tile[(wm * 64 + mi * 16 + fq * 4 + j) * EPS + wn * 64 + ni * 16 + fr] = acc[mi][ni][j];
; DI void mix_tile(const P& p, int layer, int tile, char* lds) {
;     ...
;   const int col = g * 128 + wn * 64 + fr * 4;
;   const f32x4 sc = *(const f32x4*)(p.pool_scale + layer * 512 + col);
;   u32x2 zr[16];
; #pragma unroll
;   for (int ps = 0; ps < 16; ++ps) zr[ps] = *(const u32x2*)((const bf16_t*)(p.ws + W_ZP) + (size_t)(row0 + ps * 8 + wm * 4 + fq) * 512 + col);
; #pragma unroll
;   for (int ps = 0; ps < 16; ++ps) {
;     const int lr = ps * 8 + wm * 4 + fq;
;     const f32x4 v = *(const f32x4*)(stg + lr * EPS + wn * 64 + fr * 4) * sc;
;     const u32x2 z = zr[ps];
;     *(u32x2*)(PA + (size_t)(row0 + lr) * 512 + col) = u32x2{pk2(v.x * __uint_as_float(z.x << 16), v.y * __uint_as_float(z.x & 0xffff0000u)), pk2(v.z * __uint_as_float(z.y << 16), v.w * __uint_as_float(z.y & 0xffff0000u))};
	ds_write2_b32 v66, v30, v50 offset1:16
	ds_write2_b32 v66, v31, v51 offset0:132 offset1:148
	ds_write2_b32 v0, v32, v52 offset0:8 offset1:24
	ds_write2_b32 v0, v33, v53 offset0:140 offset1:156
	ds_write2_b32 v66, v54, v2 offset0:32 offset1:48
	ds_write2_b32 v66, v55, v3 offset0:164 offset1:180
	ds_write2_b32 v0, v56, v4 offset0:40 offset1:56
	ds_write2_b32 v0, v57, v5 offset0:172 offset1:188
	v_add_u32_e32 v0, 0x2000, v66
	v_add_u32_e32 v2, 0x2400, v66
	ds_write2_b32 v0, v34, v42 offset0:64 offset1:80
	ds_write2_b32 v0, v35, v43 offset0:196 offset1:212
	ds_write2_b32 v2, v36, v44 offset0:72 offset1:88
	ds_write2_b32 v2, v37, v45 offset0:204 offset1:220
	ds_write2_b32 v0, v58, v6 offset0:96 offset1:112
	ds_write2_b32 v0, v59, v7 offset0:228 offset1:244
	ds_write2_b32 v2, v60, v8 offset0:104 offset1:120
	ds_write2_b32 v2, v61, v9 offset0:236 offset1:252
	v_add_u32_e32 v0, 0x4000, v66
	v_add_u32_e32 v2, 0x4400, v66
	v_add_u32_e32 v3, 0x4800, v66
	ds_write2_b32 v0, v38, v46 offset0:128 offset1:144
	ds_write2_b32 v2, v39, v47 offset0:4 offset1:20
	ds_write2_b32 v2, v40, v48 offset0:136 offset1:152
	ds_write2_b32 v3, v41, v49 offset0:12 offset1:28
	ds_write2_b32 v0, v62, v10 offset0:160 offset1:176
	ds_write2_b32 v2, v63, v11 offset0:36 offset1:52
	ds_write2_b32 v2, v64, v12 offset0:168 offset1:184
	ds_write2_b32 v3, v65, v13 offset0:44 offset1:60
	v_add_u32_e32 v0, 0x6000, v66
	v_add_u32_e32 v2, 0x6400, v66
	v_add_u32_e32 v3, 0x6800, v66
	ds_write2_b32 v0, v18, v22 offset0:192 offset1:208
	ds_write2_b32 v2, v19, v23 offset0:68 offset1:84
	ds_write2_b32 v2, v20, v24 offset0:200 offset1:216
	ds_write2_b32 v3, v21, v25 offset0:76 offset1:92
	ds_write2_b32 v0, v26, v14 offset0:224 offset1:240
	ds_write2_b32 v2, v27, v15 offset0:100 offset1:116
	ds_write2_b32 v2, v28, v16 offset0:232 offset1:248
	ds_write2_b32 v3, v29, v17 offset0:108 offset1:124
	v_or_b32_e32 v0, s25, v70
	v_lshl_or_b32 v0, s11, 6, v0
	s_lshl_b32 s11, s14, 2
	v_or_b32_e32 v6, s10, v69
	v_add_u32_e32 v6, s11, v6
	v_readlane_b32 s12, v240, 48
	v_lshlrev_b32_e32 v2, 2, v0
	v_lshlrev_b32_e32 v0, 1, v0
	v_readlane_b32 s13, v240, 49
	v_ashrrev_i32_e32 v7, 31, v6
	v_lshlrev_b64 v[6:7], 10, v[6:7]
	v_lshl_add_u64 v[10:11], s[12:13], 0, v[0:1]
	v_lshl_add_u64 v[12:13], v[10:11], 0, v[6:7]
	s_waitcnt lgkmcnt(0)
	s_barrier
	global_load_dwordx4 v[2:5], v2, s[0:1]
	v_add_co_u32_e32 v8, vcc, s17, v12
	global_load_dwordx2 v[16:17], v[12:13], off
	s_nop 0
	v_addc_co_u32_e32 v9, vcc, 0, v13, vcc
	global_load_dwordx2 v[50:51], v[8:9], off
	s_mov_b64 s[12:13], 0x4000
	v_lshl_add_u64 v[52:53], v[6:7], 0, s[12:13]
	s_movk_i32 s12, 0x6000
	v_lshl_add_u64 v[8:9], v[10:11], 0, v[52:53]
	v_add_co_u32_e32 v14, vcc, s12, v12
	s_mov_b32 s12, 0xa000
	s_nop 0
	v_addc_co_u32_e32 v15, vcc, 0, v13, vcc
	global_load_dwordx2 v[54:55], v[8:9], off
	global_load_dwordx2 v[56:57], v[14:15], off
	v_add_co_u32_e32 v14, vcc, s12, v12
	s_mov_b64 s[12:13], 0xc000
	v_lshl_add_u64 v[58:59], v[6:7], 0, s[36:37]
	v_addc_co_u32_e32 v15, vcc, 0, v13, vcc
	v_lshl_add_u64 v[38:39], v[6:7], 0, s[12:13]
	s_mov_b32 s12, 0xe000
	v_lshl_add_u64 v[8:9], v[10:11], 0, v[58:59]
	v_add_co_u32_e32 v20, vcc, s12, v12
	v_lshl_add_u64 v[18:19], v[10:11], 0, v[38:39]
	s_nop 0
	v_addc_co_u32_e32 v21, vcc, 0, v13, vcc
	global_load_dwordx2 v[60:61], v[8:9], off
	global_load_dwordx2 v[62:63], v[14:15], off
	global_load_dwordx2 v[40:41], v[18:19], off
	global_load_dwordx2 v[36:37], v[20:21], off
	s_mov_b32 s12, 0x12000
	v_add_co_u32_e32 v14, vcc, s12, v12
	s_mov_b64 s[12:13], 0x14000
	v_lshl_add_u64 v[30:31], v[6:7], 0, s[38:39]
	v_addc_co_u32_e32 v15, vcc, 0, v13, vcc
	v_lshl_add_u64 v[26:27], v[6:7], 0, s[12:13]
	s_mov_b32 s12, 0x16000
	v_lshl_add_u64 v[8:9], v[10:11], 0, v[30:31]
	v_add_co_u32_e32 v20, vcc, s12, v12
	v_lshl_add_u64 v[18:19], v[10:11], 0, v[26:27]
	s_nop 0
	v_addc_co_u32_e32 v21, vcc, 0, v13, vcc
	global_load_dwordx2 v[34:35], v[8:9], off
	global_load_dwordx2 v[32:33], v[14:15], off
	global_load_dwordx2 v[28:29], v[18:19], off
	global_load_dwordx2 v[24:25], v[20:21], off
	s_mov_b32 s12, 0x1a000
	v_add_co_u32_e32 v46, vcc, s12, v12
	s_mov_b64 s[12:13], 0x1c000
	v_lshl_add_u64 v[18:19], v[6:7], 0, s[40:41]
	v_addc_co_u32_e32 v47, vcc, 0, v13, vcc
	v_lshl_add_u64 v[8:9], v[6:7], 0, s[12:13]
	s_mov_b32 s12, 0x1e000
	v_lshl_add_u64 v[20:21], v[10:11], 0, v[18:19]
	v_lshl_add_u64 v[6:7], v[10:11], 0, v[8:9]
	v_add_co_u32_e32 v10, vcc, s12, v12
	v_or_b32_e32 v64, s11, v69
	v_lshl_or_b32 v12, v68, 4, s15
	v_mad_u64_u32 v[14:15], s[12:13], v64, s56, v[12:13]
	v_addc_co_u32_e32 v11, vcc, 0, v13, vcc
	ds_read_b128 v[42:45], v14
	global_load_dwordx2 v[22:23], v[20:21], off
	s_nop 0
	global_load_dwordx2 v[20:21], v[46:47], off
	global_load_dwordx2 v[12:13], v[6:7], off
	s_nop 0
	global_load_dwordx2 v[10:11], v[10:11], off
	v_lshl_add_u64 v[6:7], s[74:75], 0, v[0:1]
	ds_read_b128 v[46:49], v14 offset:4224
	v_lshl_add_u64 v[38:39], v[6:7], 0, v[38:39]
	v_lshl_add_u64 v[30:31], v[6:7], 0, v[30:31]
	v_lshl_add_u64 v[26:27], v[6:7], 0, v[26:27]
	v_lshl_add_u64 v[18:19], v[6:7], 0, v[18:19]
	v_lshl_add_u64 v[8:9], v[6:7], 0, v[8:9]
	s_waitcnt vmcnt(16) lgkmcnt(1)
	v_pk_mul_f32 v[42:43], v[2:3], v[42:43]
	v_pk_mul_f32 v[44:45], v[4:5], v[44:45]
	s_waitcnt vmcnt(15)
	v_lshlrev_b32_e32 v0, 16, v16
	v_and_b32_e32 v15, 0xffff0000, v16
	v_mul_f32_e32 v0, v42, v0
	v_mul_f32_e32 v15, v43, v15
	v_add_u32_e32 v16, s10, v64
	v_cvt_pk_bf16_f32 v42, v0, v15
	v_lshlrev_b32_e32 v0, 16, v17
	v_and_b32_e32 v15, 0xffff0000, v17
	v_ashrrev_i32_e32 v17, 31, v16
	v_mul_f32_e32 v0, v44, v0
	v_mul_f32_e32 v15, v45, v15
	v_lshlrev_b64 v[44:45], 10, v[16:17]
	v_lshl_add_u64 v[44:45], v[6:7], 0, v[44:45]
	v_cvt_pk_bf16_f32 v43, v0, v15
	global_store_dwordx2 v[44:45], v[42:43], off
	s_waitcnt lgkmcnt(0)
; DI unsigned pk2(float lo, float hi) { unsigned r; asm("v_cvt_pk_bf16_f32 %0, %1, %2" : "=v"(r) : "v"(lo), "v"(hi)); return r; }
; DI void mix_tile(const P& p, int layer, int tile, char* lds) {
;     ...
; #pragma unroll
;   for (int ps = 0; ps < 16; ++ps) {
;     const int lr = ps * 8 + wm * 4 + fq;
;     const f32x4 v = *(const f32x4*)(stg + lr * EPS + wn * 64 + fr * 4) * sc;
;     const u32x2 z = zr[ps];
;     *(u32x2*)(PA + (size_t)(row0 + lr) * 512 + col) = u32x2{pk2(v.x * __uint_as_float(z.x << 16), v.y * __uint_as_float(z.x & 0xffff0000u)), pk2(v.z * __uint_as_float(z.y << 16), v.w * __uint_as_float(z.y & 0xffff0000u))};
;   }
	v_pk_mul_f32 v[44:45], v[2:3], v[46:47]
	s_waitcnt vmcnt(15)
	v_lshlrev_b32_e32 v0, 16, v50
	v_and_b32_e32 v15, 0xffff0000, v50
	v_mul_f32_e32 v0, v44, v0
	v_mul_f32_e32 v15, v45, v15
	v_pk_mul_f32 v[42:43], v[4:5], v[48:49]
	v_cvt_pk_bf16_f32 v46, v0, v15
	v_lshlrev_b32_e32 v0, 16, v51
	v_and_b32_e32 v15, 0xffff0000, v51
	v_mul_f32_e32 v0, v42, v0
	v_mul_f32_e32 v15, v43, v15
	v_add_u32_e32 v48, 8, v16
	ds_read_b128 v[42:45], v14 offset:8448
	v_ashrrev_i32_e32 v49, 31, v48
	v_lshlrev_b64 v[48:49], 10, v[48:49]
	v_cvt_pk_bf16_f32 v47, v0, v15
	v_lshl_add_u64 v[48:49], v[6:7], 0, v[48:49]
	global_store_dwordx2 v[48:49], v[46:47], off
	ds_read_b128 v[46:49], v14 offset:12672
	s_waitcnt lgkmcnt(1)
	v_pk_mul_f32 v[42:43], v[2:3], v[42:43]
	s_waitcnt vmcnt(15)
	v_lshlrev_b32_e32 v0, 16, v54
	v_and_b32_e32 v15, 0xffff0000, v54
	v_mul_f32_e32 v0, v42, v0
	v_mul_f32_e32 v15, v43, v15
	v_pk_mul_f32 v[44:45], v[4:5], v[44:45]
	v_cvt_pk_bf16_f32 v42, v0, v15
	v_lshlrev_b32_e32 v0, 16, v55
	v_and_b32_e32 v15, 0xffff0000, v55
	v_mul_f32_e32 v0, v44, v0
	v_mul_f32_e32 v15, v45, v15
	v_lshl_add_u64 v[44:45], v[6:7], 0, v[52:53]
	v_cvt_pk_bf16_f32 v43, v0, v15
	global_store_dwordx2 v[44:45], v[42:43], off
	s_waitcnt lgkmcnt(0)
	v_pk_mul_f32 v[44:45], v[2:3], v[46:47]
	s_waitcnt vmcnt(15)
	v_lshlrev_b32_e32 v0, 16, v56
	v_and_b32_e32 v15, 0xffff0000, v56
	v_mul_f32_e32 v0, v44, v0
	v_mul_f32_e32 v15, v45, v15
	v_pk_mul_f32 v[42:43], v[4:5], v[48:49]
	v_cvt_pk_bf16_f32 v46, v0, v15
	v_lshlrev_b32_e32 v0, 16, v57
	v_and_b32_e32 v15, 0xffff0000, v57
	v_mul_f32_e32 v0, v42, v0
	v_mul_f32_e32 v15, v43, v15
	v_add_u32_e32 v48, 24, v16
	ds_read_b128 v[42:45], v14 offset:16896
	v_ashrrev_i32_e32 v49, 31, v48
	v_lshlrev_b64 v[48:49], 10, v[48:49]
	v_cvt_pk_bf16_f32 v47, v0, v15
	v_lshl_add_u64 v[48:49], v[6:7], 0, v[48:49]
	global_store_dwordx2 v[48:49], v[46:47], off
	ds_read_b128 v[46:49], v14 offset:21120
	s_waitcnt lgkmcnt(1)
	v_pk_mul_f32 v[42:43], v[2:3], v[42:43]
	s_waitcnt vmcnt(15)
	v_lshlrev_b32_e32 v0, 16, v60
	v_and_b32_e32 v15, 0xffff0000, v60
	v_mul_f32_e32 v0, v42, v0
	v_mul_f32_e32 v15, v43, v15
	v_pk_mul_f32 v[44:45], v[4:5], v[44:45]
	v_cvt_pk_bf16_f32 v42, v0, v15
	v_lshlrev_b32_e32 v0, 16, v61
	v_and_b32_e32 v15, 0xffff0000, v61
	v_mul_f32_e32 v0, v44, v0
	v_mul_f32_e32 v15, v45, v15
	v_lshl_add_u64 v[44:45], v[6:7], 0, v[58:59]
	v_cvt_pk_bf16_f32 v43, v0, v15
	global_store_dwordx2 v[44:45], v[42:43], off
	s_waitcnt lgkmcnt(0)
	v_pk_mul_f32 v[44:45], v[2:3], v[46:47]
	s_waitcnt vmcnt(15)
	v_lshlrev_b32_e32 v0, 16, v62
	v_and_b32_e32 v15, 0xffff0000, v62
	v_mul_f32_e32 v0, v44, v0
	v_mul_f32_e32 v15, v45, v15
	v_pk_mul_f32 v[42:43], v[4:5], v[48:49]
	v_cvt_pk_bf16_f32 v46, v0, v15
	v_lshlrev_b32_e32 v0, 16, v63
	v_and_b32_e32 v15, 0xffff0000, v63
	v_mul_f32_e32 v0, v42, v0
	v_mul_f32_e32 v15, v43, v15
	v_add_u32_e32 v48, 40, v16
	ds_read_b128 v[42:45], v14 offset:25344
	v_ashrrev_i32_e32 v49, 31, v48
	v_lshlrev_b64 v[48:49], 10, v[48:49]
	v_cvt_pk_bf16_f32 v47, v0, v15
	v_lshl_add_u64 v[48:49], v[6:7], 0, v[48:49]
	global_store_dwordx2 v[48:49], v[46:47], off
	ds_read_b128 v[46:49], v14 offset:29568
	s_waitcnt lgkmcnt(1)
	v_pk_mul_f32 v[42:43], v[2:3], v[42:43]
	s_waitcnt vmcnt(15)
	v_lshlrev_b32_e32 v0, 16, v40
	v_and_b32_e32 v15, 0xffff0000, v40
	v_mul_f32_e32 v0, v42, v0
	v_mul_f32_e32 v15, v43, v15
	v_pk_mul_f32 v[44:45], v[4:5], v[44:45]
	v_cvt_pk_bf16_f32 v40, v0, v15
	v_lshlrev_b32_e32 v0, 16, v41
	v_and_b32_e32 v15, 0xffff0000, v41
	v_mul_f32_e32 v0, v44, v0
	v_mul_f32_e32 v15, v45, v15
	v_cvt_pk_bf16_f32 v41, v0, v15
	global_store_dwordx2 v[38:39], v[40:41], off
	s_waitcnt lgkmcnt(0)
	v_pk_mul_f32 v[40:41], v[2:3], v[46:47]
	s_waitcnt vmcnt(15)
	v_lshlrev_b32_e32 v0, 16, v36
	v_and_b32_e32 v15, 0xffff0000, v36
	v_mul_f32_e32 v0, v40, v0
	v_mul_f32_e32 v15, v41, v15
	v_pk_mul_f32 v[38:39], v[4:5], v[48:49]
	v_cvt_pk_bf16_f32 v40, v0, v15
	v_lshlrev_b32_e32 v0, 16, v37
	v_and_b32_e32 v15, 0xffff0000, v37
	v_mul_f32_e32 v0, v38, v0
	v_mul_f32_e32 v15, v39, v15
	v_add_u32_e32 v42, 56, v16
	ds_read_b128 v[36:39], v14 offset:33792
	v_ashrrev_i32_e32 v43, 31, v42
	v_lshlrev_b64 v[42:43], 10, v[42:43]
	v_cvt_pk_bf16_f32 v41, v0, v15
	v_lshl_add_u64 v[42:43], v[6:7], 0, v[42:43]
	global_store_dwordx2 v[42:43], v[40:41], off
	ds_read_b128 v[40:43], v14 offset:38016
	s_waitcnt lgkmcnt(1)
	v_pk_mul_f32 v[36:37], v[2:3], v[36:37]
	s_waitcnt vmcnt(15)
; DI unsigned pk2(float lo, float hi) { unsigned r; asm("v_cvt_pk_bf16_f32 %0, %1, %2" : "=v"(r) : "v"(lo), "v"(hi)); return r; }
; DI void mix_tile(const P& p, int layer, int tile, char* lds) {
;     ...
; #pragma unroll
;   for (int ps = 0; ps < 16; ++ps) {
;     const int lr = ps * 8 + wm * 4 + fq;
;     const f32x4 v = *(const f32x4*)(stg + lr * EPS + wn * 64 + fr * 4) * sc;
;     const u32x2 z = zr[ps];
;     *(u32x2*)(PA + (size_t)(row0 + lr) * 512 + col) = u32x2{pk2(v.x * __uint_as_float(z.x << 16), v.y * __uint_as_float(z.x & 0xffff0000u)), pk2(v.z * __uint_as_float(z.y << 16), v.w * __uint_as_float(z.y & 0xffff0000u))};
;   }
;   __syncthreads();
	v_lshlrev_b32_e32 v0, 16, v34
	v_and_b32_e32 v15, 0xffff0000, v34
	v_mul_f32_e32 v0, v36, v0
	v_mul_f32_e32 v15, v37, v15
	v_pk_mul_f32 v[38:39], v[4:5], v[38:39]
	v_cvt_pk_bf16_f32 v34, v0, v15
	v_lshlrev_b32_e32 v0, 16, v35
	v_and_b32_e32 v15, 0xffff0000, v35
	v_mul_f32_e32 v0, v38, v0
	v_mul_f32_e32 v15, v39, v15
	v_cvt_pk_bf16_f32 v35, v0, v15
	global_store_dwordx2 v[30:31], v[34:35], off
	s_waitcnt lgkmcnt(0)
	v_pk_mul_f32 v[34:35], v[2:3], v[40:41]
	s_waitcnt vmcnt(15)
	v_lshlrev_b32_e32 v0, 16, v32
	v_and_b32_e32 v15, 0xffff0000, v32
	v_mul_f32_e32 v0, v34, v0
	v_mul_f32_e32 v15, v35, v15
	v_pk_mul_f32 v[30:31], v[4:5], v[42:43]
	v_cvt_pk_bf16_f32 v34, v0, v15
	v_lshlrev_b32_e32 v0, 16, v33
	v_and_b32_e32 v15, 0xffff0000, v33
	v_mul_f32_e32 v0, v30, v0
	v_mul_f32_e32 v15, v31, v15
	v_add_u32_e32 v36, 0x48, v16
	ds_read_b128 v[30:33], v14 offset:42240
	v_ashrrev_i32_e32 v37, 31, v36
	v_lshlrev_b64 v[36:37], 10, v[36:37]
	v_cvt_pk_bf16_f32 v35, v0, v15
	v_lshl_add_u64 v[36:37], v[6:7], 0, v[36:37]
	global_store_dwordx2 v[36:37], v[34:35], off
	ds_read_b128 v[34:37], v14 offset:46464
	s_waitcnt lgkmcnt(1)
	v_pk_mul_f32 v[30:31], v[2:3], v[30:31]
	s_waitcnt vmcnt(15)
	v_lshlrev_b32_e32 v0, 16, v28
	v_and_b32_e32 v15, 0xffff0000, v28
	v_mul_f32_e32 v0, v30, v0
	v_mul_f32_e32 v15, v31, v15
	v_pk_mul_f32 v[32:33], v[4:5], v[32:33]
	v_cvt_pk_bf16_f32 v28, v0, v15
	v_lshlrev_b32_e32 v0, 16, v29
	v_and_b32_e32 v15, 0xffff0000, v29
	v_mul_f32_e32 v0, v32, v0
	v_mul_f32_e32 v15, v33, v15
	v_cvt_pk_bf16_f32 v29, v0, v15
	global_store_dwordx2 v[26:27], v[28:29], off
	s_waitcnt lgkmcnt(0)
	v_pk_mul_f32 v[28:29], v[2:3], v[34:35]
	s_waitcnt vmcnt(15)
	v_lshlrev_b32_e32 v0, 16, v24
	v_and_b32_e32 v15, 0xffff0000, v24
	v_mul_f32_e32 v0, v28, v0
	v_mul_f32_e32 v15, v29, v15
	v_pk_mul_f32 v[26:27], v[4:5], v[36:37]
	v_cvt_pk_bf16_f32 v28, v0, v15
	v_lshlrev_b32_e32 v0, 16, v25
	v_and_b32_e32 v15, 0xffff0000, v25
	v_mul_f32_e32 v0, v26, v0
	v_mul_f32_e32 v15, v27, v15
	v_add_u32_e32 v30, 0x58, v16
	ds_read_b128 v[24:27], v14 offset:50688
	v_ashrrev_i32_e32 v31, 31, v30
	v_lshlrev_b64 v[30:31], 10, v[30:31]
	v_cvt_pk_bf16_f32 v29, v0, v15
	v_lshl_add_u64 v[30:31], v[6:7], 0, v[30:31]
	global_store_dwordx2 v[30:31], v[28:29], off
	ds_read_b128 v[28:31], v14 offset:54912
	s_waitcnt lgkmcnt(1)
	v_pk_mul_f32 v[24:25], v[2:3], v[24:25]
	s_waitcnt vmcnt(15)
	v_lshlrev_b32_e32 v0, 16, v22
	v_and_b32_e32 v15, 0xffff0000, v22
	v_mul_f32_e32 v0, v24, v0
	v_mul_f32_e32 v15, v25, v15
	v_pk_mul_f32 v[26:27], v[4:5], v[26:27]
	v_cvt_pk_bf16_f32 v22, v0, v15
	v_lshlrev_b32_e32 v0, 16, v23
	v_and_b32_e32 v15, 0xffff0000, v23
	v_mul_f32_e32 v0, v26, v0
	v_mul_f32_e32 v15, v27, v15
	v_cvt_pk_bf16_f32 v23, v0, v15
	global_store_dwordx2 v[18:19], v[22:23], off
	s_waitcnt lgkmcnt(0)
	v_pk_mul_f32 v[22:23], v[2:3], v[28:29]
	s_waitcnt vmcnt(15)
	v_lshlrev_b32_e32 v0, 16, v20
	v_and_b32_e32 v15, 0xffff0000, v20
	v_mul_f32_e32 v0, v22, v0
	v_mul_f32_e32 v15, v23, v15
	v_pk_mul_f32 v[18:19], v[4:5], v[30:31]
	v_cvt_pk_bf16_f32 v22, v0, v15
	v_lshlrev_b32_e32 v0, 16, v21
	v_and_b32_e32 v15, 0xffff0000, v21
	v_mul_f32_e32 v0, v18, v0
	v_mul_f32_e32 v15, v19, v15
	v_add_u32_e32 v24, 0x68, v16
	ds_read_b128 v[18:21], v14 offset:59136
	v_ashrrev_i32_e32 v25, 31, v24
	v_lshlrev_b64 v[24:25], 10, v[24:25]
	v_cvt_pk_bf16_f32 v23, v0, v15
	v_lshl_add_u64 v[24:25], v[6:7], 0, v[24:25]
	global_store_dwordx2 v[24:25], v[22:23], off
	ds_read_b128 v[22:25], v14 offset:63360
	s_waitcnt lgkmcnt(1)
	v_pk_mul_f32 v[18:19], v[2:3], v[18:19]
	s_waitcnt vmcnt(15)
	v_lshlrev_b32_e32 v0, 16, v12
	v_and_b32_e32 v12, 0xffff0000, v12
	v_mul_f32_e32 v0, v18, v0
	v_mul_f32_e32 v12, v19, v12
	v_pk_mul_f32 v[14:15], v[4:5], v[20:21]
	v_cvt_pk_bf16_f32 v12, v0, v12
	v_lshlrev_b32_e32 v0, 16, v13
	v_and_b32_e32 v13, 0xffff0000, v13
	v_mul_f32_e32 v0, v14, v0
	v_mul_f32_e32 v13, v15, v13
	v_cvt_pk_bf16_f32 v13, v0, v13
	s_waitcnt lgkmcnt(0)
	v_pk_mul_f32 v[2:3], v[2:3], v[22:23]
	s_waitcnt vmcnt(14)
	v_lshlrev_b32_e32 v0, 16, v10
	v_mul_f32_e32 v0, v2, v0
	v_and_b32_e32 v2, 0xffff0000, v10
	v_mul_f32_e32 v2, v3, v2
	v_pk_mul_f32 v[4:5], v[4:5], v[24:25]
	v_cvt_pk_bf16_f32 v2, v0, v2
	v_lshlrev_b32_e32 v0, 16, v11
	v_mul_f32_e32 v0, v4, v0
	v_and_b32_e32 v3, 0xffff0000, v11
	v_add_u32_e32 v4, 0x78, v16
	v_mul_f32_e32 v3, v5, v3
	v_ashrrev_i32_e32 v5, 31, v4
	v_lshlrev_b64 v[4:5], 10, v[4:5]
	v_lshl_add_u64 v[4:5], v[6:7], 0, v[4:5]
	global_store_dwordx2 v[8:9], v[12:13], off
	v_cvt_pk_bf16_f32 v3, v0, v3
	global_store_dwordx2 v[4:5], v[2:3], off
	s_barrier
	s_mov_b64 s[10:11], 0

; DI void gemm_tile(const bf16_t* __restrict__ A, int lda, const bf16_t* __restrict__ Bt, int ldb, int bvalid, int K, f32x4 (&acc)[4][4], char* lds, bool preloaded = false) {
;     ...
;   for (int kt = 0; kt < nk; ++kt) {
;     if (kt + 1 < nk) { GLDS((kt + 1) & 1, (kt + 1) << 6) }
;     compute(kt & 1);
;     __syncthreads();
;   }
; DI void phaseA_tile(const P& p, int layer, int mt, int nt, char* lds) {
;     ...
;   gemm_tile((const bf16_t*)(p.ws + W_XB) + (size_t)row0 * DM, DM, (const bf16_t*)(p.ws + W_WIN) + ((size_t)layer * NP + col0) * 1024, 1024, bvalid, 1024, acc, lds);
.LBB0_1594:
	s_add_i32 s5, s4, 0x8000
	s_and_b32 s7, s5, 0x8000
	v_add_u32_e32 v0, s7, v93
	v_lshl_add_u64 v[98:99], v[82:83], 0, s[0:1]
	v_add_u32_e32 v102, 0x4000, v0
	v_readfirstlane_b32 s7, v0
	v_lshl_add_u64 v[100:101], v[98:99], 0, s[8:9]
	s_mov_b32 m0, s7
	v_readfirstlane_b32 s7, v102
	v_add_u32_e32 v102, 0x1000, v0
	global_load_lds_dwordx4 v[100:101], off
	v_lshl_add_u64 v[100:101], v[84:85], 0, s[0:1]
	s_mov_b32 m0, s7
	v_readfirstlane_b32 s7, v102
	v_add_u32_e32 v102, 0x5000, v0
	global_load_lds_dwordx4 v[100:101], off
	v_lshl_add_u64 v[100:101], v[98:99], 0, s[10:11]
	s_mov_b32 m0, s7
	v_readfirstlane_b32 s7, v102
	v_add_u32_e32 v102, 0x2000, v0
	global_load_lds_dwordx4 v[100:101], off
	v_lshl_add_u64 v[100:101], v[86:87], 0, s[0:1]
	s_mov_b32 m0, s7
	v_readfirstlane_b32 s7, v102
	v_add_u32_e32 v102, 0x6000, v0
	global_load_lds_dwordx4 v[100:101], off
	v_lshl_add_u64 v[100:101], v[98:99], 0, s[12:13]
	s_mov_b32 m0, s7
	v_readfirstlane_b32 s7, v102
	global_load_lds_dwordx4 v[100:101], off
	v_lshl_add_u64 v[100:101], v[88:89], 0, s[0:1]
	s_mov_b32 m0, s7
	v_lshl_add_u64 v[98:99], v[98:99], 0, s[14:15]
	global_load_lds_dwordx4 v[100:101], off
	v_add_u32_e32 v100, 0x3000, v0
	v_add_u32_e32 v0, 0x7000, v0
	v_readfirstlane_b32 s7, v100
	s_mov_b32 m0, s7
	v_readfirstlane_b32 s7, v0
	global_load_lds_dwordx4 v[98:99], off
	v_lshl_add_u64 v[98:99], v[90:91], 0, s[0:1]
	s_mov_b32 m0, s7
	s_and_b32 s4, s4, 0x8000
	global_load_lds_dwordx4 v[98:99], off
	v_or_b32_e32 v0, s4, v97
	v_add_u32_e32 v110, v0, v96
	v_add_u32_e32 v0, v0, v94
	ds_read_b128 v[98:101], v110
	ds_read_b128 v[102:105], v110 offset:2048
	ds_read_b128 v[106:109], v110 offset:4096
	ds_read_b128 v[110:113], v110 offset:6144
	ds_read_b128 v[114:117], v0 offset:16384
	ds_read_b128 v[118:121], v0 offset:18432
	ds_read_b128 v[122:125], v0 offset:20480
	ds_read_b128 v[126:129], v0 offset:22528
	v_or_b32_e32 v0, s4, v95
	v_add_u32_e32 v142, v0, v96
	v_add_u32_e32 v0, v0, v94
	ds_read_b128 v[130:133], v142
	ds_read_b128 v[134:137], v142 offset:2048
	ds_read_b128 v[138:141], v142 offset:4096
	ds_read_b128 v[142:145], v142 offset:6144
	ds_read_b128 v[146:149], v0 offset:16384
	ds_read_b128 v[150:153], v0 offset:18432
	ds_read_b128 v[154:157], v0 offset:20480
	ds_read_b128 v[180:183], v0 offset:22528
	s_setprio 1
	s_waitcnt lgkmcnt(8)
	v_mfma_f32_16x16x32_bf16 v[62:65], v[98:101], v[114:117], v[62:65]
	v_mfma_f32_16x16x32_bf16 v[58:61], v[98:101], v[118:121], v[58:61]
	v_mfma_f32_16x16x32_bf16 v[54:57], v[98:101], v[122:125], v[54:57]
	v_mfma_f32_16x16x32_bf16 v[50:53], v[98:101], v[126:129], v[50:53]
	v_mfma_f32_16x16x32_bf16 v[46:49], v[102:105], v[114:117], v[46:49]
	v_mfma_f32_16x16x32_bf16 v[42:45], v[102:105], v[118:121], v[42:45]
	v_mfma_f32_16x16x32_bf16 v[38:41], v[102:105], v[122:125], v[38:41]
	v_mfma_f32_16x16x32_bf16 v[34:37], v[102:105], v[126:129], v[34:37]
	v_mfma_f32_16x16x32_bf16 v[30:33], v[106:109], v[114:117], v[30:33]
	v_mfma_f32_16x16x32_bf16 v[26:29], v[106:109], v[118:121], v[26:29]
	v_mfma_f32_16x16x32_bf16 v[22:25], v[106:109], v[122:125], v[22:25]
	v_mfma_f32_16x16x32_bf16 v[18:21], v[106:109], v[126:129], v[18:21]
	v_mfma_f32_16x16x32_bf16 v[14:17], v[110:113], v[114:117], v[14:17]
	v_mfma_f32_16x16x32_bf16 v[10:13], v[110:113], v[118:121], v[10:13]
	v_mfma_f32_16x16x32_bf16 v[6:9], v[110:113], v[122:125], v[6:9]
	v_mfma_f32_16x16x32_bf16 v[2:5], v[110:113], v[126:129], v[2:5]
	s_waitcnt lgkmcnt(0)
	v_mfma_f32_16x16x32_bf16 v[62:65], v[130:133], v[146:149], v[62:65]
	v_mfma_f32_16x16x32_bf16 v[58:61], v[130:133], v[150:153], v[58:61]
	v_mfma_f32_16x16x32_bf16 v[54:57], v[130:133], v[154:157], v[54:57]
	v_mfma_f32_16x16x32_bf16 v[50:53], v[130:133], v[180:183], v[50:53]
	v_mfma_f32_16x16x32_bf16 v[46:49], v[134:137], v[146:149], v[46:49]
	v_mfma_f32_16x16x32_bf16 v[42:45], v[134:137], v[150:153], v[42:45]
	v_mfma_f32_16x16x32_bf16 v[38:41], v[134:137], v[154:157], v[38:41]
	v_mfma_f32_16x16x32_bf16 v[34:37], v[134:137], v[180:183], v[34:37]
	v_mfma_f32_16x16x32_bf16 v[30:33], v[138:141], v[146:149], v[30:33]
	v_mfma_f32_16x16x32_bf16 v[26:29], v[138:141], v[150:153], v[26:29]
	v_mfma_f32_16x16x32_bf16 v[22:25], v[138:141], v[154:157], v[22:25]
	v_mfma_f32_16x16x32_bf16 v[18:21], v[138:141], v[180:183], v[18:21]
	v_mfma_f32_16x16x32_bf16 v[14:17], v[142:145], v[146:149], v[14:17]
	v_mfma_f32_16x16x32_bf16 v[10:13], v[142:145], v[150:153], v[10:13]
	v_mfma_f32_16x16x32_bf16 v[6:9], v[142:145], v[154:157], v[6:9]
	v_mfma_f32_16x16x32_bf16 v[2:5], v[142:145], v[180:183], v[2:5]
	s_setprio 0
	s_add_u32 s0, s0, 0x80
	s_addc_u32 s1, s1, 0
	s_cmpk_eq_i32 s0, 0x780
	s_mov_b32 s4, s5
	s_waitcnt vmcnt(0)
	s_barrier
; DI void gemm_tile(const bf16_t* __restrict__ A, int lda, const bf16_t* __restrict__ Bt, int ldb, int bvalid, int K, f32x4 (&acc)[4][4], char* lds, bool preloaded = false) {
;     ...
;   for (int kt = 0; kt < nk; ++kt) {
;     if (kt + 1 < nk) { GLDS((kt + 1) & 1, (kt + 1) << 6) }
;     compute(kt & 1);
;     __syncthreads();
;   }
; DI void phaseA_tile(const P& p, int layer, int mt, int nt, char* lds) {
;     ...
;   if (tid < 128) {
;     const float ss = (ssa.x + ssa.y + ssa.z + ssa.w) + (ssb.x + ssb.y + ssb.z + ssb.w) + (ssc.x + ssc.y + ssc.z + ssc.w) + (ssd.x + ssd.y + ssd.z + ssd.w);
;     rr[tid] = rsqrtf(ss * (1.f / 1024.f) + 1e-6f);
;   }
	s_cbranch_scc0 .LBB0_1594
	v_add_u32_e32 v0, v97, v96
	ds_read_b128 v[82:85], v0 offset:32768
	ds_read_b128 v[86:89], v0 offset:34816
	ds_read_b128 v[98:101], v0 offset:36864
	ds_read_b128 v[102:105], v0 offset:38912
	v_add_u32_e32 v0, v97, v94
	ds_read_b128 v[106:109], v0 offset:49152
	ds_read_b128 v[110:113], v0 offset:51200
	ds_read_b128 v[114:117], v0 offset:53248
	ds_read_b128 v[118:121], v0 offset:55296
	v_add_u32_e32 v0, v95, v96
	ds_read_b128 v[122:125], v0 offset:32768
	ds_read_b128 v[126:129], v0 offset:34816
	ds_read_b128 v[130:133], v0 offset:36864
	ds_read_b128 v[134:137], v0 offset:38912
	v_add_u32_e32 v0, v95, v94
	ds_read_b128 v[94:97], v0 offset:49152
	ds_read_b128 v[138:141], v0 offset:51200
	ds_read_b128 v[142:145], v0 offset:53248
	ds_read_b128 v[146:149], v0 offset:55296
	v_readfirstlane_b32 s4, v92
	s_setprio 1
	s_waitcnt lgkmcnt(11)
	v_mfma_f32_16x16x32_bf16 v[62:65], v[82:85], v[106:109], v[62:65]
	s_waitcnt lgkmcnt(10)
	v_mfma_f32_16x16x32_bf16 v[58:61], v[82:85], v[110:113], v[58:61]
	s_waitcnt lgkmcnt(9)
	v_mfma_f32_16x16x32_bf16 v[54:57], v[82:85], v[114:117], v[54:57]
	s_waitcnt lgkmcnt(8)
	v_mfma_f32_16x16x32_bf16 v[50:53], v[82:85], v[118:121], v[50:53]
	v_mfma_f32_16x16x32_bf16 v[46:49], v[86:89], v[106:109], v[46:49]
	v_mfma_f32_16x16x32_bf16 v[42:45], v[86:89], v[110:113], v[42:45]
	v_mfma_f32_16x16x32_bf16 v[38:41], v[86:89], v[114:117], v[38:41]
	v_mfma_f32_16x16x32_bf16 v[34:37], v[86:89], v[118:121], v[34:37]
	v_mfma_f32_16x16x32_bf16 v[30:33], v[98:101], v[106:109], v[30:33]
	v_mfma_f32_16x16x32_bf16 v[26:29], v[98:101], v[110:113], v[26:29]
	v_mfma_f32_16x16x32_bf16 v[22:25], v[98:101], v[114:117], v[22:25]
	v_mfma_f32_16x16x32_bf16 v[18:21], v[98:101], v[118:121], v[18:21]
	v_mfma_f32_16x16x32_bf16 v[14:17], v[102:105], v[106:109], v[14:17]
	v_mfma_f32_16x16x32_bf16 v[10:13], v[102:105], v[110:113], v[10:13]
	v_mfma_f32_16x16x32_bf16 v[6:9], v[102:105], v[114:117], v[6:9]
	v_mfma_f32_16x16x32_bf16 v[2:5], v[102:105], v[118:121], v[2:5]
	s_waitcnt lgkmcnt(3)
	v_mfma_f32_16x16x32_bf16 v[62:65], v[122:125], v[94:97], v[62:65]
	s_waitcnt lgkmcnt(2)
	v_mfma_f32_16x16x32_bf16 v[58:61], v[122:125], v[138:141], v[58:61]
	s_waitcnt lgkmcnt(1)
	v_mfma_f32_16x16x32_bf16 v[54:57], v[122:125], v[142:145], v[54:57]
	s_waitcnt lgkmcnt(0)
	v_mfma_f32_16x16x32_bf16 v[50:53], v[122:125], v[146:149], v[50:53]
	v_mfma_f32_16x16x32_bf16 v[46:49], v[126:129], v[94:97], v[46:49]
	v_mfma_f32_16x16x32_bf16 v[42:45], v[126:129], v[138:141], v[42:45]
	v_mfma_f32_16x16x32_bf16 v[38:41], v[126:129], v[142:145], v[38:41]
	v_mfma_f32_16x16x32_bf16 v[34:37], v[126:129], v[146:149], v[34:37]
	v_mfma_f32_16x16x32_bf16 v[30:33], v[130:133], v[94:97], v[30:33]
	v_mfma_f32_16x16x32_bf16 v[26:29], v[130:133], v[138:141], v[26:29]
	v_mfma_f32_16x16x32_bf16 v[22:25], v[130:133], v[142:145], v[22:25]
	v_mfma_f32_16x16x32_bf16 v[18:21], v[130:133], v[146:149], v[18:21]
	v_mfma_f32_16x16x32_bf16 v[14:17], v[134:137], v[94:97], v[14:17]
	v_mfma_f32_16x16x32_bf16 v[10:13], v[134:137], v[138:141], v[10:13]
	v_mfma_f32_16x16x32_bf16 v[6:9], v[134:137], v[142:145], v[6:9]
	v_mfma_f32_16x16x32_bf16 v[2:5], v[134:137], v[146:149], v[2:5]
	s_setprio 0
	v_cmp_gt_i32_e32 vcc, s92, v92
	s_barrier
	s_and_saveexec_b64 s[0:1], vcc
	s_cbranch_execz .LBB0_1597
	v_mov_b32_e32 v82, v78
	v_mov_b32_e32 v83, v74
	v_mov_b32_e32 v74, v79
	v_pk_add_f32 v[74:75], v[82:83], v[74:75]
	v_mov_b32_e32 v78, v80
	v_mov_b32_e32 v79, v76
	v_pk_add_f32 v[74:75], v[78:79], v[74:75]
	v_mov_b32_e32 v76, v81
	v_pk_add_f32 v[74:75], v[76:77], v[74:75]
	v_mov_b32_e32 v76, v70
	v_mov_b32_e32 v77, v66
	v_mov_b32_e32 v66, v71
	v_pk_add_f32 v[66:67], v[76:77], v[66:67]
	v_mov_b32_e32 v70, v72
	v_mov_b32_e32 v71, v68
	v_pk_add_f32 v[66:67], v[70:71], v[66:67]
	v_mov_b32_e32 v68, v73
	v_pk_add_f32 v[66:67], v[68:69], v[66:67]
	v_add_f32_e32 v0, v74, v75
	v_add_f32_e32 v0, v0, v66
	v_add_f32_e32 v0, v0, v67
	v_fmamk_f32 v0, v0, 0x3a800000, v160
	s_mov_b32 s5, 0x800000
	v_mul_f32_e32 v66, 0x4b800000, v0
	v_cmp_gt_f32_e32 vcc, s5, v0
	s_nop 1
	v_cndmask_b32_e32 v0, v0, v66, vcc
	v_rsq_f32_e32 v0, v0
	s_nop 0
	v_mul_f32_e32 v66, 0x45800000, v0
	v_cndmask_b32_e32 v0, v0, v66, vcc
	v_lshl_add_u32 v66, v92, 2, v173
	ds_write_b32 v66, v0
